# merged 32-MFMA blocks + B1 fragment wait moved mid-block (lgkmcnt(4) before barrier, lgkmcnt(0) between M1 and M2)
# baseline (speedup 1.0000x reference)
; #define PG8_STAGE(bufoff, gbase, voff) do { _Pragma("unroll") for (int _i = 0; _i < 2; ++_i) \
;     __builtin_amdgcn_global_load_lds((const unsigned*)((const char*)(gbase) + (voff)[_i]), (LAS unsigned*)(lds + (bufoff) + ldsw + _i * 8192), 16, 0, 0); } while (0)
; #define PG8_LDA(dst, b, h) do { _Pragma("unroll") for (int m = 0; m < 4; ++m) _Pragma("unroll") for (int k = 0; k < 2; ++k) dst[m][k] = *(const LAS bf16x8*)(lds + PG8_SA(b, h) + aoff + m * 2048 + k * 1024); } while (0)
; #define PG8_LDB(dst, b, h) do { _Pragma("unroll") for (int n = 0; n < 2; ++n) _Pragma("unroll") for (int k = 0; k < 2; ++k) dst[n][k] = *(const LAS bf16x8*)(lds + PG8_SB(b, h) + boff + n * 2048 + k * 1024); } while (0)
; #define PG8_MMA(ai, bj, At, Bt) do { __builtin_amdgcn_s_setprio(1); _Pragma("unroll") for (int m = 0; m < 4; ++m) _Pragma("unroll") for (int n = 0; n < 2; ++n) _Pragma("unroll") for (int k = 0; k < 2; ++k) \
;     acc[ai][bj][m][n] = __builtin_amdgcn_mfma_f32_16x16x32_bf16(Bt[n][k], At[m][k], acc[ai][bj][m][n], 0, 0, 0); __builtin_amdgcn_s_setprio(0); } while (0)
; #define PG8_WAIT_V(n) asm volatile("s_waitcnt vmcnt(" #n ")" ::: "memory")
; #define PG8_WAIT_L(n) asm volatile("s_waitcnt lgkmcnt(" #n ")" ::: "memory")
; #define PG8_BAR __builtin_amdgcn_s_barrier()
; #define PG8_SCHED __builtin_amdgcn_sched_barrier(0)
; template <class Epi, class Sched = StaticOrder>
; DI void gemm_phase(LAS unsigned char* lds, const Gemm g, const Sched& S, const Epi& E) {
;     ...
;     for (int t = 0; t < nt; t += 2) {
;       const bool last = (t == nt - 2);
;       const char* a1 = cA + (size_t)(t + 1) * kstep;
;       const char* a2 = last ? nA : cA + (size_t)(t + 2) * kstep; const char* b2 = last ? nB : cB + (size_t)(t + 2) * kstep;
;       const char* a3 = a2 + kstep; const char* b3 = b2 + kstep;
;       PG8_LDB(B0, 0, 0); PG8_SCHED; PG8_LDA(At, 0, 0); PG8_STAGE(PG8_SA(1, 1), a1 + hstep, voffA);
;       PG8_WAIT_L(8); PG8_BAR; PG8_WAIT_L(0); PG8_MMA(0, 0, At, B0); PG8_BAR; PG8_SCHED;
;       PG8_LDB(B1, 0, 1); PG8_STAGE(PG8_SB(0, 0), b2, voffB);
;       PG8_BAR; PG8_WAIT_L(0); PG8_MMA(0, 1, At, B1); PG8_BAR;
;       PG8_LDA(At, 0, 1); PG8_STAGE(PG8_SA(0, 0), a2, voffA);
;       PG8_BAR; PG8_WAIT_L(0); PG8_MMA(1, 0, At, B0); PG8_BAR; PG8_SCHED;
;       PG8_STAGE(PG8_SB(0, 1), b2 + hstep, voffB);
;       PG8_WAIT_V(6); PG8_BAR; PG8_MMA(1, 1, At, B1); PG8_BAR;
.LBB0_346:
	ds_read_b128 v[128:131], v173
	ds_read_b128 v[132:135], v173 offset:1024
	ds_read_b128 v[154:157], v173 offset:2048
	ds_read_b128 v[158:161], v173 offset:3072
	s_add_u32 s8, s6, 0xfff80080
	s_addc_u32 s9, s7, -1
	s_cmp_eq_u32 s52, 28
	s_cselect_b32 s11, s31, s9
	s_cselect_b32 s10, s42, s8
	s_cselect_b32 s9, s29, s45
	s_cselect_b32 s8, s43, s44
	s_add_i32 m0, s48, 0xc000
	ds_read_b128 v[162:165], v174
	ds_read_b128 v[166:169], v174 offset:1024
	ds_read_b128 v[178:181], v174 offset:2048
	ds_read_b128 v[182:185], v174 offset:3072
	ds_read_b128 v[186:189], v174 offset:4096
	ds_read_b128 v[190:193], v174 offset:5120
	ds_read_b128 v[194:197], v174 offset:6144
	ds_read_b128 v[198:201], v174 offset:7168
	global_load_lds_dwordx4 v146, s[6:7]
	s_add_i32 m0, s48, 0xe000
	s_nop 0
	global_load_lds_dwordx4 v148, s[6:7]
	ds_read_b128 v[202:205], v175
	ds_read_b128 v[206:209], v175 offset:1024
	ds_read_b128 v[212:215], v175 offset:2048
	ds_read_b128 v[216:219], v175 offset:3072
	s_waitcnt vmcnt(8)
	s_waitcnt lgkmcnt(4)
	s_setprio 1
	s_barrier
	v_mfma_f32_16x16x32_bf16 v[124:127], v[128:131], v[162:165], v[124:127]
	v_mfma_f32_16x16x32_bf16 v[120:123], v[154:157], v[162:165], v[120:123]
	v_mfma_f32_16x16x32_bf16 v[108:111], v[128:131], v[178:181], v[108:111]
	v_mfma_f32_16x16x32_bf16 v[104:107], v[154:157], v[178:181], v[104:107]
	v_mfma_f32_16x16x32_bf16 v[100:103], v[128:131], v[186:189], v[100:103]
	v_mfma_f32_16x16x32_bf16 v[92:95], v[154:157], v[186:189], v[92:95]
	v_mfma_f32_16x16x32_bf16 v[84:87], v[128:131], v[194:197], v[84:87]
	v_mfma_f32_16x16x32_bf16 v[76:79], v[154:157], v[194:197], v[76:79]
	v_mfma_f32_16x16x32_bf16 v[124:127], v[132:135], v[166:169], v[124:127]
	v_mfma_f32_16x16x32_bf16 v[120:123], v[158:161], v[166:169], v[120:123]
	v_mfma_f32_16x16x32_bf16 v[108:111], v[132:135], v[182:185], v[108:111]
	v_mfma_f32_16x16x32_bf16 v[104:107], v[158:161], v[182:185], v[104:107]
	v_mfma_f32_16x16x32_bf16 v[100:103], v[132:135], v[190:193], v[100:103]
	v_mfma_f32_16x16x32_bf16 v[92:95], v[158:161], v[190:193], v[92:95]
	v_mfma_f32_16x16x32_bf16 v[84:87], v[132:135], v[198:201], v[84:87]
	v_mfma_f32_16x16x32_bf16 v[76:79], v[158:161], v[198:201], v[76:79]
	s_waitcnt lgkmcnt(0)
	v_mfma_f32_16x16x32_bf16 v[116:119], v[202:205], v[162:165], v[116:119]
	v_mfma_f32_16x16x32_bf16 v[112:115], v[212:215], v[162:165], v[112:115]
	v_mfma_f32_16x16x32_bf16 v[96:99], v[202:205], v[178:181], v[96:99]
	v_mfma_f32_16x16x32_bf16 v[88:91], v[212:215], v[178:181], v[88:91]
	v_mfma_f32_16x16x32_bf16 v[80:83], v[202:205], v[186:189], v[80:83]
	v_mfma_f32_16x16x32_bf16 v[72:75], v[212:215], v[186:189], v[72:75]
	v_mfma_f32_16x16x32_bf16 v[68:71], v[202:205], v[194:197], v[68:71]
	v_mfma_f32_16x16x32_bf16 v[64:67], v[212:215], v[194:197], v[64:67]
	v_mfma_f32_16x16x32_bf16 v[116:119], v[206:209], v[166:169], v[116:119]
	v_mfma_f32_16x16x32_bf16 v[112:115], v[216:219], v[166:169], v[112:115]
	v_mfma_f32_16x16x32_bf16 v[96:99], v[206:209], v[182:185], v[96:99]
	v_mfma_f32_16x16x32_bf16 v[88:91], v[216:219], v[182:185], v[88:91]
	v_mfma_f32_16x16x32_bf16 v[80:83], v[206:209], v[190:193], v[80:83]
	v_mfma_f32_16x16x32_bf16 v[72:75], v[216:219], v[190:193], v[72:75]
	v_mfma_f32_16x16x32_bf16 v[68:71], v[206:209], v[198:201], v[68:71]
	v_mfma_f32_16x16x32_bf16 v[64:67], v[216:219], v[198:201], v[64:67]
	s_barrier
	s_setprio 0
	s_add_i32 s53, s65, s41
	s_add_u32 s98, s8, 0x80
	s_addc_u32 s99, s9, 0
	s_add_u32 s100, s10, 0x80
	s_addc_u32 s101, s11, 0
	s_mov_b32 m0, s53
	s_nop 0
	global_load_lds_dwordx4 v140, s[8:9]
	s_add_i32 m0, s53, 0x2000
	s_nop 0
	global_load_lds_dwordx4 v136, s[8:9]
	s_mov_b32 m0, s48
	ds_read_b128 v[162:165], v174 offset:16384
	ds_read_b128 v[166:169], v174 offset:17408
	ds_read_b128 v[178:181], v174 offset:18432
	ds_read_b128 v[182:185], v174 offset:19456
	ds_read_b128 v[186:189], v174 offset:20480
	ds_read_b128 v[190:193], v174 offset:21504
	ds_read_b128 v[194:197], v174 offset:22528
	ds_read_b128 v[198:201], v174 offset:23552
	global_load_lds_dwordx4 v142, s[10:11]
	s_mov_b32 m0, s49
	s_nop 0
	global_load_lds_dwordx4 v138, s[10:11]
	s_add_u32 s54, s8, 0x80000
	s_addc_u32 s55, s9, 0
	s_add_i32 s53, s72, s41
	s_mov_b32 m0, s53
	s_nop 0
	global_load_lds_dwordx4 v140, s[54:55]
	s_add_i32 m0, s53, 0x2000
	s_nop 0
	global_load_lds_dwordx4 v136, s[54:55]
	s_waitcnt vmcnt(8)
	s_waitcnt lgkmcnt(0)
	s_setprio 1
	s_barrier
	v_mfma_f32_16x16x32_bf16 v[60:63], v[128:131], v[162:165], v[60:63]
	v_mfma_f32_16x16x32_bf16 v[56:59], v[154:157], v[162:165], v[56:59]
	v_mfma_f32_16x16x32_bf16 v[52:55], v[128:131], v[178:181], v[52:55]
	v_mfma_f32_16x16x32_bf16 v[44:47], v[154:157], v[178:181], v[44:47]
	v_mfma_f32_16x16x32_bf16 v[36:39], v[128:131], v[186:189], v[36:39]
	v_mfma_f32_16x16x32_bf16 v[28:31], v[154:157], v[186:189], v[28:31]
	v_mfma_f32_16x16x32_bf16 v[20:23], v[128:131], v[194:197], v[20:23]
	v_mfma_f32_16x16x32_bf16 v[12:15], v[154:157], v[194:197], v[12:15]
	v_mfma_f32_16x16x32_bf16 v[60:63], v[132:135], v[166:169], v[60:63]
	v_mfma_f32_16x16x32_bf16 v[56:59], v[158:161], v[166:169], v[56:59]
	v_mfma_f32_16x16x32_bf16 v[52:55], v[132:135], v[182:185], v[52:55]
	v_mfma_f32_16x16x32_bf16 v[44:47], v[158:161], v[182:185], v[44:47]
	v_mfma_f32_16x16x32_bf16 v[36:39], v[132:135], v[190:193], v[36:39]
	v_mfma_f32_16x16x32_bf16 v[28:31], v[158:161], v[190:193], v[28:31]
	v_mfma_f32_16x16x32_bf16 v[20:23], v[132:135], v[198:201], v[20:23]
	v_mfma_f32_16x16x32_bf16 v[12:15], v[158:161], v[198:201], v[12:15]
	v_mfma_f32_16x16x32_bf16 v[48:51], v[202:205], v[162:165], v[48:51]
	v_mfma_f32_16x16x32_bf16 v[40:43], v[212:215], v[162:165], v[40:43]
	v_mfma_f32_16x16x32_bf16 v[32:35], v[202:205], v[178:181], v[32:35]
	v_mfma_f32_16x16x32_bf16 v[24:27], v[212:215], v[178:181], v[24:27]
	v_mfma_f32_16x16x32_bf16 v[16:19], v[202:205], v[186:189], v[16:19]
	v_mfma_f32_16x16x32_bf16 v[8:11], v[212:215], v[186:189], v[8:11]
	v_mfma_f32_16x16x32_bf16 v[4:7], v[202:205], v[194:197], v[4:7]
	v_mfma_f32_16x16x32_bf16 v[0:3], v[212:215], v[194:197], v[0:3]
	v_mfma_f32_16x16x32_bf16 v[48:51], v[206:209], v[166:169], v[48:51]
	v_mfma_f32_16x16x32_bf16 v[40:43], v[216:219], v[166:169], v[40:43]
	v_mfma_f32_16x16x32_bf16 v[32:35], v[206:209], v[182:185], v[32:35]
	v_mfma_f32_16x16x32_bf16 v[24:27], v[216:219], v[182:185], v[24:27]
	v_mfma_f32_16x16x32_bf16 v[16:19], v[206:209], v[190:193], v[16:19]
	v_mfma_f32_16x16x32_bf16 v[8:11], v[216:219], v[190:193], v[8:11]
	v_mfma_f32_16x16x32_bf16 v[4:7], v[206:209], v[198:201], v[4:7]
	v_mfma_f32_16x16x32_bf16 v[0:3], v[216:219], v[198:201], v[0:3]
	s_barrier
; #define PG8_STAGE(bufoff, gbase, voff) do { _Pragma("unroll") for (int _i = 0; _i < 2; ++_i) \
;     __builtin_amdgcn_global_load_lds((const unsigned*)((const char*)(gbase) + (voff)[_i]), (LAS unsigned*)(lds + (bufoff) + ldsw + _i * 8192), 16, 0, 0); } while (0)
; #define PG8_LDA(dst, b, h) do { _Pragma("unroll") for (int m = 0; m < 4; ++m) _Pragma("unroll") for (int k = 0; k < 2; ++k) dst[m][k] = *(const LAS bf16x8*)(lds + PG8_SA(b, h) + aoff + m * 2048 + k * 1024); } while (0)
; #define PG8_LDB(dst, b, h) do { _Pragma("unroll") for (int n = 0; n < 2; ++n) _Pragma("unroll") for (int k = 0; k < 2; ++k) dst[n][k] = *(const LAS bf16x8*)(lds + PG8_SB(b, h) + boff + n * 2048 + k * 1024); } while (0)
; #define PG8_MMA(ai, bj, At, Bt) do { __builtin_amdgcn_s_setprio(1); _Pragma("unroll") for (int m = 0; m < 4; ++m) _Pragma("unroll") for (int n = 0; n < 2; ++n) _Pragma("unroll") for (int k = 0; k < 2; ++k) \
;     acc[ai][bj][m][n] = __builtin_amdgcn_mfma_f32_16x16x32_bf16(Bt[n][k], At[m][k], acc[ai][bj][m][n], 0, 0, 0); __builtin_amdgcn_s_setprio(0); } while (0)
; #define PG8_WAIT_V(n) asm volatile("s_waitcnt vmcnt(" #n ")" ::: "memory")
; #define PG8_WAIT_L(n) asm volatile("s_waitcnt lgkmcnt(" #n ")" ::: "memory")
; #define PG8_BAR __builtin_amdgcn_s_barrier()
; #define PG8_SCHED __builtin_amdgcn_sched_barrier(0)
; template <class Epi, class Sched = StaticOrder>
; DI void gemm_phase(LAS unsigned char* lds, const Gemm g, const Sched& S, const Epi& E) {
;     ...
;       PG8_LDB(B0, 1, 0); PG8_SCHED; PG8_LDA(At, 1, 0); PG8_STAGE(PG8_SA(0, 1), a2 + hstep, voffA);
;       PG8_WAIT_L(8); PG8_BAR; PG8_WAIT_L(0); PG8_MMA(0, 0, At, B0); PG8_BAR; PG8_SCHED;
;       PG8_LDB(B1, 1, 1); PG8_STAGE(PG8_SB(1, 0), b3, voffB);
;       PG8_BAR; PG8_WAIT_L(0); PG8_MMA(0, 1, At, B1); PG8_BAR;
;       PG8_LDA(At, 1, 1); PG8_STAGE(PG8_SA(1, 0), a3, voffA);
;       PG8_BAR; PG8_WAIT_L(0); PG8_MMA(1, 0, At, B0); PG8_BAR; PG8_SCHED;
;       PG8_STAGE(PG8_SB(1, 1), b3 + hstep, voffB);
;       PG8_WAIT_V(6); PG8_BAR; PG8_MMA(1, 1, At, B1); PG8_BAR;
	s_setprio 0
	s_add_i32 s53, 0, 0x18000
	v_add_u32_e32 v158, s53, v171
	ds_read_b128 v[128:131], v158
	ds_read_b128 v[132:135], v158 offset:1024
	ds_read_b128 v[154:157], v158 offset:2048
	ds_read_b128 v[158:161], v158 offset:3072
	s_add_u32 s10, s10, 0x80000
	s_addc_u32 s11, s11, 0
	s_mov_b32 m0, s50
	ds_read_b128 v[162:165], v174 offset:32768
	ds_read_b128 v[166:169], v174 offset:33792
	ds_read_b128 v[178:181], v174 offset:34816
	ds_read_b128 v[182:185], v174 offset:35840
	ds_read_b128 v[186:189], v174 offset:36864
	ds_read_b128 v[190:193], v174 offset:37888
	ds_read_b128 v[194:197], v174 offset:38912
	ds_read_b128 v[198:201], v174 offset:39936
	global_load_lds_dwordx4 v142, s[10:11]
	s_mov_b32 m0, s51
	s_nop 0
	global_load_lds_dwordx4 v138, s[10:11]
	s_add_i32 s10, 0, 0x1c000
	v_add_u32_e32 v177, s10, v171
	ds_read_b128 v[202:205], v177
	ds_read_b128 v[206:209], v177 offset:1024
	ds_read_b128 v[212:215], v177 offset:2048
	ds_read_b128 v[216:219], v177 offset:3072
	s_waitcnt vmcnt(8)
	s_waitcnt lgkmcnt(4)
	s_setprio 1
	s_barrier
	v_mfma_f32_16x16x32_bf16 v[124:127], v[128:131], v[162:165], v[124:127]
	v_mfma_f32_16x16x32_bf16 v[120:123], v[154:157], v[162:165], v[120:123]
	v_mfma_f32_16x16x32_bf16 v[108:111], v[128:131], v[178:181], v[108:111]
	v_mfma_f32_16x16x32_bf16 v[104:107], v[154:157], v[178:181], v[104:107]
	v_mfma_f32_16x16x32_bf16 v[100:103], v[128:131], v[186:189], v[100:103]
	v_mfma_f32_16x16x32_bf16 v[92:95], v[154:157], v[186:189], v[92:95]
	v_mfma_f32_16x16x32_bf16 v[84:87], v[128:131], v[194:197], v[84:87]
	v_mfma_f32_16x16x32_bf16 v[76:79], v[154:157], v[194:197], v[76:79]
	v_mfma_f32_16x16x32_bf16 v[124:127], v[132:135], v[166:169], v[124:127]
	v_mfma_f32_16x16x32_bf16 v[120:123], v[158:161], v[166:169], v[120:123]
	v_mfma_f32_16x16x32_bf16 v[108:111], v[132:135], v[182:185], v[108:111]
	v_mfma_f32_16x16x32_bf16 v[104:107], v[158:161], v[182:185], v[104:107]
	v_mfma_f32_16x16x32_bf16 v[100:103], v[132:135], v[190:193], v[100:103]
	v_mfma_f32_16x16x32_bf16 v[92:95], v[158:161], v[190:193], v[92:95]
	v_mfma_f32_16x16x32_bf16 v[84:87], v[132:135], v[198:201], v[84:87]
	v_mfma_f32_16x16x32_bf16 v[76:79], v[158:161], v[198:201], v[76:79]
	s_waitcnt lgkmcnt(0)
	v_mfma_f32_16x16x32_bf16 v[116:119], v[202:205], v[162:165], v[116:119]
	v_mfma_f32_16x16x32_bf16 v[112:115], v[212:215], v[162:165], v[112:115]
	v_mfma_f32_16x16x32_bf16 v[96:99], v[202:205], v[178:181], v[96:99]
	v_mfma_f32_16x16x32_bf16 v[88:91], v[212:215], v[178:181], v[88:91]
	v_mfma_f32_16x16x32_bf16 v[80:83], v[202:205], v[186:189], v[80:83]
	v_mfma_f32_16x16x32_bf16 v[72:75], v[212:215], v[186:189], v[72:75]
	v_mfma_f32_16x16x32_bf16 v[68:71], v[202:205], v[194:197], v[68:71]
	v_mfma_f32_16x16x32_bf16 v[64:67], v[212:215], v[194:197], v[64:67]
	v_mfma_f32_16x16x32_bf16 v[116:119], v[206:209], v[166:169], v[116:119]
	v_mfma_f32_16x16x32_bf16 v[112:115], v[216:219], v[166:169], v[112:115]
	v_mfma_f32_16x16x32_bf16 v[96:99], v[206:209], v[182:185], v[96:99]
	v_mfma_f32_16x16x32_bf16 v[88:91], v[216:219], v[182:185], v[88:91]
	v_mfma_f32_16x16x32_bf16 v[80:83], v[206:209], v[190:193], v[80:83]
	v_mfma_f32_16x16x32_bf16 v[72:75], v[216:219], v[190:193], v[72:75]
	v_mfma_f32_16x16x32_bf16 v[68:71], v[206:209], v[198:201], v[68:71]
	v_mfma_f32_16x16x32_bf16 v[64:67], v[216:219], v[198:201], v[64:67]
	s_barrier
	s_setprio 0
	s_add_i32 s11, s53, s41
	s_mov_b32 m0, s11
	s_nop 0
	global_load_lds_dwordx4 v140, s[98:99]
	s_add_i32 m0, s11, 0x2000
	s_nop 0
	global_load_lds_dwordx4 v136, s[98:99]
	s_mov_b32 m0, s56
	ds_read_b128 v[162:165], v174 offset:49152
	ds_read_b128 v[166:169], v174 offset:50176
	ds_read_b128 v[178:181], v174 offset:51200
	ds_read_b128 v[182:185], v174 offset:52224
	ds_read_b128 v[186:189], v174 offset:53248
	ds_read_b128 v[190:193], v174 offset:54272
	ds_read_b128 v[194:197], v174 offset:55296
	ds_read_b128 v[198:201], v174 offset:56320
	global_load_lds_dwordx4 v142, s[100:101]
	s_mov_b32 m0, s57
	s_nop 0
	global_load_lds_dwordx4 v138, s[100:101]
	s_add_u32 s8, s8, 0x80080
	s_addc_u32 s9, s9, 0
	s_add_i32 s10, s10, s41
	s_mov_b32 m0, s10
	s_nop 0
	global_load_lds_dwordx4 v140, s[8:9]
	s_add_i32 m0, s10, 0x2000
	s_nop 0
	global_load_lds_dwordx4 v136, s[8:9]
	s_add_i32 s52, s52, 2
	s_add_u32 s6, s6, 0x100
	s_addc_u32 s7, s7, 0
	s_add_u32 s44, s44, 0x100
	s_addc_u32 s45, s45, 0
	s_cmp_gt_u32 s52, 29
	s_waitcnt vmcnt(8)
	s_waitcnt lgkmcnt(0)
	s_setprio 1
	s_barrier
	v_mfma_f32_16x16x32_bf16 v[60:63], v[128:131], v[162:165], v[60:63]
	v_mfma_f32_16x16x32_bf16 v[56:59], v[154:157], v[162:165], v[56:59]
	v_mfma_f32_16x16x32_bf16 v[52:55], v[128:131], v[178:181], v[52:55]
	v_mfma_f32_16x16x32_bf16 v[44:47], v[154:157], v[178:181], v[44:47]
	v_mfma_f32_16x16x32_bf16 v[36:39], v[128:131], v[186:189], v[36:39]
	v_mfma_f32_16x16x32_bf16 v[28:31], v[154:157], v[186:189], v[28:31]
	v_mfma_f32_16x16x32_bf16 v[20:23], v[128:131], v[194:197], v[20:23]
	v_mfma_f32_16x16x32_bf16 v[12:15], v[154:157], v[194:197], v[12:15]
	v_mfma_f32_16x16x32_bf16 v[60:63], v[132:135], v[166:169], v[60:63]
	v_mfma_f32_16x16x32_bf16 v[56:59], v[158:161], v[166:169], v[56:59]
	v_mfma_f32_16x16x32_bf16 v[52:55], v[132:135], v[182:185], v[52:55]
	v_mfma_f32_16x16x32_bf16 v[44:47], v[158:161], v[182:185], v[44:47]
	v_mfma_f32_16x16x32_bf16 v[36:39], v[132:135], v[190:193], v[36:39]
	v_mfma_f32_16x16x32_bf16 v[28:31], v[158:161], v[190:193], v[28:31]
	v_mfma_f32_16x16x32_bf16 v[20:23], v[132:135], v[198:201], v[20:23]
	v_mfma_f32_16x16x32_bf16 v[12:15], v[158:161], v[198:201], v[12:15]
	v_mfma_f32_16x16x32_bf16 v[48:51], v[202:205], v[162:165], v[48:51]
	v_mfma_f32_16x16x32_bf16 v[40:43], v[212:215], v[162:165], v[40:43]
	v_mfma_f32_16x16x32_bf16 v[32:35], v[202:205], v[178:181], v[32:35]
	v_mfma_f32_16x16x32_bf16 v[24:27], v[212:215], v[178:181], v[24:27]
	v_mfma_f32_16x16x32_bf16 v[16:19], v[202:205], v[186:189], v[16:19]
	v_mfma_f32_16x16x32_bf16 v[8:11], v[212:215], v[186:189], v[8:11]
	v_mfma_f32_16x16x32_bf16 v[4:7], v[202:205], v[194:197], v[4:7]
	v_mfma_f32_16x16x32_bf16 v[0:3], v[212:215], v[194:197], v[0:3]
	v_mfma_f32_16x16x32_bf16 v[48:51], v[206:209], v[166:169], v[48:51]
	v_mfma_f32_16x16x32_bf16 v[40:43], v[216:219], v[166:169], v[40:43]
	v_mfma_f32_16x16x32_bf16 v[32:35], v[206:209], v[182:185], v[32:35]
	v_mfma_f32_16x16x32_bf16 v[24:27], v[216:219], v[182:185], v[24:27]
	v_mfma_f32_16x16x32_bf16 v[16:19], v[206:209], v[190:193], v[16:19]
	v_mfma_f32_16x16x32_bf16 v[8:11], v[216:219], v[190:193], v[8:11]
	v_mfma_f32_16x16x32_bf16 v[4:7], v[206:209], v[198:201], v[4:7]
	v_mfma_f32_16x16x32_bf16 v[0:3], v[216:219], v[198:201], v[0:3]
	s_barrier
; DI unsigned pack2(float lo, float hi) { f32x2 v = {lo, hi}; bf16v2 r = __builtin_convertvector(v, bf16v2); return __builtin_bit_cast(unsigned, r); }
; DI float row_rstd(const float* ssq, int row, int fq) {
;   const f32x4 a = *(const f32x4*)(ssq + (size_t)row * 32 + fq * 8), b = *(const f32x4*)(ssq + (size_t)row * 32 + fq * 8 + 4);
;   float sm = ((a[0] + a[1]) + (a[2] + a[3])) + ((b[0] + b[1]) + (b[2] + b[3]));
;   sm += __shfl_xor(sm, 16); sm += __shfl_xor(sm, 32);
;   return rsqrtf(sm * (1.0f / 2048.f) + 1e-6f);
; }
;   DI void operator()(const f32x4 (&acc)[2][2][4][2], const Unit& u, int wr, int wc, int fr, int fq) const {
;     const int row0 = u.pm * BM + wr * 64 + fr, col0 = u.pn * BM + wc * 32 + 8 * fq;
;     float rsv[2][4];
; #pragma unroll
;     for (int ai = 0; ai < 2; ++ai)
; #pragma unroll
;       for (int m = 0; m < 4; ++m) rsv[ai][m] = row_rstd(ssq, row0 + ai * HALF + m * 16, fq);
; #pragma unroll
;     for (int ai = 0; ai < 2; ++ai)
; #pragma unroll
;       for (int m = 0; m < 4; ++m) {
;         const int row = row0 + ai * HALF + m * 16;
;         const float rs = rsv[ai][m];
;         bf16_t* rowp = O + (size_t)row * ldc + col0;
; #pragma unroll
;         for (int bj = 0; bj < 2; ++bj) {
;           const f32x4 v0 = acc[ai][bj][m][0] * rs, v1 = acc[ai][bj][m][1] * rs;
;           u32x4 w; w.x = pack2(v0[0], v0[1]); w.y = pack2(v0[2], v0[3]); w.z = pack2(v1[0], v1[1]); w.w = pack2(v1[2], v1[3]);
;           *(u32x4*)(rowp + bj * HALF) = w;
;         }
	s_setprio 0
	s_cbranch_scc0 .LBB0_346
	v_lshl_add_u32 v168, s4, 8, v170
	v_ashrrev_i32_e32 v169, 31, v168
	v_or_b32_e32 v154, 16, v168
	v_lshlrev_b64 v[128:129], 7, v[168:169]
	v_ashrrev_i32_e32 v155, 31, v154
	v_lshl_add_u64 v[128:129], v[144:145], 0, v[128:129]
	v_lshlrev_b64 v[156:157], 7, v[154:155]
	global_load_dwordx4 v[132:135], v[128:129], off
	s_nop 0
	global_load_dwordx4 v[128:131], v[128:129], off offset:16
	v_lshl_add_u64 v[156:157], v[144:145], 0, v[156:157]
	global_load_dwordx4 v[178:181], v[156:157], off
	global_load_dwordx4 v[182:185], v[156:157], off offset:16
	v_or_b32_e32 v160, 32, v168
	v_ashrrev_i32_e32 v161, 31, v160
	v_lshlrev_b64 v[156:157], 7, v[160:161]
	v_lshl_add_u64 v[156:157], v[144:145], 0, v[156:157]
	global_load_dwordx4 v[186:189], v[156:157], off
	global_load_dwordx4 v[190:193], v[156:157], off offset:16
	v_or_b32_e32 v156, 48, v168
	v_ashrrev_i32_e32 v157, 31, v156
	v_lshlrev_b64 v[158:159], 7, v[156:157]
	v_lshl_add_u64 v[158:159], v[144:145], 0, v[158:159]
	global_load_dwordx4 v[194:197], v[158:159], off
	global_load_dwordx4 v[198:201], v[158:159], off offset:16
	v_add_u32_e32 v164, 0x80, v168
	v_ashrrev_i32_e32 v165, 31, v164
	v_lshlrev_b64 v[158:159], 7, v[164:165]
	v_lshl_add_u64 v[158:159], v[144:145], 0, v[158:159]
	global_load_dwordx4 v[202:205], v[158:159], off
	global_load_dwordx4 v[206:209], v[158:159], off offset:16
	v_add_u32_e32 v158, 0x90, v168
	v_ashrrev_i32_e32 v159, 31, v158
	v_lshlrev_b64 v[162:163], 7, v[158:159]
	v_lshl_add_u64 v[162:163], v[144:145], 0, v[162:163]
	global_load_dwordx4 v[212:215], v[162:163], off
	global_load_dwordx4 v[216:219], v[162:163], off offset:16
	v_add_u32_e32 v166, 0xa0, v168
	v_ashrrev_i32_e32 v167, 31, v166
	v_lshlrev_b64 v[162:163], 7, v[166:167]
	v_lshl_add_u64 v[162:163], v[144:145], 0, v[162:163]
	global_load_dwordx4 v[220:223], v[162:163], off
	global_load_dwordx4 v[224:227], v[162:163], off offset:16
	v_add_u32_e32 v162, 0xb0, v168
	v_ashrrev_i32_e32 v163, 31, v162
	v_lshlrev_b64 v[228:229], 7, v[162:163]
	v_lshl_add_u64 v[232:233], v[144:145], 0, v[228:229]
	global_load_dwordx4 v[228:231], v[232:233], off
	s_nop 0
	global_load_dwordx4 v[232:235], v[232:233], off offset:16
	s_waitcnt vmcnt(0)
	v_mov_b32_e32 v236, v132
	v_mov_b32_e32 v237, v128
	v_mov_b32_e32 v128, v133
	v_mov_b32_e32 v132, v134
	v_mov_b32_e32 v133, v130
	v_mov_b32_e32 v130, v135
	v_pk_add_f32 v[130:131], v[132:133], v[130:131]
	v_mov_b32_e32 v132, v178
	v_mov_b32_e32 v133, v182
	v_mov_b32_e32 v182, v179
	v_mov_b32_e32 v134, v180
	v_mov_b32_e32 v135, v184
	v_mov_b32_e32 v184, v181
	v_pk_add_f32 v[128:129], v[236:237], v[128:129]
	v_pk_add_f32 v[132:133], v[132:133], v[182:183]
	v_pk_add_f32 v[134:135], v[134:135], v[184:185]
	v_pk_add_f32 v[128:129], v[128:129], v[130:131]
	v_pk_add_f32 v[130:131], v[132:133], v[134:135]
	v_mov_b32_e32 v133, v128
	v_mov_b32_e32 v132, v130
	v_and_b32_e32 v130, 64, v176
	v_add_u32_e32 v155, 64, v130
	v_xor_b32_e32 v130, 16, v176
	v_cmp_lt_i32_e32 vcc, v130, v155
	v_mov_b32_e32 v128, v131
	v_pk_add_f32 v[128:129], v[132:133], v[128:129]
	v_cndmask_b32_e32 v130, v176, v130, vcc
	v_lshlrev_b32_e32 v157, 2, v130
	ds_bpermute_b32 v131, v157, v129
	ds_bpermute_b32 v130, v157, v128
	v_mov_b32_e32 v178, v186
	v_mov_b32_e32 v179, v190
	v_mov_b32_e32 v190, v187
	v_mov_b32_e32 v186, v194
	s_waitcnt lgkmcnt(0)
	v_pk_add_f32 v[128:129], v[128:129], v[130:131]
	v_xor_b32_e32 v130, 32, v176
	v_cmp_lt_i32_e32 vcc, v130, v155
	v_mov_b32_e32 v187, v198
	v_mov_b32_e32 v198, v195
	v_cndmask_b32_e32 v130, v176, v130, vcc
	v_lshlrev_b32_e32 v155, 2, v130
	ds_bpermute_b32 v131, v155, v129
	ds_bpermute_b32 v130, v155, v128
	v_pk_add_f32 v[182:183], v[186:187], v[198:199]
	v_mov_b32_e32 v180, v188
	v_mov_b32_e32 v181, v192
	v_mov_b32_e32 v192, v189
	s_waitcnt lgkmcnt(0)
	v_pk_add_f32 v[128:129], v[128:129], v[130:131]
	v_mov_b64_e32 v[130:131], s[26:27]
	v_pk_fma_f32 v[128:129], v[128:129], s[24:25], v[130:131] op_sel_hi:[1,0,0]
	v_mov_b32_e32 v188, v196
	v_mul_f32_e32 v159, 0x4b800000, v129
	v_cmp_gt_f32_e32 vcc, s73, v129
	v_mov_b32_e32 v189, v200
	v_mov_b32_e32 v200, v197
	v_cndmask_b32_e32 v129, v129, v159, vcc
	v_rsq_f32_e32 v129, v129
	v_pk_add_f32 v[178:179], v[178:179], v[190:191]
	v_pk_add_f32 v[180:181], v[180:181], v[192:193]
	v_pk_add_f32 v[184:185], v[188:189], v[200:201]
	v_mul_f32_e32 v159, 0x45800000, v129
	v_cndmask_b32_e32 v198, v129, v159, vcc
	v_pk_mul_f32 v[126:127], v[126:127], v[198:199] op_sel_hi:[1,0]
	v_pk_mul_f32 v[124:125], v[124:125], v[198:199] op_sel_hi:[1,0]
	v_pk_mul_f32 v[122:123], v[122:123], v[198:199] op_sel_hi:[1,0]
	v_pk_mul_f32 v[120:121], v[120:121], v[198:199] op_sel_hi:[1,0]
	v_cvt_pk_bf16_f32 v124, v124, v125
	v_cvt_pk_bf16_f32 v125, v126, v127
	v_cvt_pk_bf16_f32 v127, v122, v123
	v_lshl_or_b32 v122, s5, 8, v172
	v_cvt_pk_bf16_f32 v126, v120, v121
	v_ashrrev_i32_e32 v123, 31, v122
	v_mov_b64_e32 v[120:121], s[2:3]
	v_mad_i64_i32 v[168:169], s[4:5], v168, s76, v[120:121]
	v_lshlrev_b64 v[122:123], 1, v[122:123]
	v_lshl_add_u64 v[168:169], v[168:169], 0, v[122:123]
	global_store_dwordx4 v[168:169], v[124:127], off
	v_mov_b32_e32 v194, v202
	v_mov_b32_e32 v195, v206
	v_pk_add_f32 v[124:125], v[178:179], v[180:181]
	v_pk_add_f32 v[126:127], v[182:183], v[184:185]
	v_mov_b32_e32 v179, v124
	v_mov_b32_e32 v178, v126
	v_mov_b32_e32 v124, v127
	v_pk_add_f32 v[124:125], v[178:179], v[124:125]
	ds_bpermute_b32 v127, v157, v125
	ds_bpermute_b32 v126, v157, v124
	v_mov_b32_e32 v206, v203
	v_mov_b32_e32 v196, v204
	v_mov_b32_e32 v197, v208
	v_mov_b32_e32 v208, v205
	v_mov_b32_e32 v202, v212
	v_mov_b32_e32 v203, v216
	v_mov_b32_e32 v216, v213
	v_mov_b32_e32 v204, v214
	v_mov_b32_e32 v205, v218
	v_mov_b32_e32 v218, v215
	v_pk_add_f32 v[186:187], v[194:195], v[206:207]
	v_pk_add_f32 v[188:189], v[196:197], v[208:209]
	v_pk_add_f32 v[190:191], v[202:203], v[216:217]
	v_pk_add_f32 v[192:193], v[204:205], v[218:219]
	v_pk_mul_f32 v[178:179], v[114:115], v[198:199] op_sel_hi:[1,0]
	s_waitcnt lgkmcnt(0)
; DI unsigned pack2(float lo, float hi) { f32x2 v = {lo, hi}; bf16v2 r = __builtin_convertvector(v, bf16v2); return __builtin_bit_cast(unsigned, r); }
; DI float row_rstd(const float* ssq, int row, int fq) {
;   const f32x4 a = *(const f32x4*)(ssq + (size_t)row * 32 + fq * 8), b = *(const f32x4*)(ssq + (size_t)row * 32 + fq * 8 + 4);
;   float sm = ((a[0] + a[1]) + (a[2] + a[3])) + ((b[0] + b[1]) + (b[2] + b[3]));
;   sm += __shfl_xor(sm, 16); sm += __shfl_xor(sm, 32);
;   return rsqrtf(sm * (1.0f / 2048.f) + 1e-6f);
; }
;   DI void operator()(const f32x4 (&acc)[2][2][4][2], const Unit& u, int wr, int wc, int fr, int fq) const {
;     const int row0 = u.pm * BM + wr * 64 + fr, col0 = u.pn * BM + wc * 32 + 8 * fq;
;     float rsv[2][4];
; #pragma unroll
;     for (int ai = 0; ai < 2; ++ai)
; #pragma unroll
;       for (int m = 0; m < 4; ++m) rsv[ai][m] = row_rstd(ssq, row0 + ai * HALF + m * 16, fq);
; #pragma unroll
;     for (int ai = 0; ai < 2; ++ai)
; #pragma unroll
;       for (int m = 0; m < 4; ++m) {
;         const int row = row0 + ai * HALF + m * 16;
;         const float rs = rsv[ai][m];
;         bf16_t* rowp = O + (size_t)row * ldc + col0;
; #pragma unroll
;         for (int bj = 0; bj < 2; ++bj) {
;           const f32x4 v0 = acc[ai][bj][m][0] * rs, v1 = acc[ai][bj][m][1] * rs;
;           u32x4 w; w.x = pack2(v0[0], v0[1]); w.y = pack2(v0[2], v0[3]); w.z = pack2(v1[0], v1[1]); w.w = pack2(v1[2], v1[3]);
;           *(u32x4*)(rowp + bj * HALF) = w;
;         }
	v_pk_add_f32 v[114:115], v[124:125], v[126:127]
	v_pk_add_f32 v[126:127], v[186:187], v[188:189]
	v_pk_add_f32 v[180:181], v[190:191], v[192:193]
	v_mov_b32_e32 v183, v126
	v_mov_b32_e32 v182, v180
	v_mov_b32_e32 v126, v181
	v_pk_add_f32 v[126:127], v[182:183], v[126:127]
	ds_bpermute_b32 v125, v155, v115
	ds_bpermute_b32 v124, v155, v114
	ds_bpermute_b32 v181, v157, v127
	ds_bpermute_b32 v180, v157, v126
	v_mul_f32_e32 v129, 0x4b800000, v128
	v_cmp_gt_f32_e32 vcc, s73, v128
	s_waitcnt lgkmcnt(2)
	v_pk_add_f32 v[114:115], v[114:115], v[124:125]
	v_mov_b32_e32 v194, v220
	s_waitcnt lgkmcnt(0)
	v_pk_add_f32 v[124:125], v[126:127], v[180:181]
	ds_bpermute_b32 v127, v155, v125
	ds_bpermute_b32 v126, v155, v124
	v_pk_fma_f32 v[114:115], v[114:115], s[24:25], v[130:131] op_sel_hi:[1,0,0]
	v_cndmask_b32_e32 v159, v128, v129, vcc
	v_mul_f32_e32 v128, 0x4b800000, v115
	v_cmp_gt_f32_e64 s[4:5], s73, v115
	v_cmp_gt_f32_e64 s[6:7], s73, v114
	v_mov_b32_e32 v195, v224
	v_cndmask_b32_e64 v161, v115, v128, s[4:5]
	v_mul_f32_e32 v115, 0x4b800000, v114
	v_mov_b32_e32 v224, v221
	v_mov_b32_e32 v196, v222
	v_mov_b32_e32 v197, v226
	v_mov_b32_e32 v226, v223
	v_cndmask_b32_e64 v163, v114, v115, s[6:7]
	s_waitcnt lgkmcnt(0)
	v_pk_add_f32 v[114:115], v[124:125], v[126:127]
	v_pk_add_f32 v[132:133], v[194:195], v[224:225]
	v_pk_add_f32 v[134:135], v[196:197], v[226:227]
	v_mov_b32_e32 v194, v228
	v_mov_b32_e32 v195, v232
	v_mov_b32_e32 v232, v229
	v_mov_b32_e32 v196, v230
	v_mov_b32_e32 v197, v234
	v_mov_b32_e32 v234, v231
	v_pk_fma_f32 v[114:115], v[114:115], s[24:25], v[130:131] op_sel_hi:[1,0,0]
	v_pk_add_f32 v[194:195], v[194:195], v[232:233]
	v_pk_add_f32 v[196:197], v[196:197], v[234:235]
	v_mul_f32_e32 v124, 0x4b800000, v115
	v_cmp_gt_f32_e64 s[8:9], s73, v115
	v_pk_add_f32 v[126:127], v[194:195], v[196:197]
	v_cmp_gt_f32_e64 s[10:11], s73, v114
	v_cndmask_b32_e64 v165, v115, v124, s[8:9]
	v_pk_add_f32 v[124:125], v[132:133], v[134:135]
	v_mov_b32_e32 v128, v126
	v_mov_b32_e32 v129, v124
	v_mov_b32_e32 v124, v127
	v_pk_add_f32 v[124:125], v[128:129], v[124:125]
	ds_bpermute_b32 v127, v157, v125
	ds_bpermute_b32 v126, v157, v124
	v_rsq_f32_e32 v128, v159
	v_mul_f32_e32 v115, 0x4b800000, v114
	v_cndmask_b32_e64 v129, v114, v115, s[10:11]
	v_pk_mul_f32 v[116:117], v[116:117], v[198:199] op_sel_hi:[1,0]
	s_waitcnt lgkmcnt(0)
	v_pk_add_f32 v[114:115], v[124:125], v[126:127]
	ds_bpermute_b32 v125, v155, v115
	ds_bpermute_b32 v124, v155, v114
	v_mul_f32_e32 v126, 0x45800000, v128
	v_rsq_f32_e32 v127, v161
	v_cndmask_b32_e32 v126, v128, v126, vcc
	v_rsq_f32_e32 v128, v163
	s_waitcnt lgkmcnt(0)
	v_pk_add_f32 v[114:115], v[114:115], v[124:125]
	v_mul_f32_e32 v124, 0x45800000, v127
	v_cndmask_b32_e64 v124, v127, v124, s[4:5]
	v_mul_f32_e32 v127, 0x45800000, v128
	v_pk_fma_f32 v[114:115], v[114:115], s[24:25], v[130:131] op_sel_hi:[1,0,0]
	v_rsq_f32_e32 v125, v165
	v_cndmask_b32_e64 v128, v128, v127, s[6:7]
	v_rsq_f32_e32 v127, v129
	v_mul_f32_e32 v129, 0x4b800000, v115
	v_cmp_gt_f32_e32 vcc, s73, v115
	v_cmp_gt_f32_e64 s[4:5], s73, v114
	v_pk_mul_f32 v[118:119], v[118:119], v[198:199] op_sel_hi:[1,0]
	v_cndmask_b32_e32 v129, v115, v129, vcc
	v_mul_f32_e32 v115, 0x4b800000, v114
	v_cndmask_b32_e64 v131, v114, v115, s[4:5]
	v_cvt_pk_bf16_f32 v114, v116, v117
	v_rsq_f32_e32 v117, v129
	v_cvt_pk_bf16_f32 v115, v118, v119
	v_rsq_f32_e32 v119, v131
	v_mul_f32_e32 v116, 0x45800000, v125
	v_pk_mul_f32 v[112:113], v[112:113], v[198:199] op_sel_hi:[1,0]
	v_cndmask_b32_e64 v118, v125, v116, s[8:9]
	v_mul_f32_e32 v116, 0x45800000, v127
	v_cndmask_b32_e64 v130, v127, v116, s[10:11]
	v_cvt_pk_bf16_f32 v116, v112, v113
	v_mul_f32_e32 v112, 0x45800000, v117
	v_cndmask_b32_e32 v132, v117, v112, vcc
	v_mul_f32_e32 v112, 0x45800000, v119
	v_cvt_pk_bf16_f32 v117, v178, v179
	v_cndmask_b32_e64 v112, v119, v112, s[4:5]
	global_store_dwordx4 v[168:169], v[114:117], off offset:256
	v_pk_mul_f32 v[110:111], v[110:111], v[126:127] op_sel_hi:[1,0]
	v_pk_mul_f32 v[108:109], v[108:109], v[126:127] op_sel_hi:[1,0]
	v_mad_i64_i32 v[114:115], s[4:5], v154, s76, v[120:121]
	v_pk_mul_f32 v[116:117], v[106:107], v[126:127] op_sel_hi:[1,0]
	v_pk_mul_f32 v[106:107], v[104:105], v[126:127] op_sel_hi:[1,0]
	v_lshl_add_u64 v[114:115], v[114:115], 0, v[122:123]
	v_cvt_pk_bf16_f32 v104, v108, v109
	v_cvt_pk_bf16_f32 v105, v110, v111
	v_cvt_pk_bf16_f32 v106, v106, v107
	v_cvt_pk_bf16_f32 v107, v116, v117
	global_store_dwordx4 v[114:115], v[104:107], off
	v_pk_mul_f32 v[98:99], v[98:99], v[126:127] op_sel_hi:[1,0]
	v_pk_mul_f32 v[96:97], v[96:97], v[126:127] op_sel_hi:[1,0]
	v_pk_mul_f32 v[104:105], v[90:91], v[126:127] op_sel_hi:[1,0]
	v_pk_mul_f32 v[90:91], v[88:89], v[126:127] op_sel_hi:[1,0]
	v_cvt_pk_bf16_f32 v88, v96, v97
	v_cvt_pk_bf16_f32 v89, v98, v99
	v_cvt_pk_bf16_f32 v90, v90, v91
	v_cvt_pk_bf16_f32 v91, v104, v105
	global_store_dwordx4 v[114:115], v[88:91], off offset:256
	v_pk_mul_f32 v[94:95], v[94:95], v[124:125] op_sel_hi:[1,0]
	v_pk_mul_f32 v[92:93], v[92:93], v[124:125] op_sel_hi:[1,0]
	v_mad_i64_i32 v[88:89], s[4:5], v160, s76, v[120:121]
	v_lshl_add_u64 v[96:97], v[88:89], 0, v[122:123]
	v_pk_mul_f32 v[90:91], v[102:103], v[124:125] op_sel_hi:[1,0]
	v_pk_mul_f32 v[88:89], v[100:101], v[124:125] op_sel_hi:[1,0]
	v_pk_mul_f32 v[82:83], v[82:83], v[124:125] op_sel_hi:[1,0]
	v_cvt_pk_bf16_f32 v88, v88, v89
	v_cvt_pk_bf16_f32 v89, v90, v91
	v_cvt_pk_bf16_f32 v90, v92, v93
; DI unsigned pack2(float lo, float hi) { f32x2 v = {lo, hi}; bf16v2 r = __builtin_convertvector(v, bf16v2); return __builtin_bit_cast(unsigned, r); }
; #define PG8_WAIT_V(n) asm volatile("s_waitcnt vmcnt(" #n ")" ::: "memory")
; #define PG8_BAR __builtin_amdgcn_s_barrier()
;   DI void operator()(const f32x4 (&acc)[2][2][4][2], const Unit& u, int wr, int wc, int fr, int fq) const {
;     ...
; #pragma unroll
;     for (int ai = 0; ai < 2; ++ai)
; #pragma unroll
;       for (int m = 0; m < 4; ++m) {
;         const int row = row0 + ai * HALF + m * 16;
;         const float rs = rsv[ai][m];
;         bf16_t* rowp = O + (size_t)row * ldc + col0;
; #pragma unroll
;         for (int bj = 0; bj < 2; ++bj) {
;           const f32x4 v0 = acc[ai][bj][m][0] * rs, v1 = acc[ai][bj][m][1] * rs;
;           u32x4 w; w.x = pack2(v0[0], v0[1]); w.y = pack2(v0[2], v0[3]); w.z = pack2(v1[0], v1[1]); w.w = pack2(v1[2], v1[3]);
;           *(u32x4*)(rowp + bj * HALF) = w;
;         }
; template <class Epi, class Sched = StaticOrder>
; DI void gemm_phase(LAS unsigned char* lds, const Gemm g, const Sched& S, const Epi& E) {
;     ...
;     E(acc, cur, wr, wc, fr, fq);
;     if (!has_next) break;
; #pragma unroll
;     for (int a = 0; a < 2; ++a)
; #pragma unroll
;       for (int b = 0; b < 2; ++b)
; #pragma unroll
;         for (int m = 0; m < 4; ++m)
; #pragma unroll
;           for (int n = 0; n < 2; ++n) acc[a][b][m][n] = (f32x4){0.f, 0.f, 0.f, 0.f};
;     cur = nxt; cA = nA; cB = nB; ++ui;
;   }
;   PG8_WAIT_V(0);
;   if (wr == 0) PG8_BAR;
;   PG8_BAR;
	v_cvt_pk_bf16_f32 v91, v94, v95
	global_store_dwordx4 v[96:97], v[88:91], off
	v_pk_mul_f32 v[80:81], v[80:81], v[124:125] op_sel_hi:[1,0]
	v_pk_mul_f32 v[78:79], v[78:79], v[128:129] op_sel_hi:[1,0]
	v_pk_mul_f32 v[88:89], v[74:75], v[124:125] op_sel_hi:[1,0]
	v_pk_mul_f32 v[74:75], v[72:73], v[124:125] op_sel_hi:[1,0]
	v_cvt_pk_bf16_f32 v72, v80, v81
	v_cvt_pk_bf16_f32 v73, v82, v83
	v_cvt_pk_bf16_f32 v74, v74, v75
	v_cvt_pk_bf16_f32 v75, v88, v89
	global_store_dwordx4 v[96:97], v[72:75], off offset:256
	v_pk_mul_f32 v[76:77], v[76:77], v[128:129] op_sel_hi:[1,0]
	v_pk_mul_f32 v[70:71], v[70:71], v[128:129] op_sel_hi:[1,0]
	v_mad_i64_i32 v[72:73], s[4:5], v156, s76, v[120:121]
	v_lshl_add_u64 v[80:81], v[72:73], 0, v[122:123]
	v_pk_mul_f32 v[74:75], v[86:87], v[128:129] op_sel_hi:[1,0]
	v_pk_mul_f32 v[72:73], v[84:85], v[128:129] op_sel_hi:[1,0]
	v_pk_mul_f32 v[68:69], v[68:69], v[128:129] op_sel_hi:[1,0]
	v_cvt_pk_bf16_f32 v72, v72, v73
	v_cvt_pk_bf16_f32 v73, v74, v75
	v_cvt_pk_bf16_f32 v74, v76, v77
	v_cvt_pk_bf16_f32 v75, v78, v79
	global_store_dwordx4 v[80:81], v[72:75], off
	v_pk_mul_f32 v[62:63], v[62:63], v[118:119] op_sel_hi:[1,0]
	v_pk_mul_f32 v[60:61], v[60:61], v[118:119] op_sel_hi:[1,0]
	v_pk_mul_f32 v[72:73], v[66:67], v[128:129] op_sel_hi:[1,0]
	v_pk_mul_f32 v[66:67], v[64:65], v[128:129] op_sel_hi:[1,0]
	v_cvt_pk_bf16_f32 v64, v68, v69
	v_cvt_pk_bf16_f32 v65, v70, v71
	v_cvt_pk_bf16_f32 v66, v66, v67
	v_cvt_pk_bf16_f32 v67, v72, v73
	global_store_dwordx4 v[80:81], v[64:67], off offset:256
	v_pk_mul_f32 v[50:51], v[50:51], v[118:119] op_sel_hi:[1,0]
	v_pk_mul_f32 v[48:49], v[48:49], v[118:119] op_sel_hi:[1,0]
	v_mad_i64_i32 v[64:65], s[4:5], v164, s76, v[120:121]
	v_pk_mul_f32 v[66:67], v[58:59], v[118:119] op_sel_hi:[1,0]
	v_pk_mul_f32 v[58:59], v[56:57], v[118:119] op_sel_hi:[1,0]
	v_lshl_add_u64 v[64:65], v[64:65], 0, v[122:123]
	v_cvt_pk_bf16_f32 v56, v60, v61
	v_cvt_pk_bf16_f32 v57, v62, v63
	v_cvt_pk_bf16_f32 v58, v58, v59
	v_cvt_pk_bf16_f32 v59, v66, v67
	global_store_dwordx4 v[64:65], v[56:59], off
	v_pk_mul_f32 v[46:47], v[46:47], v[130:131] op_sel_hi:[1,0]
	v_pk_mul_f32 v[44:45], v[44:45], v[130:131] op_sel_hi:[1,0]
	v_pk_mul_f32 v[56:57], v[42:43], v[118:119] op_sel_hi:[1,0]
	v_pk_mul_f32 v[42:43], v[40:41], v[118:119] op_sel_hi:[1,0]
	v_cvt_pk_bf16_f32 v40, v48, v49
	v_cvt_pk_bf16_f32 v41, v50, v51
	v_cvt_pk_bf16_f32 v42, v42, v43
	v_cvt_pk_bf16_f32 v43, v56, v57
	global_store_dwordx4 v[64:65], v[40:43], off offset:256
	v_pk_mul_f32 v[34:35], v[34:35], v[130:131] op_sel_hi:[1,0]
	v_pk_mul_f32 v[32:33], v[32:33], v[130:131] op_sel_hi:[1,0]
	v_mad_i64_i32 v[40:41], s[4:5], v158, s76, v[120:121]
	v_lshl_add_u64 v[48:49], v[40:41], 0, v[122:123]
	v_pk_mul_f32 v[42:43], v[54:55], v[130:131] op_sel_hi:[1,0]
	v_pk_mul_f32 v[40:41], v[52:53], v[130:131] op_sel_hi:[1,0]
	v_pk_mul_f32 v[30:31], v[30:31], v[132:133] op_sel_hi:[1,0]
	v_cvt_pk_bf16_f32 v40, v40, v41
	v_cvt_pk_bf16_f32 v41, v42, v43
	v_cvt_pk_bf16_f32 v42, v44, v45
	v_cvt_pk_bf16_f32 v43, v46, v47
	global_store_dwordx4 v[48:49], v[40:43], off
	v_pk_mul_f32 v[28:29], v[28:29], v[132:133] op_sel_hi:[1,0]
	v_pk_mul_f32 v[18:19], v[18:19], v[132:133] op_sel_hi:[1,0]
	v_pk_mul_f32 v[40:41], v[26:27], v[130:131] op_sel_hi:[1,0]
	v_pk_mul_f32 v[26:27], v[24:25], v[130:131] op_sel_hi:[1,0]
	v_cvt_pk_bf16_f32 v24, v32, v33
	v_cvt_pk_bf16_f32 v25, v34, v35
	v_cvt_pk_bf16_f32 v26, v26, v27
	v_cvt_pk_bf16_f32 v27, v40, v41
	global_store_dwordx4 v[48:49], v[24:27], off offset:256
	v_pk_mul_f32 v[16:17], v[16:17], v[132:133] op_sel_hi:[1,0]
	v_pk_mul_f32 v[14:15], v[14:15], v[112:113] op_sel_hi:[1,0]
	v_mad_i64_i32 v[24:25], s[4:5], v166, s76, v[120:121]
	v_lshl_add_u64 v[32:33], v[24:25], 0, v[122:123]
	v_pk_mul_f32 v[26:27], v[38:39], v[132:133] op_sel_hi:[1,0]
	v_pk_mul_f32 v[24:25], v[36:37], v[132:133] op_sel_hi:[1,0]
	v_pk_mul_f32 v[12:13], v[12:13], v[112:113] op_sel_hi:[1,0]
	v_cvt_pk_bf16_f32 v24, v24, v25
	v_cvt_pk_bf16_f32 v25, v26, v27
	v_cvt_pk_bf16_f32 v26, v28, v29
	v_cvt_pk_bf16_f32 v27, v30, v31
	global_store_dwordx4 v[32:33], v[24:27], off
	v_pk_mul_f32 v[6:7], v[6:7], v[112:113] op_sel_hi:[1,0]
	v_pk_mul_f32 v[4:5], v[4:5], v[112:113] op_sel_hi:[1,0]
	v_pk_mul_f32 v[24:25], v[10:11], v[132:133] op_sel_hi:[1,0]
	v_pk_mul_f32 v[10:11], v[8:9], v[132:133] op_sel_hi:[1,0]
	v_cvt_pk_bf16_f32 v8, v16, v17
	v_cvt_pk_bf16_f32 v9, v18, v19
	v_cvt_pk_bf16_f32 v10, v10, v11
	v_cvt_pk_bf16_f32 v11, v24, v25
	global_store_dwordx4 v[32:33], v[8:11], off offset:256
	s_and_b64 vcc, exec, s[0:1]
	s_mov_b64 s[8:9], s[36:37]
	v_mad_i64_i32 v[8:9], s[4:5], v162, s76, v[120:121]
	v_lshl_add_u64 v[16:17], v[8:9], 0, v[122:123]
	v_pk_mul_f32 v[10:11], v[22:23], v[112:113] op_sel_hi:[1,0]
	v_pk_mul_f32 v[8:9], v[20:21], v[112:113] op_sel_hi:[1,0]
	s_mov_b32 s5, s28
	v_cvt_pk_bf16_f32 v8, v8, v9
	v_cvt_pk_bf16_f32 v9, v10, v11
	v_cvt_pk_bf16_f32 v10, v12, v13
	v_cvt_pk_bf16_f32 v11, v14, v15
	global_store_dwordx4 v[16:17], v[8:11], off
	s_mov_b32 s4, s30
	s_mov_b64 s[6:7], s[34:35]
	v_pk_mul_f32 v[8:9], v[2:3], v[112:113] op_sel_hi:[1,0]
	v_pk_mul_f32 v[2:3], v[0:1], v[112:113] op_sel_hi:[1,0]
	v_cvt_pk_bf16_f32 v0, v4, v5
	v_cvt_pk_bf16_f32 v1, v6, v7
	v_cvt_pk_bf16_f32 v2, v2, v3
	v_cvt_pk_bf16_f32 v3, v8, v9
	global_store_dwordx4 v[16:17], v[0:3], off offset:256
	s_cbranch_vccz .LBB0_343
	s_waitcnt vmcnt(0)
	s_cmpk_gt_u32 s27, 0xff
	s_cbranch_scc1 .LBB0_350
	s_barrier

; #define PG8_STAGE(bufoff, gbase, voff) do { _Pragma("unroll") for (int _i = 0; _i < 2; ++_i) \
;     __builtin_amdgcn_global_load_lds((const unsigned*)((const char*)(gbase) + (voff)[_i]), (LAS unsigned*)(lds + (bufoff) + ldsw + _i * 8192), 16, 0, 0); } while (0)
; #define PG8_LDA(dst, b, h) do { _Pragma("unroll") for (int m = 0; m < 4; ++m) _Pragma("unroll") for (int k = 0; k < 2; ++k) dst[m][k] = *(const LAS bf16x8*)(lds + PG8_SA(b, h) + aoff + m * 2048 + k * 1024); } while (0)
; #define PG8_LDB(dst, b, h) do { _Pragma("unroll") for (int n = 0; n < 2; ++n) _Pragma("unroll") for (int k = 0; k < 2; ++k) dst[n][k] = *(const LAS bf16x8*)(lds + PG8_SB(b, h) + boff + n * 2048 + k * 1024); } while (0)
; #define PG8_MMA(ai, bj, At, Bt) do { __builtin_amdgcn_s_setprio(1); _Pragma("unroll") for (int m = 0; m < 4; ++m) _Pragma("unroll") for (int n = 0; n < 2; ++n) _Pragma("unroll") for (int k = 0; k < 2; ++k) \
;     acc[ai][bj][m][n] = __builtin_amdgcn_mfma_f32_16x16x32_bf16(Bt[n][k], At[m][k], acc[ai][bj][m][n], 0, 0, 0); __builtin_amdgcn_s_setprio(0); } while (0)
; #define PG8_WAIT_V(n) asm volatile("s_waitcnt vmcnt(" #n ")" ::: "memory")
; #define PG8_WAIT_L(n) asm volatile("s_waitcnt lgkmcnt(" #n ")" ::: "memory")
; #define PG8_BAR __builtin_amdgcn_s_barrier()
; #define PG8_SCHED __builtin_amdgcn_sched_barrier(0)
; template <class Epi, class Sched = StaticOrder>
; DI void gemm_phase(LAS unsigned char* lds, const Gemm g, const Sched& S, const Epi& E) {
;     ...
;     for (int t = 0; t < nt; t += 2) {
;       const bool last = (t == nt - 2);
;       const char* a1 = cA + (size_t)(t + 1) * kstep;
;       const char* a2 = last ? nA : cA + (size_t)(t + 2) * kstep; const char* b2 = last ? nB : cB + (size_t)(t + 2) * kstep;
;       const char* a3 = a2 + kstep; const char* b3 = b2 + kstep;
;       PG8_LDB(B0, 0, 0); PG8_SCHED; PG8_LDA(At, 0, 0); PG8_STAGE(PG8_SA(1, 1), a1 + hstep, voffA);
;       PG8_WAIT_L(8); PG8_BAR; PG8_WAIT_L(0); PG8_MMA(0, 0, At, B0); PG8_BAR; PG8_SCHED;
;       PG8_LDB(B1, 0, 1); PG8_STAGE(PG8_SB(0, 0), b2, voffB);
;       PG8_BAR; PG8_WAIT_L(0); PG8_MMA(0, 1, At, B1); PG8_BAR;
;       PG8_LDA(At, 0, 1); PG8_STAGE(PG8_SA(0, 0), a2, voffA);
;       PG8_BAR; PG8_WAIT_L(0); PG8_MMA(1, 0, At, B0); PG8_BAR; PG8_SCHED;
;       PG8_STAGE(PG8_SB(0, 1), b2 + hstep, voffB);
;       PG8_WAIT_V(6); PG8_BAR; PG8_MMA(1, 1, At, B1); PG8_BAR;
.LBB0_728:
	ds_read_b128 v[128:131], v207
	ds_read_b128 v[132:135], v207 offset:1024
	ds_read_b128 v[136:139], v207 offset:2048
	ds_read_b128 v[140:143], v207 offset:3072
	s_add_u32 s24, s22, 0xfff80080
	s_addc_u32 s25, s23, -1
	s_cmp_eq_u32 s53, 28
	s_cselect_b32 s27, s17, s25
	s_cselect_b32 s26, s43, s24
	s_cselect_b32 s25, s15, s52
	s_cselect_b32 s24, s44, s45
	s_add_i32 m0, s37, 0xc000
	ds_read_b128 v[144:147], v208
	ds_read_b128 v[148:151], v208 offset:1024
	ds_read_b128 v[152:155], v208 offset:2048
	ds_read_b128 v[156:159], v208 offset:3072
	ds_read_b128 v[160:163], v208 offset:4096
	ds_read_b128 v[164:167], v208 offset:5120
	ds_read_b128 v[168:171], v208 offset:6144
	ds_read_b128 v[172:175], v208 offset:7168
	global_load_lds_dwordx4 v184, s[22:23]
	s_add_i32 m0, s37, 0xe000
	s_nop 0
	global_load_lds_dwordx4 v186, s[22:23]
	ds_read_b128 v[192:195], v209
	ds_read_b128 v[196:199], v209 offset:1024
	ds_read_b128 v[200:203], v209 offset:2048
	ds_read_b128 v[212:215], v209 offset:3072
	s_waitcnt vmcnt(8)
	s_waitcnt lgkmcnt(4)
	s_setprio 1
	s_barrier
	v_mfma_f32_16x16x32_bf16 v[124:127], v[128:131], v[144:147], v[124:127]
	v_mfma_f32_16x16x32_bf16 v[120:123], v[136:139], v[144:147], v[120:123]
	v_mfma_f32_16x16x32_bf16 v[108:111], v[128:131], v[152:155], v[108:111]
	v_mfma_f32_16x16x32_bf16 v[104:107], v[136:139], v[152:155], v[104:107]
	v_mfma_f32_16x16x32_bf16 v[92:95], v[128:131], v[160:163], v[92:95]
	v_mfma_f32_16x16x32_bf16 v[88:91], v[136:139], v[160:163], v[88:91]
	v_mfma_f32_16x16x32_bf16 v[76:79], v[128:131], v[168:171], v[76:79]
	v_mfma_f32_16x16x32_bf16 v[72:75], v[136:139], v[168:171], v[72:75]
	v_mfma_f32_16x16x32_bf16 v[124:127], v[132:135], v[148:151], v[124:127]
	v_mfma_f32_16x16x32_bf16 v[120:123], v[140:143], v[148:151], v[120:123]
	v_mfma_f32_16x16x32_bf16 v[108:111], v[132:135], v[156:159], v[108:111]
	v_mfma_f32_16x16x32_bf16 v[104:107], v[140:143], v[156:159], v[104:107]
	v_mfma_f32_16x16x32_bf16 v[92:95], v[132:135], v[164:167], v[92:95]
	v_mfma_f32_16x16x32_bf16 v[88:91], v[140:143], v[164:167], v[88:91]
	v_mfma_f32_16x16x32_bf16 v[76:79], v[132:135], v[172:175], v[76:79]
	v_mfma_f32_16x16x32_bf16 v[72:75], v[140:143], v[172:175], v[72:75]
	s_waitcnt lgkmcnt(0)
	v_mfma_f32_16x16x32_bf16 v[116:119], v[192:195], v[144:147], v[116:119]
	v_mfma_f32_16x16x32_bf16 v[112:115], v[200:203], v[144:147], v[112:115]
	v_mfma_f32_16x16x32_bf16 v[100:103], v[192:195], v[152:155], v[100:103]
	v_mfma_f32_16x16x32_bf16 v[96:99], v[200:203], v[152:155], v[96:99]
	v_mfma_f32_16x16x32_bf16 v[84:87], v[192:195], v[160:163], v[84:87]
	v_mfma_f32_16x16x32_bf16 v[80:83], v[200:203], v[160:163], v[80:83]
	v_mfma_f32_16x16x32_bf16 v[68:71], v[192:195], v[168:171], v[68:71]
	v_mfma_f32_16x16x32_bf16 v[64:67], v[200:203], v[168:171], v[64:67]
	v_mfma_f32_16x16x32_bf16 v[116:119], v[196:199], v[148:151], v[116:119]
	v_mfma_f32_16x16x32_bf16 v[112:115], v[212:215], v[148:151], v[112:115]
	v_mfma_f32_16x16x32_bf16 v[100:103], v[196:199], v[156:159], v[100:103]
	v_mfma_f32_16x16x32_bf16 v[96:99], v[212:215], v[156:159], v[96:99]
	v_mfma_f32_16x16x32_bf16 v[84:87], v[196:199], v[164:167], v[84:87]
	v_mfma_f32_16x16x32_bf16 v[80:83], v[212:215], v[164:167], v[80:83]
	v_mfma_f32_16x16x32_bf16 v[68:71], v[196:199], v[172:175], v[68:71]
	v_mfma_f32_16x16x32_bf16 v[64:67], v[212:215], v[172:175], v[64:67]
	s_barrier
	s_setprio 0
	s_add_i32 s54, s50, s35
	s_add_u32 s98, s24, 0x80
	s_addc_u32 s99, s25, 0
	s_add_u32 s100, s26, 0x80
	s_addc_u32 s101, s27, 0
	s_mov_b32 m0, s54
	s_nop 0
	global_load_lds_dwordx4 v180, s[24:25]
	s_add_i32 m0, s54, 0x2000
	s_nop 0
	global_load_lds_dwordx4 v176, s[24:25]
	s_mov_b32 m0, s37
	ds_read_b128 v[144:147], v208 offset:16384
	ds_read_b128 v[148:151], v208 offset:17408
	ds_read_b128 v[152:155], v208 offset:18432
	ds_read_b128 v[156:159], v208 offset:19456
	ds_read_b128 v[160:163], v208 offset:20480
	ds_read_b128 v[164:167], v208 offset:21504
	ds_read_b128 v[168:171], v208 offset:22528
	ds_read_b128 v[172:175], v208 offset:23552
	global_load_lds_dwordx4 v182, s[26:27]
	s_mov_b32 m0, s38
	s_nop 0
	global_load_lds_dwordx4 v178, s[26:27]
	s_add_u32 s54, s24, 0x80000
	s_addc_u32 s55, s25, 0
	s_add_i32 s57, s51, s35
	s_mov_b32 m0, s57
	s_nop 0
	global_load_lds_dwordx4 v180, s[54:55]
	s_add_i32 m0, s57, 0x2000
	s_nop 0
	global_load_lds_dwordx4 v176, s[54:55]
	s_waitcnt vmcnt(8)
	s_waitcnt lgkmcnt(0)
	s_setprio 1
	s_barrier
	v_mfma_f32_16x16x32_bf16 v[60:63], v[128:131], v[144:147], v[60:63]
	v_mfma_f32_16x16x32_bf16 v[56:59], v[136:139], v[144:147], v[56:59]
	v_mfma_f32_16x16x32_bf16 v[44:47], v[128:131], v[152:155], v[44:47]
	v_mfma_f32_16x16x32_bf16 v[40:43], v[136:139], v[152:155], v[40:43]
	v_mfma_f32_16x16x32_bf16 v[28:31], v[128:131], v[160:163], v[28:31]
	v_mfma_f32_16x16x32_bf16 v[24:27], v[136:139], v[160:163], v[24:27]
	v_mfma_f32_16x16x32_bf16 v[12:15], v[128:131], v[168:171], v[12:15]
	v_mfma_f32_16x16x32_bf16 v[8:11], v[136:139], v[168:171], v[8:11]
	v_mfma_f32_16x16x32_bf16 v[60:63], v[132:135], v[148:151], v[60:63]
	v_mfma_f32_16x16x32_bf16 v[56:59], v[140:143], v[148:151], v[56:59]
	v_mfma_f32_16x16x32_bf16 v[44:47], v[132:135], v[156:159], v[44:47]
	v_mfma_f32_16x16x32_bf16 v[40:43], v[140:143], v[156:159], v[40:43]
	v_mfma_f32_16x16x32_bf16 v[28:31], v[132:135], v[164:167], v[28:31]
	v_mfma_f32_16x16x32_bf16 v[24:27], v[140:143], v[164:167], v[24:27]
	v_mfma_f32_16x16x32_bf16 v[12:15], v[132:135], v[172:175], v[12:15]
	v_mfma_f32_16x16x32_bf16 v[8:11], v[140:143], v[172:175], v[8:11]
	v_mfma_f32_16x16x32_bf16 v[52:55], v[192:195], v[144:147], v[52:55]
	v_mfma_f32_16x16x32_bf16 v[48:51], v[200:203], v[144:147], v[48:51]
	v_mfma_f32_16x16x32_bf16 v[36:39], v[192:195], v[152:155], v[36:39]
	v_mfma_f32_16x16x32_bf16 v[32:35], v[200:203], v[152:155], v[32:35]
	v_mfma_f32_16x16x32_bf16 v[20:23], v[192:195], v[160:163], v[20:23]
	v_mfma_f32_16x16x32_bf16 v[16:19], v[200:203], v[160:163], v[16:19]
	v_mfma_f32_16x16x32_bf16 v[4:7], v[192:195], v[168:171], v[4:7]
	v_mfma_f32_16x16x32_bf16 v[0:3], v[200:203], v[168:171], v[0:3]
	v_mfma_f32_16x16x32_bf16 v[52:55], v[196:199], v[148:151], v[52:55]
	v_mfma_f32_16x16x32_bf16 v[48:51], v[212:215], v[148:151], v[48:51]
	v_mfma_f32_16x16x32_bf16 v[36:39], v[196:199], v[156:159], v[36:39]
	v_mfma_f32_16x16x32_bf16 v[32:35], v[212:215], v[156:159], v[32:35]
	v_mfma_f32_16x16x32_bf16 v[20:23], v[196:199], v[164:167], v[20:23]
	v_mfma_f32_16x16x32_bf16 v[16:19], v[212:215], v[164:167], v[16:19]
	v_mfma_f32_16x16x32_bf16 v[4:7], v[196:199], v[172:175], v[4:7]
	v_mfma_f32_16x16x32_bf16 v[0:3], v[212:215], v[172:175], v[0:3]
	s_barrier
; #define PG8_STAGE(bufoff, gbase, voff) do { _Pragma("unroll") for (int _i = 0; _i < 2; ++_i) \
;     __builtin_amdgcn_global_load_lds((const unsigned*)((const char*)(gbase) + (voff)[_i]), (LAS unsigned*)(lds + (bufoff) + ldsw + _i * 8192), 16, 0, 0); } while (0)
; #define PG8_LDA(dst, b, h) do { _Pragma("unroll") for (int m = 0; m < 4; ++m) _Pragma("unroll") for (int k = 0; k < 2; ++k) dst[m][k] = *(const LAS bf16x8*)(lds + PG8_SA(b, h) + aoff + m * 2048 + k * 1024); } while (0)
; #define PG8_LDB(dst, b, h) do { _Pragma("unroll") for (int n = 0; n < 2; ++n) _Pragma("unroll") for (int k = 0; k < 2; ++k) dst[n][k] = *(const LAS bf16x8*)(lds + PG8_SB(b, h) + boff + n * 2048 + k * 1024); } while (0)
; #define PG8_MMA(ai, bj, At, Bt) do { __builtin_amdgcn_s_setprio(1); _Pragma("unroll") for (int m = 0; m < 4; ++m) _Pragma("unroll") for (int n = 0; n < 2; ++n) _Pragma("unroll") for (int k = 0; k < 2; ++k) \
;     acc[ai][bj][m][n] = __builtin_amdgcn_mfma_f32_16x16x32_bf16(Bt[n][k], At[m][k], acc[ai][bj][m][n], 0, 0, 0); __builtin_amdgcn_s_setprio(0); } while (0)
; #define PG8_WAIT_V(n) asm volatile("s_waitcnt vmcnt(" #n ")" ::: "memory")
; #define PG8_WAIT_L(n) asm volatile("s_waitcnt lgkmcnt(" #n ")" ::: "memory")
; #define PG8_BAR __builtin_amdgcn_s_barrier()
; #define PG8_SCHED __builtin_amdgcn_sched_barrier(0)
; template <class Epi, class Sched = StaticOrder>
; DI void gemm_phase(LAS unsigned char* lds, const Gemm g, const Sched& S, const Epi& E) {
;     ...
;       PG8_LDB(B0, 1, 0); PG8_SCHED; PG8_LDA(At, 1, 0); PG8_STAGE(PG8_SA(0, 1), a2 + hstep, voffA);
;       PG8_WAIT_L(8); PG8_BAR; PG8_WAIT_L(0); PG8_MMA(0, 0, At, B0); PG8_BAR; PG8_SCHED;
;       PG8_LDB(B1, 1, 1); PG8_STAGE(PG8_SB(1, 0), b3, voffB);
;       PG8_BAR; PG8_WAIT_L(0); PG8_MMA(0, 1, At, B1); PG8_BAR;
;       PG8_LDA(At, 1, 1); PG8_STAGE(PG8_SA(1, 0), a3, voffA);
;       PG8_BAR; PG8_WAIT_L(0); PG8_MMA(1, 0, At, B0); PG8_BAR; PG8_SCHED;
;       PG8_STAGE(PG8_SB(1, 1), b3 + hstep, voffB);
;       PG8_WAIT_V(6); PG8_BAR; PG8_MMA(1, 1, At, B1); PG8_BAR;
	s_setprio 0
	s_add_i32 s54, 0, 0x18000
	v_add_u32_e32 v140, s54, v205
	ds_read_b128 v[128:131], v140
	ds_read_b128 v[132:135], v140 offset:1024
	ds_read_b128 v[136:139], v140 offset:2048
	ds_read_b128 v[140:143], v140 offset:3072
	s_add_u32 s26, s26, 0x80000
	s_addc_u32 s27, s27, 0
	s_mov_b32 m0, s39
	ds_read_b128 v[144:147], v208 offset:32768
	ds_read_b128 v[148:151], v208 offset:33792
	ds_read_b128 v[152:155], v208 offset:34816
	ds_read_b128 v[156:159], v208 offset:35840
	ds_read_b128 v[160:163], v208 offset:36864
	ds_read_b128 v[164:167], v208 offset:37888
	ds_read_b128 v[168:171], v208 offset:38912
	ds_read_b128 v[172:175], v208 offset:39936
	global_load_lds_dwordx4 v182, s[26:27]
	s_mov_b32 m0, s40
	s_nop 0
	global_load_lds_dwordx4 v178, s[26:27]
	s_add_i32 s26, 0, 0x1c000
	v_add_u32_e32 v212, s26, v205
	ds_read_b128 v[192:195], v212
	ds_read_b128 v[196:199], v212 offset:1024
	ds_read_b128 v[200:203], v212 offset:2048
	ds_read_b128 v[212:215], v212 offset:3072
	s_waitcnt vmcnt(8)
	s_waitcnt lgkmcnt(4)
	s_setprio 1
	s_barrier
	v_mfma_f32_16x16x32_bf16 v[124:127], v[128:131], v[144:147], v[124:127]
	v_mfma_f32_16x16x32_bf16 v[120:123], v[136:139], v[144:147], v[120:123]
	v_mfma_f32_16x16x32_bf16 v[108:111], v[128:131], v[152:155], v[108:111]
	v_mfma_f32_16x16x32_bf16 v[104:107], v[136:139], v[152:155], v[104:107]
	v_mfma_f32_16x16x32_bf16 v[92:95], v[128:131], v[160:163], v[92:95]
	v_mfma_f32_16x16x32_bf16 v[88:91], v[136:139], v[160:163], v[88:91]
	v_mfma_f32_16x16x32_bf16 v[76:79], v[128:131], v[168:171], v[76:79]
	v_mfma_f32_16x16x32_bf16 v[72:75], v[136:139], v[168:171], v[72:75]
	v_mfma_f32_16x16x32_bf16 v[124:127], v[132:135], v[148:151], v[124:127]
	v_mfma_f32_16x16x32_bf16 v[120:123], v[140:143], v[148:151], v[120:123]
	v_mfma_f32_16x16x32_bf16 v[108:111], v[132:135], v[156:159], v[108:111]
	v_mfma_f32_16x16x32_bf16 v[104:107], v[140:143], v[156:159], v[104:107]
	v_mfma_f32_16x16x32_bf16 v[92:95], v[132:135], v[164:167], v[92:95]
	v_mfma_f32_16x16x32_bf16 v[88:91], v[140:143], v[164:167], v[88:91]
	v_mfma_f32_16x16x32_bf16 v[76:79], v[132:135], v[172:175], v[76:79]
	v_mfma_f32_16x16x32_bf16 v[72:75], v[140:143], v[172:175], v[72:75]
	s_waitcnt lgkmcnt(0)
	v_mfma_f32_16x16x32_bf16 v[116:119], v[192:195], v[144:147], v[116:119]
	v_mfma_f32_16x16x32_bf16 v[112:115], v[200:203], v[144:147], v[112:115]
	v_mfma_f32_16x16x32_bf16 v[100:103], v[192:195], v[152:155], v[100:103]
	v_mfma_f32_16x16x32_bf16 v[96:99], v[200:203], v[152:155], v[96:99]
	v_mfma_f32_16x16x32_bf16 v[84:87], v[192:195], v[160:163], v[84:87]
	v_mfma_f32_16x16x32_bf16 v[80:83], v[200:203], v[160:163], v[80:83]
	v_mfma_f32_16x16x32_bf16 v[68:71], v[192:195], v[168:171], v[68:71]
	v_mfma_f32_16x16x32_bf16 v[64:67], v[200:203], v[168:171], v[64:67]
	v_mfma_f32_16x16x32_bf16 v[116:119], v[196:199], v[148:151], v[116:119]
	v_mfma_f32_16x16x32_bf16 v[112:115], v[212:215], v[148:151], v[112:115]
	v_mfma_f32_16x16x32_bf16 v[100:103], v[196:199], v[156:159], v[100:103]
	v_mfma_f32_16x16x32_bf16 v[96:99], v[212:215], v[156:159], v[96:99]
	v_mfma_f32_16x16x32_bf16 v[84:87], v[196:199], v[164:167], v[84:87]
	v_mfma_f32_16x16x32_bf16 v[80:83], v[212:215], v[164:167], v[80:83]
	v_mfma_f32_16x16x32_bf16 v[68:71], v[196:199], v[172:175], v[68:71]
	v_mfma_f32_16x16x32_bf16 v[64:67], v[212:215], v[172:175], v[64:67]
	s_barrier
	s_setprio 0
	s_add_i32 s27, s54, s35
	s_mov_b32 m0, s27
	s_nop 0
	global_load_lds_dwordx4 v180, s[98:99]
	s_add_i32 m0, s27, 0x2000
	s_nop 0
	global_load_lds_dwordx4 v176, s[98:99]
	s_mov_b32 m0, s46
	ds_read_b128 v[144:147], v208 offset:49152
	ds_read_b128 v[148:151], v208 offset:50176
	ds_read_b128 v[152:155], v208 offset:51200
	ds_read_b128 v[156:159], v208 offset:52224
	ds_read_b128 v[160:163], v208 offset:53248
	ds_read_b128 v[164:167], v208 offset:54272
	ds_read_b128 v[168:171], v208 offset:55296
	ds_read_b128 v[172:175], v208 offset:56320
	global_load_lds_dwordx4 v182, s[100:101]
	s_mov_b32 m0, s47
	s_nop 0
	global_load_lds_dwordx4 v178, s[100:101]
	s_add_u32 s24, s24, 0x80080
	s_addc_u32 s25, s25, 0
	s_add_i32 s26, s26, s35
	s_mov_b32 m0, s26
	s_nop 0
	global_load_lds_dwordx4 v180, s[24:25]
	s_add_i32 m0, s26, 0x2000
	s_nop 0
	global_load_lds_dwordx4 v176, s[24:25]
	s_add_i32 s53, s53, 2
	s_add_u32 s22, s22, 0x100
	s_addc_u32 s23, s23, 0
	s_add_u32 s45, s45, 0x100
	s_addc_u32 s52, s52, 0
	s_cmp_gt_u32 s53, 29
	s_waitcnt vmcnt(8)
	s_waitcnt lgkmcnt(0)
	s_setprio 1
	s_barrier
	v_mfma_f32_16x16x32_bf16 v[60:63], v[128:131], v[144:147], v[60:63]
	v_mfma_f32_16x16x32_bf16 v[56:59], v[136:139], v[144:147], v[56:59]
	v_mfma_f32_16x16x32_bf16 v[44:47], v[128:131], v[152:155], v[44:47]
	v_mfma_f32_16x16x32_bf16 v[40:43], v[136:139], v[152:155], v[40:43]
	v_mfma_f32_16x16x32_bf16 v[28:31], v[128:131], v[160:163], v[28:31]
	v_mfma_f32_16x16x32_bf16 v[24:27], v[136:139], v[160:163], v[24:27]
	v_mfma_f32_16x16x32_bf16 v[12:15], v[128:131], v[168:171], v[12:15]
	v_mfma_f32_16x16x32_bf16 v[8:11], v[136:139], v[168:171], v[8:11]
	v_mfma_f32_16x16x32_bf16 v[60:63], v[132:135], v[148:151], v[60:63]
	v_mfma_f32_16x16x32_bf16 v[56:59], v[140:143], v[148:151], v[56:59]
	v_mfma_f32_16x16x32_bf16 v[44:47], v[132:135], v[156:159], v[44:47]
	v_mfma_f32_16x16x32_bf16 v[40:43], v[140:143], v[156:159], v[40:43]
	v_mfma_f32_16x16x32_bf16 v[28:31], v[132:135], v[164:167], v[28:31]
	v_mfma_f32_16x16x32_bf16 v[24:27], v[140:143], v[164:167], v[24:27]
	v_mfma_f32_16x16x32_bf16 v[12:15], v[132:135], v[172:175], v[12:15]
	v_mfma_f32_16x16x32_bf16 v[8:11], v[140:143], v[172:175], v[8:11]
	v_mfma_f32_16x16x32_bf16 v[52:55], v[192:195], v[144:147], v[52:55]
	v_mfma_f32_16x16x32_bf16 v[48:51], v[200:203], v[144:147], v[48:51]
	v_mfma_f32_16x16x32_bf16 v[36:39], v[192:195], v[152:155], v[36:39]
	v_mfma_f32_16x16x32_bf16 v[32:35], v[200:203], v[152:155], v[32:35]
	v_mfma_f32_16x16x32_bf16 v[20:23], v[192:195], v[160:163], v[20:23]
	v_mfma_f32_16x16x32_bf16 v[16:19], v[200:203], v[160:163], v[16:19]
	v_mfma_f32_16x16x32_bf16 v[4:7], v[192:195], v[168:171], v[4:7]
	v_mfma_f32_16x16x32_bf16 v[0:3], v[200:203], v[168:171], v[0:3]
	v_mfma_f32_16x16x32_bf16 v[52:55], v[196:199], v[148:151], v[52:55]
	v_mfma_f32_16x16x32_bf16 v[48:51], v[212:215], v[148:151], v[48:51]
	v_mfma_f32_16x16x32_bf16 v[36:39], v[196:199], v[156:159], v[36:39]
	v_mfma_f32_16x16x32_bf16 v[32:35], v[212:215], v[156:159], v[32:35]
	v_mfma_f32_16x16x32_bf16 v[20:23], v[196:199], v[164:167], v[20:23]
	v_mfma_f32_16x16x32_bf16 v[16:19], v[212:215], v[164:167], v[16:19]
	v_mfma_f32_16x16x32_bf16 v[4:7], v[196:199], v[172:175], v[4:7]
	v_mfma_f32_16x16x32_bf16 v[0:3], v[212:215], v[172:175], v[0:3]
	s_barrier
; DI unsigned pack2(float lo, float hi) { f32x2 v = {lo, hi}; bf16v2 r = __builtin_convertvector(v, bf16v2); return __builtin_bit_cast(unsigned, r); }
;   DI void operator()(const f32x4 (&acc)[2][2][4][2], const Unit& u, int wr, int wc, int fr, int fq) const {
;     const int row0 = u.pm * BM + wr * 64 + fr, col0 = u.pn * BM + wc * 32 + 8 * fq;
; #pragma unroll
;     for (int ai = 0; ai < 2; ++ai) {
;       f32x4 bv[4][2][2];
; #pragma unroll
;       for (int m = 0; m < 4; ++m)
; #pragma unroll
;         for (int bj = 0; bj < 2; ++bj) {
;           const float* bp = base + (size_t)(row0 + ai * HALF + m * 16) * 2048 + col0 + bj * HALF;
;           bv[m][bj][0] = *(const f32x4*)bp; bv[m][bj][1] = *(const f32x4*)(bp + 4);
;         }
; #pragma unroll
;       for (int m = 0; m < 4; ++m) {
;         const int row = row0 + ai * HALF + m * 16;
;         const size_t off = (size_t)row * 2048 + col0;
;         float ss = 0.f;
; #pragma unroll
;         for (int bj = 0; bj < 2; ++bj) {
;           const f32x4 v0 = acc[ai][bj][m][0] + bv[m][bj][0], v1 = acc[ai][bj][m][1] + bv[m][bj][1];
;           *(f32x4*)(C + off + bj * HALF) = v0; *(f32x4*)(C + off + bj * HALF + 4) = v1;
;           if (xb) {
;             u32x4 w; w.x = pack2(v0[0], v0[1]); w.y = pack2(v0[2], v0[3]); w.z = pack2(v1[0], v1[1]); w.w = pack2(v1[2], v1[3]);
;             *(u32x4*)(xb + off + bj * HALF) = w;
;             ss += v0[0] * v0[0] + v0[1] * v0[1] + v0[2] * v0[2] + v0[3] * v0[3] + v1[0] * v1[0] + v1[1] * v1[1] + v1[2] * v1[2] + v1[3] * v1[3];
;           }
;         }
;         if (xb) {
;           ss += __shfl_xor(ss, 16); ss += __shfl_xor(ss, 32);
;           if (fq == 0) ssq[(size_t)row * 32 + u.pn * 4 + wc] = ss;
	s_setprio 0
	s_cbranch_scc0 .LBB0_728
	v_lshl_add_u32 v196, s12, 8, v204
	v_lshl_or_b32 v192, s42, 8, v206
	v_ashrrev_i32_e32 v193, 31, v192
	v_ashrrev_i32_e32 v197, 31, v196
	v_lshl_add_u64 v[194:195], v[192:193], 2, s[60:61]
	v_lshlrev_b64 v[128:129], 13, v[196:197]
	v_lshl_add_u64 v[128:129], v[194:195], 0, v[128:129]
	global_load_dwordx4 v[214:217], v[128:129], off
	global_load_dwordx4 v[218:221], v[128:129], off offset:16
	global_load_dwordx4 v[222:225], v[128:129], off offset:512
	global_load_dwordx4 v[226:229], v[128:129], off offset:528
	v_or_b32_e32 v202, 16, v196
	v_or_b32_e32 v200, 32, v196
	v_or_b32_e32 v198, 48, v196
	v_ashrrev_i32_e32 v203, 31, v202
	v_ashrrev_i32_e32 v201, 31, v200
	v_ashrrev_i32_e32 v199, 31, v198
	v_lshlrev_b64 v[128:129], 13, v[202:203]
	v_lshlrev_b64 v[130:131], 13, v[200:201]
	v_lshlrev_b64 v[132:133], 13, v[198:199]
	v_lshl_add_u64 v[128:129], v[194:195], 0, v[128:129]
	v_lshl_add_u64 v[130:131], v[194:195], 0, v[130:131]
	v_lshl_add_u64 v[132:133], v[194:195], 0, v[132:133]
	global_load_dwordx4 v[168:171], v[128:129], off offset:16
	global_load_dwordx4 v[172:175], v[128:129], off
	global_load_dwordx4 v[160:163], v[128:129], off offset:528
	global_load_dwordx4 v[164:167], v[128:129], off offset:512
	global_load_dwordx4 v[152:155], v[130:131], off offset:16
	global_load_dwordx4 v[156:159], v[130:131], off
	global_load_dwordx4 v[144:147], v[130:131], off offset:528
	global_load_dwordx4 v[148:151], v[130:131], off offset:512
	global_load_dwordx4 v[136:139], v[132:133], off offset:16
	global_load_dwordx4 v[140:143], v[132:133], off
	s_nop 0
	global_load_dwordx4 v[128:131], v[132:133], off offset:528
	s_nop 0
	global_load_dwordx4 v[132:135], v[132:133], off offset:512
	v_and_b32_e32 v212, 64, v211
	v_xor_b32_e32 v230, 16, v211
	v_add_u32_e32 v232, 64, v212
	v_xor_b32_e32 v231, 32, v211
	v_cmp_lt_i32_e32 vcc, v230, v232
	v_lshlrev_b64 v[212:213], 11, v[196:197]
	v_readlane_b32 s64, v243, 3
	v_cndmask_b32_e32 v233, v211, v230, vcc
	v_cmp_lt_i32_e32 vcc, v231, v232
	v_readlane_b32 s78, v243, 17
	v_readlane_b32 s79, v243, 18
	v_cndmask_b32_e32 v234, v211, v231, vcc
	v_lshl_add_u64 v[230:231], v[212:213], 0, v[192:193]
	v_lshlrev_b32_e32 v212, 2, v233
	v_lshl_add_u64 v[232:233], v[230:231], 2, s[78:79]
	v_lshl_add_u64 v[230:231], v[230:231], 1, s[2:3]
	s_lshl_b32 s22, s42, 2
	s_ashr_i32 s23, s22, 31
	v_readlane_b32 s65, v243, 4
	v_readlane_b32 s66, v243, 5
	v_readlane_b32 s67, v243, 6
	v_readlane_b32 s68, v243, 7
	v_readlane_b32 s69, v243, 8
	v_readlane_b32 s70, v243, 9
	v_readlane_b32 s71, v243, 10
	v_readlane_b32 s72, v243, 11
	v_readlane_b32 s73, v243, 12
	v_readlane_b32 s74, v243, 13
	v_readlane_b32 s75, v243, 14
	v_readlane_b32 s76, v243, 15
	v_readlane_b32 s77, v243, 16
	s_waitcnt vmcnt(0)
	v_pk_add_f32 v[126:127], v[126:127], v[216:217]
	v_pk_add_f32 v[124:125], v[124:125], v[214:215]
	v_pk_add_f32 v[116:117], v[116:117], v[222:223]
	v_pk_add_f32 v[122:123], v[122:123], v[220:221]
	v_pk_add_f32 v[120:121], v[120:121], v[218:219]
	v_pk_add_f32 v[214:215], v[112:113], v[226:227]
	global_store_dwordx4 v[232:233], v[124:127], off
	global_store_dwordx4 v[232:233], v[120:123], off offset:16
	v_cvt_pk_bf16_f32 v112, v124, v125
	v_mul_f32_e32 v125, v125, v125
	v_mul_f32_e32 v213, v117, v117
	v_pk_add_f32 v[118:119], v[118:119], v[224:225]
	v_fmac_f32_e32 v125, v124, v124
	v_fmac_f32_e32 v213, v116, v116
	v_fmac_f32_e32 v125, v126, v126
	v_fmac_f32_e32 v213, v118, v118
	v_fmac_f32_e32 v125, v127, v127
	v_fmac_f32_e32 v213, v119, v119
	v_fmac_f32_e32 v125, v120, v120
	v_fmac_f32_e32 v213, v214, v214
	v_pk_add_f32 v[216:217], v[114:115], v[228:229]
	v_fmac_f32_e32 v125, v121, v121
	v_fmac_f32_e32 v213, v215, v215
	v_fmac_f32_e32 v125, v122, v122
	v_fmac_f32_e32 v213, v216, v216
	v_fmac_f32_e32 v125, v123, v123
	v_fmac_f32_e32 v213, v217, v217
	v_cvt_pk_bf16_f32 v114, v120, v121
	v_add_f32_e32 v120, v125, v213
	ds_bpermute_b32 v121, v212, v120
	v_cvt_pk_bf16_f32 v113, v126, v127
	v_cvt_pk_bf16_f32 v115, v122, v123
	global_store_dwordx4 v[230:231], v[112:115], off
	global_store_dwordx4 v[232:233], v[116:119], off offset:512
	global_store_dwordx4 v[232:233], v[214:217], off offset:528
	v_cvt_pk_bf16_f32 v122, v116, v117
	s_waitcnt lgkmcnt(0)
	v_add_f32_e32 v112, v120, v121
	v_lshlrev_b32_e32 v120, 2, v234
	ds_bpermute_b32 v113, v120, v112
	v_cvt_pk_bf16_f32 v123, v118, v119
	v_cvt_pk_bf16_f32 v124, v214, v215
	v_cvt_pk_bf16_f32 v125, v216, v217
	global_store_dwordx4 v[230:231], v[122:125], off offset:256
	s_and_saveexec_b64 s[24:25], s[0:1]
	s_cbranch_execz .LBB0_731
	s_waitcnt lgkmcnt(0)
	v_add_f32_e32 v114, v112, v113
	v_lshlrev_b64 v[112:113], 7, v[196:197]
	v_lshl_add_u64 v[112:113], s[8:9], 0, v[112:113]
	v_lshl_add_u64 v[112:113], s[22:23], 2, v[112:113]
	s_lshl_b32 s12, s41, 2
	v_lshl_add_u64 v[112:113], v[112:113], 0, s[12:13]
	global_store_dword v[112:113], v114, off

; #define PG8_STAGE(bufoff, gbase, voff) do { _Pragma("unroll") for (int _i = 0; _i < 2; ++_i) \
;     __builtin_amdgcn_global_load_lds((const unsigned*)((const char*)(gbase) + (voff)[_i]), (LAS unsigned*)(lds + (bufoff) + ldsw + _i * 8192), 16, 0, 0); } while (0)
; #define PG8_LDA(dst, b, h) do { _Pragma("unroll") for (int m = 0; m < 4; ++m) _Pragma("unroll") for (int k = 0; k < 2; ++k) dst[m][k] = *(const LAS bf16x8*)(lds + PG8_SA(b, h) + aoff + m * 2048 + k * 1024); } while (0)
; #define PG8_LDB(dst, b, h) do { _Pragma("unroll") for (int n = 0; n < 2; ++n) _Pragma("unroll") for (int k = 0; k < 2; ++k) dst[n][k] = *(const LAS bf16x8*)(lds + PG8_SB(b, h) + boff + n * 2048 + k * 1024); } while (0)
; #define PG8_MMA(ai, bj, At, Bt) do { __builtin_amdgcn_s_setprio(1); _Pragma("unroll") for (int m = 0; m < 4; ++m) _Pragma("unroll") for (int n = 0; n < 2; ++n) _Pragma("unroll") for (int k = 0; k < 2; ++k) \
;     acc[ai][bj][m][n] = __builtin_amdgcn_mfma_f32_16x16x32_bf16(Bt[n][k], At[m][k], acc[ai][bj][m][n], 0, 0, 0); __builtin_amdgcn_s_setprio(0); } while (0)
; #define PG8_WAIT_V(n) asm volatile("s_waitcnt vmcnt(" #n ")" ::: "memory")
; #define PG8_WAIT_L(n) asm volatile("s_waitcnt lgkmcnt(" #n ")" ::: "memory")
; #define PG8_BAR __builtin_amdgcn_s_barrier()
; #define PG8_SCHED __builtin_amdgcn_sched_barrier(0)
; template <class Epi, class Sched = StaticOrder>
; DI void gemm_phase(LAS unsigned char* lds, const Gemm g, const Sched& S, const Epi& E) {
;     ...
;     for (int t = 0; t < nt; t += 2) {
;       const bool last = (t == nt - 2);
;       const char* a1 = cA + (size_t)(t + 1) * kstep;
;       const char* a2 = last ? nA : cA + (size_t)(t + 2) * kstep; const char* b2 = last ? nB : cB + (size_t)(t + 2) * kstep;
;       const char* a3 = a2 + kstep; const char* b3 = b2 + kstep;
;       PG8_LDB(B0, 0, 0); PG8_SCHED; PG8_LDA(At, 0, 0); PG8_STAGE(PG8_SA(1, 1), a1 + hstep, voffA);
;       PG8_WAIT_L(8); PG8_BAR; PG8_WAIT_L(0); PG8_MMA(0, 0, At, B0); PG8_BAR; PG8_SCHED;
;       PG8_LDB(B1, 0, 1); PG8_STAGE(PG8_SB(0, 0), b2, voffB);
;       PG8_BAR; PG8_WAIT_L(0); PG8_MMA(0, 1, At, B1); PG8_BAR;
;       PG8_LDA(At, 0, 1); PG8_STAGE(PG8_SA(0, 0), a2, voffA);
;       PG8_BAR; PG8_WAIT_L(0); PG8_MMA(1, 0, At, B0); PG8_BAR; PG8_SCHED;
;       PG8_STAGE(PG8_SB(0, 1), b2 + hstep, voffB);
;       PG8_WAIT_V(6); PG8_BAR; PG8_MMA(1, 1, At, B1); PG8_BAR;
.LBB0_811:
	ds_read_b128 v[64:67], v201
	ds_read_b128 v[68:71], v201 offset:1024
	ds_read_b128 v[72:75], v201 offset:2048
	ds_read_b128 v[76:79], v201 offset:3072
	s_add_u32 s46, s14, 0xfff80080
	s_addc_u32 s47, s15, -1
	s_cmp_eq_u32 s52, 28
	s_cselect_b32 s49, s37, s47
	s_cselect_b32 s48, s42, s46
	s_cselect_b32 s47, s35, s45
	s_cselect_b32 s46, s43, s44
	s_add_i32 m0, s62, 0xc000
	ds_read_b128 v[80:83], v202
	ds_read_b128 v[84:87], v202 offset:1024
	ds_read_b128 v[92:95], v202 offset:2048
	ds_read_b128 v[96:99], v202 offset:3072
	ds_read_b128 v[180:183], v202 offset:4096
	ds_read_b128 v[184:187], v202 offset:5120
	ds_read_b128 v[188:191], v202 offset:6144
	ds_read_b128 v[192:195], v202 offset:7168
	global_load_lds_dwordx4 v170, s[14:15]
	s_add_i32 m0, s62, 0xe000
	s_nop 0
	global_load_lds_dwordx4 v172, s[14:15]
	ds_read_b128 v[206:209], v203
	ds_read_b128 v[212:215], v203 offset:1024
	ds_read_b128 v[216:219], v203 offset:2048
	ds_read_b128 v[220:223], v203 offset:3072
	s_waitcnt vmcnt(8)
	s_waitcnt lgkmcnt(4)
	s_setprio 1
	s_barrier
	v_mfma_f32_16x16x32_bf16 v[156:159], v[64:67], v[80:83], v[156:159]
	v_mfma_f32_16x16x32_bf16 v[144:147], v[72:75], v[80:83], v[144:147]
	v_mfma_f32_16x16x32_bf16 v[140:143], v[64:67], v[92:95], v[140:143]
	v_mfma_f32_16x16x32_bf16 v[132:135], v[72:75], v[92:95], v[132:135]
	v_mfma_f32_16x16x32_bf16 v[124:127], v[64:67], v[180:183], v[124:127]
	v_mfma_f32_16x16x32_bf16 v[116:119], v[72:75], v[180:183], v[116:119]
	v_mfma_f32_16x16x32_bf16 v[112:115], v[64:67], v[188:191], v[112:115]
	v_mfma_f32_16x16x32_bf16 v[108:111], v[72:75], v[188:191], v[108:111]
	v_mfma_f32_16x16x32_bf16 v[156:159], v[68:71], v[84:87], v[156:159]
	v_mfma_f32_16x16x32_bf16 v[144:147], v[76:79], v[84:87], v[144:147]
	v_mfma_f32_16x16x32_bf16 v[140:143], v[68:71], v[96:99], v[140:143]
	v_mfma_f32_16x16x32_bf16 v[132:135], v[76:79], v[96:99], v[132:135]
	v_mfma_f32_16x16x32_bf16 v[124:127], v[68:71], v[184:187], v[124:127]
	v_mfma_f32_16x16x32_bf16 v[116:119], v[76:79], v[184:187], v[116:119]
	v_mfma_f32_16x16x32_bf16 v[112:115], v[68:71], v[192:195], v[112:115]
	v_mfma_f32_16x16x32_bf16 v[108:111], v[76:79], v[192:195], v[108:111]
	s_waitcnt lgkmcnt(0)
	v_mfma_f32_16x16x32_bf16 v[152:155], v[206:209], v[80:83], v[152:155]
	v_mfma_f32_16x16x32_bf16 v[80:83], v[216:219], v[80:83], v[148:151]
	v_mfma_f32_16x16x32_bf16 v[152:155], v[212:215], v[84:87], v[152:155]
	v_mfma_f32_16x16x32_bf16 v[80:83], v[220:223], v[84:87], v[80:83]
	v_mfma_f32_16x16x32_bf16 v[84:87], v[206:209], v[92:95], v[136:139]
	v_mfma_f32_16x16x32_bf16 v[92:95], v[216:219], v[92:95], v[128:131]
	v_mfma_f32_16x16x32_bf16 v[104:107], v[216:219], v[180:183], v[104:107]
	v_mfma_f32_16x16x32_bf16 v[100:103], v[206:209], v[188:191], v[100:103]
	v_mfma_f32_16x16x32_bf16 v[88:91], v[216:219], v[188:191], v[88:91]
	v_mfma_f32_16x16x32_bf16 v[84:87], v[212:215], v[96:99], v[84:87]
	v_mfma_f32_16x16x32_bf16 v[92:95], v[220:223], v[96:99], v[92:95]
	v_mfma_f32_16x16x32_bf16 v[96:99], v[206:209], v[180:183], v[120:123]
	v_mfma_f32_16x16x32_bf16 v[104:107], v[220:223], v[184:187], v[104:107]
	v_mfma_f32_16x16x32_bf16 v[100:103], v[212:215], v[192:195], v[100:103]
	v_mfma_f32_16x16x32_bf16 v[88:91], v[220:223], v[192:195], v[88:91]
	v_mfma_f32_16x16x32_bf16 v[96:99], v[212:215], v[184:187], v[96:99]
	s_barrier
	s_setprio 0
	s_add_i32 s53, s72, s60
	s_add_u32 s98, s46, 0x80
	s_addc_u32 s99, s47, 0
	s_add_u32 s100, s48, 0x80
	s_addc_u32 s101, s49, 0
	s_mov_b32 m0, s53
	s_nop 0
	global_load_lds_dwordx4 v164, s[46:47]
	s_add_i32 m0, s53, 0x2000
	s_nop 0
	global_load_lds_dwordx4 v160, s[46:47]
	s_mov_b32 m0, s62
	ds_read_b128 v[120:123], v202 offset:16384
	ds_read_b128 v[128:131], v202 offset:17408
	ds_read_b128 v[136:139], v202 offset:18432
	ds_read_b128 v[148:151], v202 offset:19456
	ds_read_b128 v[180:183], v202 offset:20480
	ds_read_b128 v[184:187], v202 offset:21504
	ds_read_b128 v[188:191], v202 offset:22528
	ds_read_b128 v[192:195], v202 offset:23552
	global_load_lds_dwordx4 v166, s[48:49]
	s_mov_b32 m0, s63
	s_nop 0
	global_load_lds_dwordx4 v162, s[48:49]
	s_add_u32 s54, s46, 0x80000
	s_addc_u32 s55, s47, 0
	s_add_i32 s53, s73, s60
	s_mov_b32 m0, s53
	s_nop 0
	global_load_lds_dwordx4 v164, s[54:55]
	s_add_i32 m0, s53, 0x2000
	s_nop 0
	global_load_lds_dwordx4 v160, s[54:55]
	s_waitcnt vmcnt(8)
	s_waitcnt lgkmcnt(0)
	s_setprio 1
	s_barrier
	v_mfma_f32_16x16x32_bf16 v[60:63], v[64:67], v[120:123], v[60:63]
	v_mfma_f32_16x16x32_bf16 v[48:51], v[72:75], v[120:123], v[48:51]
	v_mfma_f32_16x16x32_bf16 v[44:47], v[64:67], v[136:139], v[44:47]
	v_mfma_f32_16x16x32_bf16 v[36:39], v[72:75], v[136:139], v[36:39]
	v_mfma_f32_16x16x32_bf16 v[28:31], v[64:67], v[180:183], v[28:31]
	v_mfma_f32_16x16x32_bf16 v[20:23], v[72:75], v[180:183], v[20:23]
	v_mfma_f32_16x16x32_bf16 v[16:19], v[64:67], v[188:191], v[16:19]
	v_mfma_f32_16x16x32_bf16 v[12:15], v[72:75], v[188:191], v[12:15]
	v_mfma_f32_16x16x32_bf16 v[60:63], v[68:71], v[128:131], v[60:63]
	v_mfma_f32_16x16x32_bf16 v[48:51], v[76:79], v[128:131], v[48:51]
	v_mfma_f32_16x16x32_bf16 v[44:47], v[68:71], v[148:151], v[44:47]
	v_mfma_f32_16x16x32_bf16 v[36:39], v[76:79], v[148:151], v[36:39]
	v_mfma_f32_16x16x32_bf16 v[28:31], v[68:71], v[184:187], v[28:31]
	v_mfma_f32_16x16x32_bf16 v[20:23], v[76:79], v[184:187], v[20:23]
	v_mfma_f32_16x16x32_bf16 v[16:19], v[68:71], v[192:195], v[16:19]
	v_mfma_f32_16x16x32_bf16 v[12:15], v[76:79], v[192:195], v[12:15]
	v_mfma_f32_16x16x32_bf16 v[56:59], v[206:209], v[120:123], v[56:59]
	v_mfma_f32_16x16x32_bf16 v[52:55], v[216:219], v[120:123], v[52:55]
	v_mfma_f32_16x16x32_bf16 v[40:43], v[206:209], v[136:139], v[40:43]
	v_mfma_f32_16x16x32_bf16 v[32:35], v[216:219], v[136:139], v[32:35]
	v_mfma_f32_16x16x32_bf16 v[24:27], v[206:209], v[180:183], v[24:27]
	v_mfma_f32_16x16x32_bf16 v[8:11], v[216:219], v[180:183], v[8:11]
	v_mfma_f32_16x16x32_bf16 v[4:7], v[206:209], v[188:191], v[4:7]
	v_mfma_f32_16x16x32_bf16 v[0:3], v[216:219], v[188:191], v[0:3]
	v_mfma_f32_16x16x32_bf16 v[56:59], v[212:215], v[128:131], v[56:59]
	v_mfma_f32_16x16x32_bf16 v[52:55], v[220:223], v[128:131], v[52:55]
	v_mfma_f32_16x16x32_bf16 v[40:43], v[212:215], v[148:151], v[40:43]
	v_mfma_f32_16x16x32_bf16 v[32:35], v[220:223], v[148:151], v[32:35]
	v_mfma_f32_16x16x32_bf16 v[24:27], v[212:215], v[184:187], v[24:27]
	v_mfma_f32_16x16x32_bf16 v[8:11], v[220:223], v[184:187], v[8:11]
	v_mfma_f32_16x16x32_bf16 v[4:7], v[212:215], v[192:195], v[4:7]
	v_mfma_f32_16x16x32_bf16 v[0:3], v[220:223], v[192:195], v[0:3]
	s_barrier
; #define PG8_STAGE(bufoff, gbase, voff) do { _Pragma("unroll") for (int _i = 0; _i < 2; ++_i) \
;     __builtin_amdgcn_global_load_lds((const unsigned*)((const char*)(gbase) + (voff)[_i]), (LAS unsigned*)(lds + (bufoff) + ldsw + _i * 8192), 16, 0, 0); } while (0)
; #define PG8_LDA(dst, b, h) do { _Pragma("unroll") for (int m = 0; m < 4; ++m) _Pragma("unroll") for (int k = 0; k < 2; ++k) dst[m][k] = *(const LAS bf16x8*)(lds + PG8_SA(b, h) + aoff + m * 2048 + k * 1024); } while (0)
; #define PG8_LDB(dst, b, h) do { _Pragma("unroll") for (int n = 0; n < 2; ++n) _Pragma("unroll") for (int k = 0; k < 2; ++k) dst[n][k] = *(const LAS bf16x8*)(lds + PG8_SB(b, h) + boff + n * 2048 + k * 1024); } while (0)
; #define PG8_MMA(ai, bj, At, Bt) do { __builtin_amdgcn_s_setprio(1); _Pragma("unroll") for (int m = 0; m < 4; ++m) _Pragma("unroll") for (int n = 0; n < 2; ++n) _Pragma("unroll") for (int k = 0; k < 2; ++k) \
;     acc[ai][bj][m][n] = __builtin_amdgcn_mfma_f32_16x16x32_bf16(Bt[n][k], At[m][k], acc[ai][bj][m][n], 0, 0, 0); __builtin_amdgcn_s_setprio(0); } while (0)
; #define PG8_WAIT_V(n) asm volatile("s_waitcnt vmcnt(" #n ")" ::: "memory")
; #define PG8_WAIT_L(n) asm volatile("s_waitcnt lgkmcnt(" #n ")" ::: "memory")
; #define PG8_BAR __builtin_amdgcn_s_barrier()
; #define PG8_SCHED __builtin_amdgcn_sched_barrier(0)
; template <class Epi, class Sched = StaticOrder>
; DI void gemm_phase(LAS unsigned char* lds, const Gemm g, const Sched& S, const Epi& E) {
;     ...
;       PG8_LDB(B0, 1, 0); PG8_SCHED; PG8_LDA(At, 1, 0); PG8_STAGE(PG8_SA(0, 1), a2 + hstep, voffA);
;       PG8_WAIT_L(8); PG8_BAR; PG8_WAIT_L(0); PG8_MMA(0, 0, At, B0); PG8_BAR; PG8_SCHED;
;       PG8_LDB(B1, 1, 1); PG8_STAGE(PG8_SB(1, 0), b3, voffB);
;       PG8_BAR; PG8_WAIT_L(0); PG8_MMA(0, 1, At, B1); PG8_BAR;
;       PG8_LDA(At, 1, 1); PG8_STAGE(PG8_SA(1, 0), a3, voffA);
;       PG8_BAR; PG8_WAIT_L(0); PG8_MMA(1, 0, At, B0); PG8_BAR; PG8_SCHED;
;       PG8_STAGE(PG8_SB(1, 1), b3 + hstep, voffB);
;       PG8_WAIT_V(6); PG8_BAR; PG8_MMA(1, 1, At, B1); PG8_BAR;
	s_setprio 0
	s_add_i32 s53, 0, 0x18000
	v_add_u32_e32 v76, s53, v198
	ds_read_b128 v[64:67], v76
	ds_read_b128 v[68:71], v76 offset:1024
	ds_read_b128 v[72:75], v76 offset:2048
	ds_read_b128 v[76:79], v76 offset:3072
	s_add_u32 s48, s48, 0x80000
	s_addc_u32 s49, s49, 0
	s_mov_b32 m0, s64
	ds_read_b128 v[120:123], v202 offset:32768
	ds_read_b128 v[128:131], v202 offset:33792
	ds_read_b128 v[180:183], v202 offset:34816
	ds_read_b128 v[184:187], v202 offset:35840
	ds_read_b128 v[188:191], v202 offset:36864
	ds_read_b128 v[192:195], v202 offset:37888
	ds_read_b128 v[206:209], v202 offset:38912
	ds_read_b128 v[212:215], v202 offset:39936
	global_load_lds_dwordx4 v166, s[48:49]
	s_mov_b32 m0, s65
	s_nop 0
	global_load_lds_dwordx4 v162, s[48:49]
	s_add_i32 s48, 0, 0x1c000
	v_add_u32_e32 v244, s48, v198
	ds_read_b128 v[216:219], v244
	ds_read_b128 v[220:223], v244 offset:1024
	ds_read_b128 v[224:227], v244 offset:2048
	ds_read_b128 v[228:231], v244 offset:3072
	s_waitcnt vmcnt(8)
	s_waitcnt lgkmcnt(4)
	s_setprio 1
	s_barrier
	v_mfma_f32_16x16x32_bf16 v[136:139], v[64:67], v[120:123], v[156:159]
	v_mfma_f32_16x16x32_bf16 v[156:159], v[68:71], v[128:131], v[136:139]
	v_mfma_f32_16x16x32_bf16 v[136:139], v[72:75], v[120:123], v[144:147]
	v_mfma_f32_16x16x32_bf16 v[144:147], v[76:79], v[128:131], v[136:139]
	v_mfma_f32_16x16x32_bf16 v[136:139], v[64:67], v[180:183], v[140:143]
	v_mfma_f32_16x16x32_bf16 v[132:135], v[72:75], v[180:183], v[132:135]
	v_mfma_f32_16x16x32_bf16 v[124:127], v[64:67], v[188:191], v[124:127]
	v_mfma_f32_16x16x32_bf16 v[116:119], v[72:75], v[188:191], v[116:119]
	v_mfma_f32_16x16x32_bf16 v[112:115], v[64:67], v[206:209], v[112:115]
	v_mfma_f32_16x16x32_bf16 v[108:111], v[72:75], v[206:209], v[108:111]
	v_mfma_f32_16x16x32_bf16 v[140:143], v[68:71], v[184:187], v[136:139]
	v_mfma_f32_16x16x32_bf16 v[132:135], v[76:79], v[184:187], v[132:135]
	v_mfma_f32_16x16x32_bf16 v[124:127], v[68:71], v[192:195], v[124:127]
	v_mfma_f32_16x16x32_bf16 v[116:119], v[76:79], v[192:195], v[116:119]
	v_mfma_f32_16x16x32_bf16 v[112:115], v[68:71], v[212:215], v[112:115]
	v_mfma_f32_16x16x32_bf16 v[108:111], v[76:79], v[212:215], v[108:111]
	s_waitcnt lgkmcnt(0)
	v_mfma_f32_16x16x32_bf16 v[80:83], v[224:227], v[120:123], v[80:83]
	v_mfma_f32_16x16x32_bf16 v[136:139], v[216:219], v[120:123], v[152:155]
	v_mfma_f32_16x16x32_bf16 v[148:151], v[228:231], v[128:131], v[80:83]
	v_mfma_f32_16x16x32_bf16 v[80:83], v[216:219], v[180:183], v[84:87]
	v_mfma_f32_16x16x32_bf16 v[152:155], v[220:223], v[128:131], v[136:139]
	v_mfma_f32_16x16x32_bf16 v[136:139], v[220:223], v[184:187], v[80:83]
	v_mfma_f32_16x16x32_bf16 v[80:83], v[224:227], v[180:183], v[92:95]
	v_mfma_f32_16x16x32_bf16 v[128:131], v[228:231], v[184:187], v[80:83]
	v_mfma_f32_16x16x32_bf16 v[80:83], v[216:219], v[188:191], v[96:99]
	v_mfma_f32_16x16x32_bf16 v[120:123], v[220:223], v[192:195], v[80:83]
	v_mfma_f32_16x16x32_bf16 v[80:83], v[224:227], v[188:191], v[104:107]
	v_mfma_f32_16x16x32_bf16 v[104:107], v[228:231], v[192:195], v[80:83]
	v_mfma_f32_16x16x32_bf16 v[80:83], v[216:219], v[206:209], v[100:103]
	v_mfma_f32_16x16x32_bf16 v[100:103], v[220:223], v[212:215], v[80:83]
	v_mfma_f32_16x16x32_bf16 v[80:83], v[224:227], v[206:209], v[88:91]
	v_mfma_f32_16x16x32_bf16 v[88:91], v[228:231], v[212:215], v[80:83]
	s_barrier
	s_setprio 0
	s_add_i32 s49, s53, s60
	s_mov_b32 m0, s49
	s_nop 0
	global_load_lds_dwordx4 v164, s[98:99]
	s_add_i32 m0, s49, 0x2000
	s_nop 0
	global_load_lds_dwordx4 v160, s[98:99]
	s_mov_b32 m0, s67
	s_nop 2
	ds_read_b128 v[80:83], v202 offset:49152
	ds_read_b128 v[84:87], v202 offset:50176
	ds_read_b128 v[92:95], v202 offset:51200
	ds_read_b128 v[96:99], v202 offset:52224
	ds_read_b128 v[180:183], v202 offset:53248
	ds_read_b128 v[184:187], v202 offset:54272
	ds_read_b128 v[188:191], v202 offset:55296
	ds_read_b128 v[192:195], v202 offset:56320
	global_load_lds_dwordx4 v166, s[100:101]
	s_mov_b32 m0, s68
	s_nop 0
	global_load_lds_dwordx4 v162, s[100:101]
	s_add_u32 s46, s46, 0x80080
	s_addc_u32 s47, s47, 0
	s_add_i32 s48, s48, s60
	s_mov_b32 m0, s48
	s_nop 0
	global_load_lds_dwordx4 v164, s[46:47]
	s_add_i32 m0, s48, 0x2000
	s_nop 0
	global_load_lds_dwordx4 v160, s[46:47]
	s_add_i32 s52, s52, 2
	s_add_u32 s14, s14, 0x100
	s_addc_u32 s15, s15, 0
	s_add_u32 s44, s44, 0x100
	s_addc_u32 s45, s45, 0
	s_cmp_gt_u32 s52, 29
	s_waitcnt vmcnt(8)
	s_waitcnt lgkmcnt(0)
	s_setprio 1
	s_barrier
	v_mfma_f32_16x16x32_bf16 v[60:63], v[64:67], v[80:83], v[60:63]
	v_mfma_f32_16x16x32_bf16 v[48:51], v[72:75], v[80:83], v[48:51]
	v_mfma_f32_16x16x32_bf16 v[44:47], v[64:67], v[92:95], v[44:47]
	v_mfma_f32_16x16x32_bf16 v[36:39], v[72:75], v[92:95], v[36:39]
	v_mfma_f32_16x16x32_bf16 v[28:31], v[64:67], v[180:183], v[28:31]
	v_mfma_f32_16x16x32_bf16 v[20:23], v[72:75], v[180:183], v[20:23]
	v_mfma_f32_16x16x32_bf16 v[16:19], v[64:67], v[188:191], v[16:19]
	v_mfma_f32_16x16x32_bf16 v[12:15], v[72:75], v[188:191], v[12:15]
	v_mfma_f32_16x16x32_bf16 v[60:63], v[68:71], v[84:87], v[60:63]
	v_mfma_f32_16x16x32_bf16 v[48:51], v[76:79], v[84:87], v[48:51]
	v_mfma_f32_16x16x32_bf16 v[44:47], v[68:71], v[96:99], v[44:47]
	v_mfma_f32_16x16x32_bf16 v[36:39], v[76:79], v[96:99], v[36:39]
	v_mfma_f32_16x16x32_bf16 v[28:31], v[68:71], v[184:187], v[28:31]
	v_mfma_f32_16x16x32_bf16 v[20:23], v[76:79], v[184:187], v[20:23]
	v_mfma_f32_16x16x32_bf16 v[16:19], v[68:71], v[192:195], v[16:19]
	v_mfma_f32_16x16x32_bf16 v[12:15], v[76:79], v[192:195], v[12:15]
	v_mfma_f32_16x16x32_bf16 v[56:59], v[216:219], v[80:83], v[56:59]
	v_mfma_f32_16x16x32_bf16 v[52:55], v[224:227], v[80:83], v[52:55]
	v_mfma_f32_16x16x32_bf16 v[40:43], v[216:219], v[92:95], v[40:43]
	v_mfma_f32_16x16x32_bf16 v[32:35], v[224:227], v[92:95], v[32:35]
	v_mfma_f32_16x16x32_bf16 v[24:27], v[216:219], v[180:183], v[24:27]
	v_mfma_f32_16x16x32_bf16 v[8:11], v[224:227], v[180:183], v[8:11]
	v_mfma_f32_16x16x32_bf16 v[4:7], v[216:219], v[188:191], v[4:7]
	v_mfma_f32_16x16x32_bf16 v[0:3], v[224:227], v[188:191], v[0:3]
	v_mfma_f32_16x16x32_bf16 v[56:59], v[220:223], v[84:87], v[56:59]
	v_mfma_f32_16x16x32_bf16 v[52:55], v[228:231], v[84:87], v[52:55]
	v_mfma_f32_16x16x32_bf16 v[40:43], v[220:223], v[96:99], v[40:43]
	v_mfma_f32_16x16x32_bf16 v[32:35], v[228:231], v[96:99], v[32:35]
	v_mfma_f32_16x16x32_bf16 v[24:27], v[220:223], v[184:187], v[24:27]
	v_mfma_f32_16x16x32_bf16 v[8:11], v[228:231], v[184:187], v[8:11]
	v_mfma_f32_16x16x32_bf16 v[4:7], v[220:223], v[192:195], v[4:7]
	v_mfma_f32_16x16x32_bf16 v[0:3], v[228:231], v[192:195], v[0:3]
	s_barrier
; DI float row_rstd(const float* ssq, int row, int fq) {
;   const f32x4 a = *(const f32x4*)(ssq + (size_t)row * 32 + fq * 8), b = *(const f32x4*)(ssq + (size_t)row * 32 + fq * 8 + 4);
;   float sm = ((a[0] + a[1]) + (a[2] + a[3])) + ((b[0] + b[1]) + (b[2] + b[3]));
;   sm += __shfl_xor(sm, 16); sm += __shfl_xor(sm, 32);
;   return rsqrtf(sm * (1.0f / 2048.f) + 1e-6f);
; }
;   DI void operator()(const f32x4 (&acc)[2][2][4][2], const Unit& u, int wr, int wc, int fr, int fq) const {
;     const int col = u.pn * 128 + wc * 32 + 8 * fq;
;     float w0[8], w1[8], w2[8], bb[8];
; #pragma unroll
;     for (int e = 0; e < 8; ++e) { w0[e] = cw[col + e]; w1[e] = cw[5632 + col + e]; w2[e] = cw[2 * 5632 + col + e]; bb[e] = cb[col + e]; }
; #pragma unroll
;     for (int ai = 0; ai < 2; ++ai) {
;       const int row0 = u.pm * BM + ai * HALF + wr * 64, span = row0 >> 6;
;       float rsv[4];
; #pragma unroll
;       for (int m = 0; m < 4; ++m) rsv[m] = row_rstd(ssq, row0 + 16 * m + fr, fq);
	s_setprio 0
	s_cbranch_scc0 .LBB0_811
	s_lshl_b32 s35, s12, 8
	s_add_i32 s35, s35, s66
	v_or_b32_e32 v190, s35, v179
	v_ashrrev_i32_e32 v191, 31, v190
	v_lshlrev_b64 v[64:65], 7, v[190:191]
	v_or_b32_e32 v188, 16, v190
	v_lshl_add_u64 v[64:65], v[168:169], 0, v[64:65]
	v_ashrrev_i32_e32 v189, 31, v188
	global_load_dwordx4 v[192:195], v[64:65], off
	global_load_dwordx4 v[206:209], v[64:65], off offset:16
	v_lshlrev_b64 v[64:65], 7, v[188:189]
	v_lshl_add_u64 v[64:65], v[168:169], 0, v[64:65]
	global_load_dwordx4 v[212:215], v[64:65], off
	global_load_dwordx4 v[216:219], v[64:65], off offset:16
	v_or_b32_e32 v186, 32, v190
	v_ashrrev_i32_e32 v187, 31, v186
	v_lshlrev_b64 v[64:65], 7, v[186:187]
	v_or_b32_e32 v184, 48, v190
	v_lshl_add_u64 v[64:65], v[168:169], 0, v[64:65]
	v_ashrrev_i32_e32 v185, 31, v184
	global_load_dwordx4 v[220:223], v[64:65], off
	global_load_dwordx4 v[224:227], v[64:65], off offset:16
	v_lshlrev_b64 v[64:65], 7, v[184:185]
	v_lshl_add_u64 v[64:65], v[168:169], 0, v[64:65]
	global_load_dwordx4 v[228:231], v[64:65], off
	global_load_dwordx4 v[232:235], v[64:65], off offset:16
	v_lshl_or_b32 v180, s13, 7, v200
	v_and_b32_e32 v65, 64, v204
	v_xor_b32_e32 v64, 16, v204
	v_ashrrev_i32_e32 v181, 31, v180
	v_add_u32_e32 v65, 64, v65
	v_readlane_b32 s44, v243, 3
	v_xor_b32_e32 v66, 32, v204
	v_lshlrev_b64 v[182:183], 2, v[180:181]
	v_cmp_lt_i32_e32 vcc, v64, v65
	v_readlane_b32 s52, v243, 11
	v_readlane_b32 s53, v243, 12
	v_cndmask_b32_e32 v64, v204, v64, vcc
	v_cmp_lt_i32_e32 vcc, v66, v65
	v_lshl_add_u64 v[92:93], s[52:53], 0, v[182:183]
	v_readlane_b32 s54, v243, 13
	v_cndmask_b32_e32 v65, v204, v66, vcc
	v_add_co_u32_e32 v94, vcc, 0x5000, v92
	v_readlane_b32 s55, v243, 14
	s_nop 0
	v_addc_co_u32_e32 v95, vcc, 0, v93, vcc
	v_add_co_u32_e32 v96, vcc, 0xb000, v92
	v_lshl_add_u64 v[72:73], s[54:55], 0, v[182:183]
	v_lshl_add_u64 v[74:75], v[92:93], 0, s[26:27]
	v_lshl_add_u64 v[76:77], v[92:93], 0, s[28:29]
	v_addc_co_u32_e32 v97, vcc, 0, v93, vcc
	v_lshlrev_b32_e32 v187, 2, v64
	v_lshlrev_b32_e32 v185, 2, v65
	global_load_dwordx4 v[64:67], v[92:93], off offset:16
	global_load_dwordx4 v[80:83], v[92:93], off
	global_load_dwordx4 v[68:71], v[72:73], off offset:16
	global_load_dwordx4 v[84:87], v[72:73], off
	s_nop 0
	global_load_dwordx4 v[72:75], v[74:75], off offset:16
	s_nop 0
	global_load_dwordx4 v[76:79], v[76:77], off offset:16
	s_nop 0
	global_load_dwordx4 v[92:95], v[94:95], off offset:2048
	s_nop 0
	global_load_dwordx4 v[96:99], v[96:97], off
	v_mov_b32_e32 v211, 0
	v_mov_b32_e32 v205, 0
	v_readlane_b32 s45, v243, 4
	v_readlane_b32 s46, v243, 5
	v_readlane_b32 s47, v243, 6
	v_readlane_b32 s48, v243, 7
	v_readlane_b32 s49, v243, 8
	v_readlane_b32 s50, v243, 9
	v_readlane_b32 s51, v243, 10
	v_readlane_b32 s56, v243, 15
	v_readlane_b32 s57, v243, 16
	v_readlane_b32 s58, v243, 17
	v_readlane_b32 s59, v243, 18
	s_waitcnt vmcnt(0)
	v_mov_b32_e32 v196, v192
	v_mov_b32_e32 v197, v206
	v_mov_b32_e32 v206, v193
	v_mov_b32_e32 v192, v194
	v_mov_b32_e32 v193, v208
	v_mov_b32_e32 v208, v195
	v_pk_add_f32 v[194:195], v[196:197], v[206:207]
	v_pk_add_f32 v[192:193], v[192:193], v[208:209]
	v_mov_b32_e32 v196, v212
	v_mov_b32_e32 v197, v216
	v_mov_b32_e32 v216, v213
	v_mov_b32_e32 v206, v214
	v_mov_b32_e32 v207, v218
	v_mov_b32_e32 v218, v215
	v_pk_add_f32 v[192:193], v[194:195], v[192:193]
	v_pk_add_f32 v[194:195], v[196:197], v[216:217]
	v_pk_add_f32 v[196:197], v[206:207], v[218:219]
	v_mov_b32_e32 v208, v220
	v_pk_add_f32 v[194:195], v[194:195], v[196:197]
	v_mov_b32_e32 v197, v192
	v_mov_b32_e32 v196, v194
	v_mov_b32_e32 v192, v195
	v_pk_add_f32 v[192:193], v[196:197], v[192:193]
	ds_bpermute_b32 v195, v187, v193
	ds_bpermute_b32 v194, v187, v192
	v_mov_b32_e32 v209, v224
	v_mov_b32_e32 v224, v221
	v_mov_b32_e32 v212, v222
	v_mov_b32_e32 v213, v226
	s_waitcnt lgkmcnt(0)
	v_pk_add_f32 v[192:193], v[192:193], v[194:195]
	ds_bpermute_b32 v195, v185, v193
	ds_bpermute_b32 v194, v185, v192
	v_mov_b32_e32 v226, v223
	v_mov_b32_e32 v196, v228
	v_mov_b32_e32 v197, v232
	v_mov_b32_e32 v232, v229
	s_waitcnt lgkmcnt(0)
; DI unsigned pack2(float lo, float hi) { f32x2 v = {lo, hi}; bf16v2 r = __builtin_convertvector(v, bf16v2); return __builtin_bit_cast(unsigned, r); }
; DI float silu_f(float x) { return x * sigmoid_f(x); }
; DI float dpp_ror1(float v) { return __int_as_float(__builtin_amdgcn_update_dpp(0, __float_as_int(v), 0x121, 0xf, 0xf, false)); }
; DI float dpp_ror2(float v) { return __int_as_float(__builtin_amdgcn_update_dpp(0, __float_as_int(v), 0x122, 0xf, 0xf, false)); }
; DI float row_rstd(const float* ssq, int row, int fq) {
;     ...
;   float sm = ((a[0] + a[1]) + (a[2] + a[3])) + ((b[0] + b[1]) + (b[2] + b[3]));
;   sm += __shfl_xor(sm, 16); sm += __shfl_xor(sm, 32);
;   return rsqrtf(sm * (1.0f / 2048.f) + 1e-6f);
;   DI void operator()(const f32x4 (&acc)[2][2][4][2], const Unit& u, int wr, int wc, int fr, int fq) const {
;     ...
;       for (int m = 0; m < 4; ++m) {
;         float g[8], uu[8], a[8];
;         const float rs = rsv[m];
; #pragma unroll
;         for (int e = 0; e < 4; ++e) { g[e] = acc[ai][0][m][0][e] * rs; g[4 + e] = acc[ai][0][m][1][e] * rs; uu[e] = acc[ai][1][m][0][e] * rs; uu[4 + e] = acc[ai][1][m][1][e] * rs; }
; #pragma unroll
;         for (int e = 0; e < 8; ++e) {
;           const float x1 = dpp_ror1(g[e]), x2 = dpp_ror2(g[e]);
;           const float pr1 = (fr == 0) ? p1[e] : x1, pr2 = (fr < 2) ? p2[e] : x2;
;           a[e] = w2[e] * g[e] + w1[e] * pr1 + w0[e] * pr2 + bb[e];
;           p1[e] = x1; p2[e] = x2;
;         }
;         if (m == 0 && fr < 2) {
;           float* ha = headA + (size_t)(span * 2 + fr) * 5632 + col; float* hu = headU + (size_t)(span * 2 + fr) * 5632 + col;
;           *(f32x4*)ha = (f32x4){a[0], a[1], a[2], a[3]}; *(f32x4*)(ha + 4) = (f32x4){a[4], a[5], a[6], a[7]};
;           *(f32x4*)hu = (f32x4){uu[0], uu[1], uu[2], uu[3]}; *(f32x4*)(hu + 4) = (f32x4){uu[4], uu[5], uu[6], uu[7]};
;         } else {
;           u32x4 w;
;           w.x = pack2(silu_f(a[0]) * uu[0], silu_f(a[1]) * uu[1]);
;           w.y = pack2(silu_f(a[2]) * uu[2], silu_f(a[3]) * uu[3]);
;           w.z = pack2(silu_f(a[4]) * uu[4], silu_f(a[5]) * uu[5]);
;           w.w = pack2(silu_f(a[6]) * uu[6], silu_f(a[7]) * uu[7]);
;           *(u32x4*)(H + (size_t)(row0 + 16 * m + fr) * 5632 + col) = w;
	v_pk_add_f32 v[192:193], v[192:193], v[194:195]
	v_mov_b32_e32 v206, v230
	v_pk_fma_f32 v[192:193], v[192:193], s[30:31], v[178:179] op_sel_hi:[1,0,0]
	v_mov_b32_e32 v207, v234
	v_mul_f32_e32 v189, 0x4b800000, v193
	v_cmp_gt_f32_e64 s[12:13], s74, v193
	v_mov_b32_e32 v234, v231
	v_pk_add_f32 v[208:209], v[208:209], v[224:225]
	v_cndmask_b32_e64 v189, v193, v189, s[12:13]
	v_rsq_f32_e32 v189, v189
	v_pk_add_f32 v[212:213], v[212:213], v[226:227]
	v_pk_add_f32 v[196:197], v[196:197], v[232:233]
	v_pk_add_f32 v[194:195], v[206:207], v[234:235]
	v_mul_f32_e32 v191, 0x45800000, v189
	v_cndmask_b32_e64 v220, v189, v191, s[12:13]
	v_pk_add_f32 v[208:209], v[208:209], v[212:213]
	v_pk_add_f32 v[194:195], v[196:197], v[194:195]
	v_pk_mul_f32 v[156:157], v[156:157], v[220:221] op_sel_hi:[1,0]
	v_mov_b32_e32 v216, 0
	v_mov_b32_e32 v218, 0
	v_mov_b32_e32 v196, v194
	v_mov_b32_e32 v197, v208
	v_mov_b32_e32 v208, v195
	v_mov_b32_dpp v216, v156 row_ror:1 row_mask:0xf bank_mask:0xf
	v_mov_b32_dpp v218, v157 row_ror:1 row_mask:0xf bank_mask:0xf
	v_pk_add_f32 v[194:195], v[196:197], v[208:209]
	v_cndmask_b32_e64 v207, v218, 0, s[0:1]
	v_cndmask_b32_e64 v206, v216, 0, s[0:1]
	v_pk_mul_f32 v[158:159], v[158:159], v[220:221] op_sel_hi:[1,0]
	v_mov_b32_e32 v212, 0
	v_mov_b32_e32 v214, 0
	ds_bpermute_b32 v197, v187, v195
	ds_bpermute_b32 v196, v187, v194
	v_mov_b32_e32 v215, 0
	v_mov_b32_e32 v217, 0
	v_pk_mul_f32 v[206:207], v[92:93], v[206:207]
	v_mov_b32_dpp v212, v158 row_ror:1 row_mask:0xf bank_mask:0xf
	v_mov_b32_dpp v214, v159 row_ror:1 row_mask:0xf bank_mask:0xf
	v_mov_b32_dpp v215, v156 row_ror:2 row_mask:0xf bank_mask:0xf
	v_mov_b32_dpp v217, v157 row_ror:2 row_mask:0xf bank_mask:0xf
	v_pk_fma_f32 v[156:157], v[96:97], v[156:157], v[206:207]
	v_mov_b32_e32 v213, 0
	v_cndmask_b32_e64 v207, v214, 0, s[0:1]
	v_cndmask_b32_e64 v206, v212, 0, s[0:1]
	v_cndmask_b32_e64 v209, v217, 0, s[4:5]
	v_cndmask_b32_e64 v208, v215, 0, s[4:5]
	v_mov_b32_dpp v211, v158 row_ror:2 row_mask:0xf bank_mask:0xf
	v_mov_b32_dpp v213, v159 row_ror:2 row_mask:0xf bank_mask:0xf
	v_pk_mul_f32 v[206:207], v[94:95], v[206:207]
	v_pk_fma_f32 v[156:157], v[80:81], v[208:209], v[156:157]
	v_cndmask_b32_e64 v209, v213, 0, s[4:5]
	v_cndmask_b32_e64 v208, v211, 0, s[4:5]
	v_pk_fma_f32 v[158:159], v[98:99], v[158:159], v[206:207]
	v_pk_mul_f32 v[144:145], v[144:145], v[220:221] op_sel_hi:[1,0]
	v_pk_fma_f32 v[158:159], v[82:83], v[208:209], v[158:159]
	v_mov_b32_e32 v207, 0
	v_mov_b32_e32 v209, 0
	v_pk_mul_f32 v[146:147], v[146:147], v[220:221] op_sel_hi:[1,0]
	v_mov_b32_e32 v191, 0
	s_waitcnt lgkmcnt(0)
	v_pk_add_f32 v[194:195], v[194:195], v[196:197]
	v_mov_b32_dpp v207, v144 row_ror:1 row_mask:0xf bank_mask:0xf
	v_mov_b32_dpp v209, v145 row_ror:1 row_mask:0xf bank_mask:0xf
	v_mov_b32_dpp v191, v146 row_ror:1 row_mask:0xf bank_mask:0xf
	v_mov_b32_dpp v205, v147 row_ror:1 row_mask:0xf bank_mask:0xf
	ds_bpermute_b32 v197, v185, v195
	ds_bpermute_b32 v196, v185, v194
	v_pk_mul_f32 v[152:153], v[152:153], v[220:221] op_sel_hi:[1,0]
	v_pk_mul_f32 v[148:149], v[148:149], v[220:221] op_sel_hi:[1,0]
	v_pk_mul_f32 v[154:155], v[154:155], v[220:221] op_sel_hi:[1,0]
	v_pk_mul_f32 v[150:151], v[150:151], v[220:221] op_sel_hi:[1,0]
	v_mov_b32_e32 v206, 0
	v_mov_b32_e32 v208, 0
	v_cndmask_b32_e64 v223, v209, 0, s[0:1]
	v_cndmask_b32_e64 v222, v207, 0, s[0:1]
	v_mov_b32_e32 v189, 0
	v_mov_b32_e32 v193, 0
	v_cndmask_b32_e64 v221, v205, 0, s[0:1]
	v_cndmask_b32_e64 v220, v191, 0, s[0:1]
	v_mov_b32_dpp v206, v144 row_ror:2 row_mask:0xf bank_mask:0xf
	v_mov_b32_dpp v208, v145 row_ror:2 row_mask:0xf bank_mask:0xf
	v_pk_mul_f32 v[222:223], v[72:73], v[222:223]
	v_mov_b32_dpp v189, v146 row_ror:2 row_mask:0xf bank_mask:0xf
	v_mov_b32_dpp v193, v147 row_ror:2 row_mask:0xf bank_mask:0xf
	v_pk_mul_f32 v[220:221], v[74:75], v[220:221]
	v_cndmask_b32_e64 v225, v208, 0, s[4:5]
	v_cndmask_b32_e64 v224, v206, 0, s[4:5]
	v_pk_fma_f32 v[144:145], v[76:77], v[144:145], v[222:223]
	v_cndmask_b32_e64 v223, v193, 0, s[4:5]
	v_cndmask_b32_e64 v222, v189, 0, s[4:5]
	v_pk_fma_f32 v[146:147], v[78:79], v[146:147], v[220:221]
	v_pk_fma_f32 v[144:145], v[64:65], v[224:225], v[144:145]
	v_pk_fma_f32 v[146:147], v[66:67], v[222:223], v[146:147]
	v_cmp_gt_f32_e32 vcc, s74, v192
	v_pk_add_f32 v[156:157], v[84:85], v[156:157]
	v_pk_add_f32 v[158:159], v[86:87], v[158:159]
	v_pk_add_f32 v[144:145], v[68:69], v[144:145]
	v_pk_add_f32 v[146:147], v[70:71], v[146:147]
	s_and_saveexec_b64 s[12:13], s[10:11]
	s_xor_b64 s[12:13], exec, s[12:13]
	s_cbranch_execz .LBB0_814
	v_mul_f32_e32 v219, 0xbfb8aa3b, v156
	v_exp_f32_e32 v219, v219
	v_mul_f32_e32 v220, 0xbfb8aa3b, v157
	v_exp_f32_e32 v220, v220
	v_mul_f32_e32 v222, 0xbfb8aa3b, v159
	v_add_f32_e32 v219, 1.0, v219
	v_exp_f32_e32 v223, v222
	v_add_f32_e32 v221, 1.0, v220
	v_rcp_f32_e32 v220, v219
	v_mul_f32_e32 v219, 0xbfb8aa3b, v158
	v_exp_f32_e32 v219, v219
	v_rcp_f32_e32 v221, v221
	v_add_f32_e32 v219, 1.0, v219
	v_rcp_f32_e32 v222, v219
	v_add_f32_e32 v219, 1.0, v223
	v_rcp_f32_e32 v223, v219
	v_pk_mul_f32 v[156:157], v[156:157], v[220:221]
	s_nop 0
	v_pk_mul_f32 v[152:153], v[152:153], v[156:157]
	v_pk_mul_f32 v[156:157], v[158:159], v[222:223]
	v_cvt_pk_bf16_f32 v152, v152, v153
	v_mul_f32_e32 v153, 0xbfb8aa3b, v144
	v_pk_mul_f32 v[154:155], v[154:155], v[156:157]
	v_exp_f32_e32 v156, v153
	v_mul_f32_e32 v153, 0xbfb8aa3b, v145
	v_exp_f32_e32 v157, v153
	v_cvt_pk_bf16_f32 v153, v154, v155
	v_add_f32_e32 v154, 1.0, v156
	v_mul_f32_e32 v156, 0xbfb8aa3b, v146
	v_add_f32_e32 v155, 1.0, v157
	v_mul_f32_e32 v157, 0xbfb8aa3b, v147
	v_exp_f32_e32 v156, v156
	v_exp_f32_e32 v157, v157
	v_rcp_f32_e32 v154, v154
	v_rcp_f32_e32 v155, v155
	v_add_f32_e32 v156, 1.0, v156
	v_add_f32_e32 v157, 1.0, v157
	v_rcp_f32_e32 v156, v156
	v_rcp_f32_e32 v157, v157
	v_pk_mul_f32 v[144:145], v[144:145], v[154:155]
	s_nop 0
	v_pk_mul_f32 v[144:145], v[148:149], v[144:145]
	s_nop 0
	v_cvt_pk_bf16_f32 v154, v144, v145
	v_pk_mul_f32 v[144:145], v[146:147], v[156:157]
	s_nop 0
	v_pk_mul_f32 v[144:145], v[150:151], v[144:145]
	s_nop 0
	v_cvt_pk_bf16_f32 v155, v144, v145
	v_mov_b64_e32 v[144:145], s[16:17]
	v_mad_i64_i32 v[144:145], s[14:15], v190, s75, v[144:145]
	v_lshl_add_u64 v[144:145], v[180:181], 1, v[144:145]
	global_store_dwordx4 v[144:145], v[152:155], off

; #define PG8_STAGE(bufoff, gbase, voff) do { _Pragma("unroll") for (int _i = 0; _i < 2; ++_i) \
;     __builtin_amdgcn_global_load_lds((const unsigned*)((const char*)(gbase) + (voff)[_i]), (LAS unsigned*)(lds + (bufoff) + ldsw + _i * 8192), 16, 0, 0); } while (0)
; #define PG8_LDA(dst, b, h) do { _Pragma("unroll") for (int m = 0; m < 4; ++m) _Pragma("unroll") for (int k = 0; k < 2; ++k) dst[m][k] = *(const LAS bf16x8*)(lds + PG8_SA(b, h) + aoff + m * 2048 + k * 1024); } while (0)
; #define PG8_LDB(dst, b, h) do { _Pragma("unroll") for (int n = 0; n < 2; ++n) _Pragma("unroll") for (int k = 0; k < 2; ++k) dst[n][k] = *(const LAS bf16x8*)(lds + PG8_SB(b, h) + boff + n * 2048 + k * 1024); } while (0)
; #define PG8_MMA(ai, bj, At, Bt) do { __builtin_amdgcn_s_setprio(1); _Pragma("unroll") for (int m = 0; m < 4; ++m) _Pragma("unroll") for (int n = 0; n < 2; ++n) _Pragma("unroll") for (int k = 0; k < 2; ++k) \
;     acc[ai][bj][m][n] = __builtin_amdgcn_mfma_f32_16x16x32_bf16(Bt[n][k], At[m][k], acc[ai][bj][m][n], 0, 0, 0); __builtin_amdgcn_s_setprio(0); } while (0)
; #define PG8_WAIT_V(n) asm volatile("s_waitcnt vmcnt(" #n ")" ::: "memory")
; #define PG8_WAIT_L(n) asm volatile("s_waitcnt lgkmcnt(" #n ")" ::: "memory")
; #define PG8_BAR __builtin_amdgcn_s_barrier()
; #define PG8_SCHED __builtin_amdgcn_sched_barrier(0)
; template <class Epi, class Sched = StaticOrder>
; DI void gemm_phase(LAS unsigned char* lds, const Gemm g, const Sched& S, const Epi& E) {
;     ...
;     for (int t = 0; t < nt; t += 2) {
;       const bool last = (t == nt - 2);
;       const char* a1 = cA + (size_t)(t + 1) * kstep;
;       const char* a2 = last ? nA : cA + (size_t)(t + 2) * kstep; const char* b2 = last ? nB : cB + (size_t)(t + 2) * kstep;
;       const char* a3 = a2 + kstep; const char* b3 = b2 + kstep;
;       PG8_LDB(B0, 0, 0); PG8_SCHED; PG8_LDA(At, 0, 0); PG8_STAGE(PG8_SA(1, 1), a1 + hstep, voffA);
;       PG8_WAIT_L(8); PG8_BAR; PG8_WAIT_L(0); PG8_MMA(0, 0, At, B0); PG8_BAR; PG8_SCHED;
;       PG8_LDB(B1, 0, 1); PG8_STAGE(PG8_SB(0, 0), b2, voffB);
;       PG8_BAR; PG8_WAIT_L(0); PG8_MMA(0, 1, At, B1); PG8_BAR;
;       PG8_LDA(At, 0, 1); PG8_STAGE(PG8_SA(0, 0), a2, voffA);
;       PG8_BAR; PG8_WAIT_L(0); PG8_MMA(1, 0, At, B0); PG8_BAR; PG8_SCHED;
;       PG8_STAGE(PG8_SB(0, 1), b2 + hstep, voffB);
;       PG8_WAIT_V(6); PG8_BAR; PG8_MMA(1, 1, At, B1); PG8_BAR;
.LBB0_961:
	ds_read_b128 v[128:131], v214
	ds_read_b128 v[132:135], v214 offset:1024
	ds_read_b128 v[136:139], v214 offset:2048
	ds_read_b128 v[140:143], v214 offset:3072
	s_add_u32 s20, s18, 0xffea0080
	s_addc_u32 s21, s19, -1
	s_cmpk_eq_i32 s44, 0x54
	s_cselect_b32 s23, s5, s21
	s_cselect_b32 s22, s4, s20
	s_cselect_b32 s21, s7, s43
	s_cselect_b32 s20, s6, s42
	s_add_i32 m0, s31, 0xc000
	ds_read_b128 v[144:147], v215
	ds_read_b128 v[148:151], v215 offset:1024
	ds_read_b128 v[152:155], v215 offset:2048
	ds_read_b128 v[156:159], v215 offset:3072
	ds_read_b128 v[160:163], v215 offset:4096
	ds_read_b128 v[164:167], v215 offset:5120
	ds_read_b128 v[168:171], v215 offset:6144
	ds_read_b128 v[172:175], v215 offset:7168
	global_load_lds_dwordx4 v184, s[18:19]
	s_add_i32 m0, s31, 0xe000
	s_nop 0
	global_load_lds_dwordx4 v186, s[18:19]
	ds_read_b128 v[192:195], v216
	ds_read_b128 v[196:199], v216 offset:1024
	ds_read_b128 v[200:203], v216 offset:2048
	ds_read_b128 v[204:207], v216 offset:3072
	s_waitcnt vmcnt(8)
	s_waitcnt lgkmcnt(4)
	s_setprio 1
	s_barrier
	v_mfma_f32_16x16x32_bf16 v[124:127], v[128:131], v[144:147], v[124:127]
	v_mfma_f32_16x16x32_bf16 v[120:123], v[136:139], v[144:147], v[120:123]
	v_mfma_f32_16x16x32_bf16 v[108:111], v[128:131], v[152:155], v[108:111]
	v_mfma_f32_16x16x32_bf16 v[104:107], v[136:139], v[152:155], v[104:107]
	v_mfma_f32_16x16x32_bf16 v[92:95], v[128:131], v[160:163], v[92:95]
	v_mfma_f32_16x16x32_bf16 v[88:91], v[136:139], v[160:163], v[88:91]
	v_mfma_f32_16x16x32_bf16 v[76:79], v[128:131], v[168:171], v[76:79]
	v_mfma_f32_16x16x32_bf16 v[72:75], v[136:139], v[168:171], v[72:75]
	v_mfma_f32_16x16x32_bf16 v[124:127], v[132:135], v[148:151], v[124:127]
	v_mfma_f32_16x16x32_bf16 v[120:123], v[140:143], v[148:151], v[120:123]
	v_mfma_f32_16x16x32_bf16 v[108:111], v[132:135], v[156:159], v[108:111]
	v_mfma_f32_16x16x32_bf16 v[104:107], v[140:143], v[156:159], v[104:107]
	v_mfma_f32_16x16x32_bf16 v[92:95], v[132:135], v[164:167], v[92:95]
	v_mfma_f32_16x16x32_bf16 v[88:91], v[140:143], v[164:167], v[88:91]
	v_mfma_f32_16x16x32_bf16 v[76:79], v[132:135], v[172:175], v[76:79]
	v_mfma_f32_16x16x32_bf16 v[72:75], v[140:143], v[172:175], v[72:75]
	s_waitcnt lgkmcnt(0)
	v_mfma_f32_16x16x32_bf16 v[116:119], v[192:195], v[144:147], v[116:119]
	v_mfma_f32_16x16x32_bf16 v[112:115], v[200:203], v[144:147], v[112:115]
	v_mfma_f32_16x16x32_bf16 v[100:103], v[192:195], v[152:155], v[100:103]
	v_mfma_f32_16x16x32_bf16 v[96:99], v[200:203], v[152:155], v[96:99]
	v_mfma_f32_16x16x32_bf16 v[84:87], v[192:195], v[160:163], v[84:87]
	v_mfma_f32_16x16x32_bf16 v[80:83], v[200:203], v[160:163], v[80:83]
	v_mfma_f32_16x16x32_bf16 v[68:71], v[192:195], v[168:171], v[68:71]
	v_mfma_f32_16x16x32_bf16 v[64:67], v[200:203], v[168:171], v[64:67]
	v_mfma_f32_16x16x32_bf16 v[116:119], v[196:199], v[148:151], v[116:119]
	v_mfma_f32_16x16x32_bf16 v[112:115], v[204:207], v[148:151], v[112:115]
	v_mfma_f32_16x16x32_bf16 v[100:103], v[196:199], v[156:159], v[100:103]
	v_mfma_f32_16x16x32_bf16 v[96:99], v[204:207], v[156:159], v[96:99]
	v_mfma_f32_16x16x32_bf16 v[84:87], v[196:199], v[164:167], v[84:87]
	v_mfma_f32_16x16x32_bf16 v[80:83], v[204:207], v[164:167], v[80:83]
	v_mfma_f32_16x16x32_bf16 v[68:71], v[196:199], v[172:175], v[68:71]
	v_mfma_f32_16x16x32_bf16 v[64:67], v[204:207], v[172:175], v[64:67]
	s_barrier
	s_setprio 0
	s_add_i32 s45, s46, s30
	s_add_u32 s98, s20, 0x80
	s_addc_u32 s99, s21, 0
	s_add_u32 s100, s22, 0x80
	s_addc_u32 s101, s23, 0
	s_mov_b32 m0, s45
	s_nop 0
	global_load_lds_dwordx4 v178, s[20:21]
	s_add_i32 m0, s45, 0x2000
	s_nop 0
	global_load_lds_dwordx4 v182, s[20:21]
	s_mov_b32 m0, s31
	ds_read_b128 v[144:147], v215 offset:16384
	ds_read_b128 v[148:151], v215 offset:17408
	ds_read_b128 v[152:155], v215 offset:18432
	ds_read_b128 v[156:159], v215 offset:19456
	ds_read_b128 v[160:163], v215 offset:20480
	ds_read_b128 v[164:167], v215 offset:21504
	ds_read_b128 v[168:171], v215 offset:22528
	ds_read_b128 v[172:175], v215 offset:23552
	global_load_lds_dwordx4 v176, s[22:23]
	s_mov_b32 m0, s33
	s_nop 0
	global_load_lds_dwordx4 v180, s[22:23]
	s_add_u32 s52, s20, 0x160000
	s_addc_u32 s53, s21, 0
	s_add_i32 s45, s47, s30
	s_mov_b32 m0, s45
	s_nop 0
	global_load_lds_dwordx4 v178, s[52:53]
	s_add_i32 m0, s45, 0x2000
	s_nop 0
	global_load_lds_dwordx4 v182, s[52:53]
	s_waitcnt vmcnt(8)
	s_waitcnt lgkmcnt(0)
	s_setprio 1
	s_barrier
	v_mfma_f32_16x16x32_bf16 v[60:63], v[128:131], v[144:147], v[60:63]
	v_mfma_f32_16x16x32_bf16 v[56:59], v[136:139], v[144:147], v[56:59]
	v_mfma_f32_16x16x32_bf16 v[44:47], v[128:131], v[152:155], v[44:47]
	v_mfma_f32_16x16x32_bf16 v[40:43], v[136:139], v[152:155], v[40:43]
	v_mfma_f32_16x16x32_bf16 v[28:31], v[128:131], v[160:163], v[28:31]
	v_mfma_f32_16x16x32_bf16 v[24:27], v[136:139], v[160:163], v[24:27]
	v_mfma_f32_16x16x32_bf16 v[12:15], v[128:131], v[168:171], v[12:15]
	v_mfma_f32_16x16x32_bf16 v[8:11], v[136:139], v[168:171], v[8:11]
	v_mfma_f32_16x16x32_bf16 v[60:63], v[132:135], v[148:151], v[60:63]
	v_mfma_f32_16x16x32_bf16 v[56:59], v[140:143], v[148:151], v[56:59]
	v_mfma_f32_16x16x32_bf16 v[44:47], v[132:135], v[156:159], v[44:47]
	v_mfma_f32_16x16x32_bf16 v[40:43], v[140:143], v[156:159], v[40:43]
	v_mfma_f32_16x16x32_bf16 v[28:31], v[132:135], v[164:167], v[28:31]
	v_mfma_f32_16x16x32_bf16 v[24:27], v[140:143], v[164:167], v[24:27]
	v_mfma_f32_16x16x32_bf16 v[12:15], v[132:135], v[172:175], v[12:15]
	v_mfma_f32_16x16x32_bf16 v[8:11], v[140:143], v[172:175], v[8:11]
	v_mfma_f32_16x16x32_bf16 v[52:55], v[192:195], v[144:147], v[52:55]
	v_mfma_f32_16x16x32_bf16 v[48:51], v[200:203], v[144:147], v[48:51]
	v_mfma_f32_16x16x32_bf16 v[36:39], v[192:195], v[152:155], v[36:39]
	v_mfma_f32_16x16x32_bf16 v[32:35], v[200:203], v[152:155], v[32:35]
	v_mfma_f32_16x16x32_bf16 v[20:23], v[192:195], v[160:163], v[20:23]
	v_mfma_f32_16x16x32_bf16 v[16:19], v[200:203], v[160:163], v[16:19]
	v_mfma_f32_16x16x32_bf16 v[4:7], v[192:195], v[168:171], v[4:7]
	v_mfma_f32_16x16x32_bf16 v[0:3], v[200:203], v[168:171], v[0:3]
	v_mfma_f32_16x16x32_bf16 v[52:55], v[196:199], v[148:151], v[52:55]
	v_mfma_f32_16x16x32_bf16 v[48:51], v[204:207], v[148:151], v[48:51]
	v_mfma_f32_16x16x32_bf16 v[36:39], v[196:199], v[156:159], v[36:39]
	v_mfma_f32_16x16x32_bf16 v[32:35], v[204:207], v[156:159], v[32:35]
	v_mfma_f32_16x16x32_bf16 v[20:23], v[196:199], v[164:167], v[20:23]
	v_mfma_f32_16x16x32_bf16 v[16:19], v[204:207], v[164:167], v[16:19]
	v_mfma_f32_16x16x32_bf16 v[4:7], v[196:199], v[172:175], v[4:7]
	v_mfma_f32_16x16x32_bf16 v[0:3], v[204:207], v[172:175], v[0:3]
	s_barrier
; #define PG8_STAGE(bufoff, gbase, voff) do { _Pragma("unroll") for (int _i = 0; _i < 2; ++_i) \
;     __builtin_amdgcn_global_load_lds((const unsigned*)((const char*)(gbase) + (voff)[_i]), (LAS unsigned*)(lds + (bufoff) + ldsw + _i * 8192), 16, 0, 0); } while (0)
; #define PG8_LDA(dst, b, h) do { _Pragma("unroll") for (int m = 0; m < 4; ++m) _Pragma("unroll") for (int k = 0; k < 2; ++k) dst[m][k] = *(const LAS bf16x8*)(lds + PG8_SA(b, h) + aoff + m * 2048 + k * 1024); } while (0)
; #define PG8_LDB(dst, b, h) do { _Pragma("unroll") for (int n = 0; n < 2; ++n) _Pragma("unroll") for (int k = 0; k < 2; ++k) dst[n][k] = *(const LAS bf16x8*)(lds + PG8_SB(b, h) + boff + n * 2048 + k * 1024); } while (0)
; #define PG8_MMA(ai, bj, At, Bt) do { __builtin_amdgcn_s_setprio(1); _Pragma("unroll") for (int m = 0; m < 4; ++m) _Pragma("unroll") for (int n = 0; n < 2; ++n) _Pragma("unroll") for (int k = 0; k < 2; ++k) \
;     acc[ai][bj][m][n] = __builtin_amdgcn_mfma_f32_16x16x32_bf16(Bt[n][k], At[m][k], acc[ai][bj][m][n], 0, 0, 0); __builtin_amdgcn_s_setprio(0); } while (0)
; #define PG8_WAIT_V(n) asm volatile("s_waitcnt vmcnt(" #n ")" ::: "memory")
; #define PG8_WAIT_L(n) asm volatile("s_waitcnt lgkmcnt(" #n ")" ::: "memory")
; #define PG8_BAR __builtin_amdgcn_s_barrier()
; #define PG8_SCHED __builtin_amdgcn_sched_barrier(0)
; template <class Epi, class Sched = StaticOrder>
; DI void gemm_phase(LAS unsigned char* lds, const Gemm g, const Sched& S, const Epi& E) {
;     ...
;       PG8_LDB(B0, 1, 0); PG8_SCHED; PG8_LDA(At, 1, 0); PG8_STAGE(PG8_SA(0, 1), a2 + hstep, voffA);
;       PG8_WAIT_L(8); PG8_BAR; PG8_WAIT_L(0); PG8_MMA(0, 0, At, B0); PG8_BAR; PG8_SCHED;
;       PG8_LDB(B1, 1, 1); PG8_STAGE(PG8_SB(1, 0), b3, voffB);
;       PG8_BAR; PG8_WAIT_L(0); PG8_MMA(0, 1, At, B1); PG8_BAR;
;       PG8_LDA(At, 1, 1); PG8_STAGE(PG8_SA(1, 0), a3, voffA);
;       PG8_BAR; PG8_WAIT_L(0); PG8_MMA(1, 0, At, B0); PG8_BAR; PG8_SCHED;
;       PG8_STAGE(PG8_SB(1, 1), b3 + hstep, voffB);
;       PG8_WAIT_V(6); PG8_BAR; PG8_MMA(1, 1, At, B1); PG8_BAR;
	s_setprio 0
	s_add_i32 s45, 0, 0x18000
	v_add_u32_e32 v140, s45, v212
	ds_read_b128 v[128:131], v140
	ds_read_b128 v[132:135], v140 offset:1024
	ds_read_b128 v[136:139], v140 offset:2048
	ds_read_b128 v[140:143], v140 offset:3072
	s_add_u32 s22, s22, 0x160000
	s_addc_u32 s23, s23, 0
	s_mov_b32 m0, s34
	ds_read_b128 v[144:147], v215 offset:32768
	ds_read_b128 v[148:151], v215 offset:33792
	ds_read_b128 v[152:155], v215 offset:34816
	ds_read_b128 v[156:159], v215 offset:35840
	ds_read_b128 v[160:163], v215 offset:36864
	ds_read_b128 v[164:167], v215 offset:37888
	ds_read_b128 v[168:171], v215 offset:38912
	ds_read_b128 v[172:175], v215 offset:39936
	global_load_lds_dwordx4 v176, s[22:23]
	s_mov_b32 m0, s35
	s_nop 0
	global_load_lds_dwordx4 v180, s[22:23]
	s_add_i32 s22, 0, 0x1c000
	v_add_u32_e32 v204, s22, v212
	ds_read_b128 v[192:195], v204
	ds_read_b128 v[196:199], v204 offset:1024
	ds_read_b128 v[200:203], v204 offset:2048
	ds_read_b128 v[204:207], v204 offset:3072
	s_waitcnt vmcnt(8)
	s_waitcnt lgkmcnt(4)
	s_setprio 1
	s_barrier
	v_mfma_f32_16x16x32_bf16 v[124:127], v[128:131], v[144:147], v[124:127]
	v_mfma_f32_16x16x32_bf16 v[120:123], v[136:139], v[144:147], v[120:123]
	v_mfma_f32_16x16x32_bf16 v[108:111], v[128:131], v[152:155], v[108:111]
	v_mfma_f32_16x16x32_bf16 v[104:107], v[136:139], v[152:155], v[104:107]
	v_mfma_f32_16x16x32_bf16 v[92:95], v[128:131], v[160:163], v[92:95]
	v_mfma_f32_16x16x32_bf16 v[88:91], v[136:139], v[160:163], v[88:91]
	v_mfma_f32_16x16x32_bf16 v[76:79], v[128:131], v[168:171], v[76:79]
	v_mfma_f32_16x16x32_bf16 v[72:75], v[136:139], v[168:171], v[72:75]
	v_mfma_f32_16x16x32_bf16 v[124:127], v[132:135], v[148:151], v[124:127]
	v_mfma_f32_16x16x32_bf16 v[120:123], v[140:143], v[148:151], v[120:123]
	v_mfma_f32_16x16x32_bf16 v[108:111], v[132:135], v[156:159], v[108:111]
	v_mfma_f32_16x16x32_bf16 v[104:107], v[140:143], v[156:159], v[104:107]
	v_mfma_f32_16x16x32_bf16 v[92:95], v[132:135], v[164:167], v[92:95]
	v_mfma_f32_16x16x32_bf16 v[88:91], v[140:143], v[164:167], v[88:91]
	v_mfma_f32_16x16x32_bf16 v[76:79], v[132:135], v[172:175], v[76:79]
	v_mfma_f32_16x16x32_bf16 v[72:75], v[140:143], v[172:175], v[72:75]
	s_waitcnt lgkmcnt(0)
	v_mfma_f32_16x16x32_bf16 v[116:119], v[192:195], v[144:147], v[116:119]
	v_mfma_f32_16x16x32_bf16 v[112:115], v[200:203], v[144:147], v[112:115]
	v_mfma_f32_16x16x32_bf16 v[100:103], v[192:195], v[152:155], v[100:103]
	v_mfma_f32_16x16x32_bf16 v[96:99], v[200:203], v[152:155], v[96:99]
	v_mfma_f32_16x16x32_bf16 v[84:87], v[192:195], v[160:163], v[84:87]
	v_mfma_f32_16x16x32_bf16 v[80:83], v[200:203], v[160:163], v[80:83]
	v_mfma_f32_16x16x32_bf16 v[68:71], v[192:195], v[168:171], v[68:71]
	v_mfma_f32_16x16x32_bf16 v[64:67], v[200:203], v[168:171], v[64:67]
	v_mfma_f32_16x16x32_bf16 v[116:119], v[196:199], v[148:151], v[116:119]
	v_mfma_f32_16x16x32_bf16 v[112:115], v[204:207], v[148:151], v[112:115]
	v_mfma_f32_16x16x32_bf16 v[100:103], v[196:199], v[156:159], v[100:103]
	v_mfma_f32_16x16x32_bf16 v[96:99], v[204:207], v[156:159], v[96:99]
	v_mfma_f32_16x16x32_bf16 v[84:87], v[196:199], v[164:167], v[84:87]
	v_mfma_f32_16x16x32_bf16 v[80:83], v[204:207], v[164:167], v[80:83]
	v_mfma_f32_16x16x32_bf16 v[68:71], v[196:199], v[172:175], v[68:71]
	v_mfma_f32_16x16x32_bf16 v[64:67], v[204:207], v[172:175], v[64:67]
	s_barrier
	s_setprio 0
	s_add_i32 s23, s45, s30
	s_mov_b32 m0, s23
	s_nop 0
	global_load_lds_dwordx4 v178, s[98:99]
	s_add_i32 m0, s23, 0x2000
	s_nop 0
	global_load_lds_dwordx4 v182, s[98:99]
	s_mov_b32 m0, s37
	ds_read_b128 v[144:147], v215 offset:49152
	ds_read_b128 v[148:151], v215 offset:50176
	ds_read_b128 v[152:155], v215 offset:51200
	ds_read_b128 v[156:159], v215 offset:52224
	ds_read_b128 v[160:163], v215 offset:53248
	ds_read_b128 v[164:167], v215 offset:54272
	ds_read_b128 v[168:171], v215 offset:55296
	ds_read_b128 v[172:175], v215 offset:56320
	global_load_lds_dwordx4 v176, s[100:101]
	s_mov_b32 m0, s38
	s_nop 0
	global_load_lds_dwordx4 v180, s[100:101]
	s_add_u32 s20, s20, 0x160080
	s_addc_u32 s21, s21, 0
	s_add_i32 s22, s22, s30
	s_mov_b32 m0, s22
	s_nop 0
	global_load_lds_dwordx4 v178, s[20:21]
	s_add_i32 m0, s22, 0x2000
	s_nop 0
	global_load_lds_dwordx4 v182, s[20:21]
	s_add_i32 s44, s44, 2
	s_add_u32 s18, s18, 0x100
	s_addc_u32 s19, s19, 0
	s_add_u32 s42, s42, 0x100
	s_addc_u32 s43, s43, 0
	s_cmpk_gt_u32 s44, 0x55
	s_waitcnt vmcnt(8)
	s_waitcnt lgkmcnt(0)
	s_setprio 1
	s_barrier
	v_mfma_f32_16x16x32_bf16 v[60:63], v[128:131], v[144:147], v[60:63]
	v_mfma_f32_16x16x32_bf16 v[56:59], v[136:139], v[144:147], v[56:59]
	v_mfma_f32_16x16x32_bf16 v[44:47], v[128:131], v[152:155], v[44:47]
	v_mfma_f32_16x16x32_bf16 v[40:43], v[136:139], v[152:155], v[40:43]
	v_mfma_f32_16x16x32_bf16 v[28:31], v[128:131], v[160:163], v[28:31]
	v_mfma_f32_16x16x32_bf16 v[24:27], v[136:139], v[160:163], v[24:27]
	v_mfma_f32_16x16x32_bf16 v[12:15], v[128:131], v[168:171], v[12:15]
	v_mfma_f32_16x16x32_bf16 v[8:11], v[136:139], v[168:171], v[8:11]
	v_mfma_f32_16x16x32_bf16 v[60:63], v[132:135], v[148:151], v[60:63]
	v_mfma_f32_16x16x32_bf16 v[56:59], v[140:143], v[148:151], v[56:59]
	v_mfma_f32_16x16x32_bf16 v[44:47], v[132:135], v[156:159], v[44:47]
	v_mfma_f32_16x16x32_bf16 v[40:43], v[140:143], v[156:159], v[40:43]
	v_mfma_f32_16x16x32_bf16 v[28:31], v[132:135], v[164:167], v[28:31]
	v_mfma_f32_16x16x32_bf16 v[24:27], v[140:143], v[164:167], v[24:27]
	v_mfma_f32_16x16x32_bf16 v[12:15], v[132:135], v[172:175], v[12:15]
	v_mfma_f32_16x16x32_bf16 v[8:11], v[140:143], v[172:175], v[8:11]
	v_mfma_f32_16x16x32_bf16 v[52:55], v[192:195], v[144:147], v[52:55]
	v_mfma_f32_16x16x32_bf16 v[48:51], v[200:203], v[144:147], v[48:51]
	v_mfma_f32_16x16x32_bf16 v[36:39], v[192:195], v[152:155], v[36:39]
	v_mfma_f32_16x16x32_bf16 v[32:35], v[200:203], v[152:155], v[32:35]
	v_mfma_f32_16x16x32_bf16 v[20:23], v[192:195], v[160:163], v[20:23]
	v_mfma_f32_16x16x32_bf16 v[16:19], v[200:203], v[160:163], v[16:19]
	v_mfma_f32_16x16x32_bf16 v[4:7], v[192:195], v[168:171], v[4:7]
	v_mfma_f32_16x16x32_bf16 v[0:3], v[200:203], v[168:171], v[0:3]
	v_mfma_f32_16x16x32_bf16 v[52:55], v[196:199], v[148:151], v[52:55]
	v_mfma_f32_16x16x32_bf16 v[48:51], v[204:207], v[148:151], v[48:51]
	v_mfma_f32_16x16x32_bf16 v[36:39], v[196:199], v[156:159], v[36:39]
	v_mfma_f32_16x16x32_bf16 v[32:35], v[204:207], v[156:159], v[32:35]
	v_mfma_f32_16x16x32_bf16 v[20:23], v[196:199], v[164:167], v[20:23]
	v_mfma_f32_16x16x32_bf16 v[16:19], v[204:207], v[164:167], v[16:19]
	v_mfma_f32_16x16x32_bf16 v[4:7], v[196:199], v[172:175], v[4:7]
	v_mfma_f32_16x16x32_bf16 v[0:3], v[204:207], v[172:175], v[0:3]
	s_barrier
; DI unsigned pack2(float lo, float hi) { f32x2 v = {lo, hi}; bf16v2 r = __builtin_convertvector(v, bf16v2); return __builtin_bit_cast(unsigned, r); }
;   DI void operator()(const f32x4 (&acc)[2][2][4][2], const Unit& u, int wr, int wc, int fr, int fq) const {
;     const int row0 = u.pm * BM + wr * 64 + fr, col0 = u.pn * BM + wc * 32 + 8 * fq;
; #pragma unroll
;     for (int ai = 0; ai < 2; ++ai) {
;       f32x4 bv[4][2][2];
; #pragma unroll
;       for (int m = 0; m < 4; ++m)
; #pragma unroll
;         for (int bj = 0; bj < 2; ++bj) {
;           const float* bp = base + (size_t)(row0 + ai * HALF + m * 16) * 2048 + col0 + bj * HALF;
;           bv[m][bj][0] = *(const f32x4*)bp; bv[m][bj][1] = *(const f32x4*)(bp + 4);
;         }
; #pragma unroll
;       for (int m = 0; m < 4; ++m) {
;         const int row = row0 + ai * HALF + m * 16;
;         const size_t off = (size_t)row * 2048 + col0;
;         float ss = 0.f;
; #pragma unroll
;         for (int bj = 0; bj < 2; ++bj) {
;           const f32x4 v0 = acc[ai][bj][m][0] + bv[m][bj][0], v1 = acc[ai][bj][m][1] + bv[m][bj][1];
;           *(f32x4*)(C + off + bj * HALF) = v0; *(f32x4*)(C + off + bj * HALF + 4) = v1;
;           if (xb) {
;             u32x4 w; w.x = pack2(v0[0], v0[1]); w.y = pack2(v0[2], v0[3]); w.z = pack2(v1[0], v1[1]); w.w = pack2(v1[2], v1[3]);
;             *(u32x4*)(xb + off + bj * HALF) = w;
;             ss += v0[0] * v0[0] + v0[1] * v0[1] + v0[2] * v0[2] + v0[3] * v0[3] + v1[0] * v1[0] + v1[1] * v1[1] + v1[2] * v1[2] + v1[3] * v1[3];
;           }
;         }
;         if (xb) {
;           ss += __shfl_xor(ss, 16); ss += __shfl_xor(ss, 32);
;           if (fq == 0) ssq[(size_t)row * 32 + u.pn * 4 + wc] = ss;
;         }
	s_setprio 0
	s_cbranch_scc0 .LBB0_961
	v_lshl_add_u32 v194, s51, 8, v211
	v_lshl_or_b32 v192, s2, 8, v213
	v_readlane_b32 s52, v243, 3
	v_ashrrev_i32_e32 v193, 31, v192
	v_readlane_b32 s66, v243, 17
	v_readlane_b32 s67, v243, 18
	v_ashrrev_i32_e32 v195, 31, v194
	v_lshlrev_b64 v[128:129], 13, v[194:195]
	v_lshl_add_u64 v[196:197], v[192:193], 2, s[66:67]
	v_lshl_add_u64 v[236:237], v[196:197], 0, v[128:129]
	global_load_dwordx4 v[220:223], v[236:237], off
	global_load_dwordx4 v[224:227], v[236:237], off offset:16
	global_load_dwordx4 v[228:231], v[236:237], off offset:512
	global_load_dwordx4 v[232:235], v[236:237], off offset:528
	v_or_b32_e32 v206, 16, v194
	v_or_b32_e32 v202, 32, v194
	v_or_b32_e32 v198, 48, v194
	v_ashrrev_i32_e32 v207, 31, v206
	v_ashrrev_i32_e32 v203, 31, v202
	v_ashrrev_i32_e32 v199, 31, v198
	v_lshlrev_b64 v[128:129], 13, v[206:207]
	v_lshlrev_b64 v[130:131], 13, v[202:203]
	v_lshlrev_b64 v[132:133], 13, v[198:199]
	v_lshl_add_u64 v[208:209], v[196:197], 0, v[128:129]
	v_lshl_add_u64 v[204:205], v[196:197], 0, v[130:131]
	v_lshl_add_u64 v[200:201], v[196:197], 0, v[132:133]
	global_load_dwordx4 v[168:171], v[208:209], off offset:16
	global_load_dwordx4 v[172:175], v[208:209], off
	global_load_dwordx4 v[160:163], v[208:209], off offset:528
	global_load_dwordx4 v[164:167], v[208:209], off offset:512
	global_load_dwordx4 v[152:155], v[204:205], off offset:16
	global_load_dwordx4 v[156:159], v[204:205], off
	global_load_dwordx4 v[144:147], v[204:205], off offset:528
	global_load_dwordx4 v[148:151], v[204:205], off offset:512
	global_load_dwordx4 v[136:139], v[200:201], off offset:16
	global_load_dwordx4 v[140:143], v[200:201], off
	global_load_dwordx4 v[128:131], v[200:201], off offset:528
	global_load_dwordx4 v[132:135], v[200:201], off offset:512
	v_and_b32_e32 v218, 64, v217
	v_xor_b32_e32 v238, 16, v217
	v_add_u32_e32 v240, 64, v218
	v_xor_b32_e32 v239, 32, v217
	v_cmp_lt_i32_e32 vcc, v238, v240
	v_lshlrev_b64 v[218:219], 11, v[194:195]
	s_lshl_b32 s18, s2, 2
	v_cndmask_b32_e32 v241, v217, v238, vcc
	v_cmp_lt_i32_e32 vcc, v239, v240
	s_ashr_i32 s19, s18, 31
	v_readlane_b32 s53, v243, 4
	v_cndmask_b32_e32 v240, v217, v239, vcc
	v_lshl_add_u64 v[238:239], v[218:219], 0, v[192:193]
	v_lshlrev_b32_e32 v218, 2, v241
	v_lshl_add_u64 v[238:239], v[238:239], 1, s[12:13]
	v_readlane_b32 s54, v243, 5
	v_readlane_b32 s55, v243, 6
	v_readlane_b32 s56, v243, 7
	v_readlane_b32 s57, v243, 8
	v_readlane_b32 s58, v243, 9
	v_readlane_b32 s59, v243, 10
	v_readlane_b32 s60, v243, 11
	v_readlane_b32 s61, v243, 12
	v_readlane_b32 s62, v243, 13
	v_readlane_b32 s63, v243, 14
	v_readlane_b32 s64, v243, 15
	v_readlane_b32 s65, v243, 16
	s_waitcnt vmcnt(0)
	v_pk_add_f32 v[126:127], v[126:127], v[222:223]
	v_pk_add_f32 v[124:125], v[124:125], v[220:221]
	v_pk_add_f32 v[116:117], v[116:117], v[228:229]
	v_pk_add_f32 v[122:123], v[122:123], v[226:227]
	v_pk_add_f32 v[120:121], v[120:121], v[224:225]
	v_pk_add_f32 v[220:221], v[112:113], v[232:233]
	global_store_dwordx4 v[236:237], v[124:127], off
	global_store_dwordx4 v[236:237], v[120:123], off offset:16
	v_cvt_pk_bf16_f32 v112, v124, v125
	v_mul_f32_e32 v125, v125, v125
	v_mul_f32_e32 v219, v117, v117
	v_pk_add_f32 v[118:119], v[118:119], v[230:231]
	v_fmac_f32_e32 v125, v124, v124
	v_fmac_f32_e32 v219, v116, v116
	v_fmac_f32_e32 v125, v126, v126
	v_fmac_f32_e32 v219, v118, v118
	v_fmac_f32_e32 v125, v127, v127
	v_fmac_f32_e32 v219, v119, v119
	v_fmac_f32_e32 v125, v120, v120
	v_fmac_f32_e32 v219, v220, v220
	v_pk_add_f32 v[222:223], v[114:115], v[234:235]
	v_fmac_f32_e32 v125, v121, v121
	v_fmac_f32_e32 v219, v221, v221
	v_fmac_f32_e32 v125, v122, v122
	v_fmac_f32_e32 v219, v222, v222
	v_fmac_f32_e32 v125, v123, v123
	v_fmac_f32_e32 v219, v223, v223
	v_cvt_pk_bf16_f32 v114, v120, v121
	v_add_f32_e32 v121, v125, v219
	v_cvt_pk_bf16_f32 v115, v122, v123
	ds_bpermute_b32 v122, v218, v121
	v_cvt_pk_bf16_f32 v113, v126, v127
	global_store_dwordx4 v[238:239], v[112:115], off
	global_store_dwordx4 v[236:237], v[116:119], off offset:512
	global_store_dwordx4 v[236:237], v[220:223], off offset:528
	v_lshlrev_b32_e32 v126, 2, v240
	v_cvt_pk_bf16_f32 v120, v116, v117
	s_waitcnt lgkmcnt(0)
	v_add_f32_e32 v112, v121, v122
	ds_bpermute_b32 v113, v126, v112
	v_cvt_pk_bf16_f32 v121, v118, v119
	v_cvt_pk_bf16_f32 v122, v220, v221
	v_cvt_pk_bf16_f32 v123, v222, v223
	global_store_dwordx4 v[238:239], v[120:123], off offset:256
	s_and_saveexec_b64 s[20:21], s[0:1]
	s_cbranch_execz .LBB0_964
	s_waitcnt lgkmcnt(0)
	v_add_f32_e32 v114, v112, v113
	v_lshlrev_b64 v[112:113], 7, v[194:195]
	v_lshl_add_u64 v[112:113], s[14:15], 0, v[112:113]
	v_lshl_add_u64 v[112:113], s[18:19], 2, v[112:113]
	s_lshl_b32 s2, s36, 2
	v_lshl_add_u64 v[112:113], v[112:113], 0, s[2:3]
	global_store_dword v[112:113], v114, off

; #define PG8_STAGE(bufoff, gbase, voff) do { _Pragma("unroll") for (int _i = 0; _i < 2; ++_i) \
;     __builtin_amdgcn_global_load_lds((const unsigned*)((const char*)(gbase) + (voff)[_i]), (LAS unsigned*)(lds + (bufoff) + ldsw + _i * 8192), 16, 0, 0); } while (0)
; #define PG8_LDA(dst, b, h) do { _Pragma("unroll") for (int m = 0; m < 4; ++m) _Pragma("unroll") for (int k = 0; k < 2; ++k) dst[m][k] = *(const LAS bf16x8*)(lds + PG8_SA(b, h) + aoff + m * 2048 + k * 1024); } while (0)
; #define PG8_LDB(dst, b, h) do { _Pragma("unroll") for (int n = 0; n < 2; ++n) _Pragma("unroll") for (int k = 0; k < 2; ++k) dst[n][k] = *(const LAS bf16x8*)(lds + PG8_SB(b, h) + boff + n * 2048 + k * 1024); } while (0)
; #define PG8_MMA(ai, bj, At, Bt) do { __builtin_amdgcn_s_setprio(1); _Pragma("unroll") for (int m = 0; m < 4; ++m) _Pragma("unroll") for (int n = 0; n < 2; ++n) _Pragma("unroll") for (int k = 0; k < 2; ++k) \
;     acc[ai][bj][m][n] = __builtin_amdgcn_mfma_f32_16x16x32_bf16(Bt[n][k], At[m][k], acc[ai][bj][m][n], 0, 0, 0); __builtin_amdgcn_s_setprio(0); } while (0)
; #define PG8_WAIT_V(n) asm volatile("s_waitcnt vmcnt(" #n ")" ::: "memory")
; #define PG8_WAIT_L(n) asm volatile("s_waitcnt lgkmcnt(" #n ")" ::: "memory")
; #define PG8_BAR __builtin_amdgcn_s_barrier()
; #define PG8_SCHED __builtin_amdgcn_sched_barrier(0)
; template <class Epi, class Sched = StaticOrder>
; DI void gemm_phase(LAS unsigned char* lds, const Gemm g, const Sched& S, const Epi& E) {
;     ...
;     for (int t = 0; t < nt; t += 2) {
;       const bool last = (t == nt - 2);
;       const char* a1 = cA + (size_t)(t + 1) * kstep;
;       const char* a2 = last ? nA : cA + (size_t)(t + 2) * kstep; const char* b2 = last ? nB : cB + (size_t)(t + 2) * kstep;
;       const char* a3 = a2 + kstep; const char* b3 = b2 + kstep;
;       PG8_LDB(B0, 0, 0); PG8_SCHED; PG8_LDA(At, 0, 0); PG8_STAGE(PG8_SA(1, 1), a1 + hstep, voffA);
;       PG8_WAIT_L(8); PG8_BAR; PG8_WAIT_L(0); PG8_MMA(0, 0, At, B0); PG8_BAR; PG8_SCHED;
;       PG8_LDB(B1, 0, 1); PG8_STAGE(PG8_SB(0, 0), b2, voffB);
;       PG8_BAR; PG8_WAIT_L(0); PG8_MMA(0, 1, At, B1); PG8_BAR;
;       PG8_LDA(At, 0, 1); PG8_STAGE(PG8_SA(0, 0), a2, voffA);
;       PG8_BAR; PG8_WAIT_L(0); PG8_MMA(1, 0, At, B0); PG8_BAR; PG8_SCHED;
;       PG8_STAGE(PG8_SB(0, 1), b2 + hstep, voffB);
;       PG8_WAIT_V(6); PG8_BAR; PG8_MMA(1, 1, At, B1); PG8_BAR;
.LBB0_1052:
	ds_read_b128 v[128:131], v203
	ds_read_b128 v[132:135], v203 offset:1024
	ds_read_b128 v[136:139], v203 offset:2048
	ds_read_b128 v[140:143], v203 offset:3072
	s_add_u32 s12, s10, 0xfff80080
	s_addc_u32 s13, s11, -1
	s_cmp_eq_u32 s52, 28
	s_cselect_b32 s65, s41, s13
	s_cselect_b32 s64, s42, s12
	s_cselect_b32 s13, s43, s49
	s_cselect_b32 s12, s44, s45
	s_add_i32 m0, s61, 0xc000
	ds_read_b128 v[144:147], v204
	ds_read_b128 v[148:151], v204 offset:1024
	ds_read_b128 v[152:155], v204 offset:2048
	ds_read_b128 v[156:159], v204 offset:3072
	ds_read_b128 v[178:181], v204 offset:4096
	ds_read_b128 v[182:185], v204 offset:5120
	ds_read_b128 v[186:189], v204 offset:6144
	ds_read_b128 v[190:193], v204 offset:7168
	global_load_lds_dwordx4 v172, s[10:11]
	s_add_i32 m0, s61, 0xe000
	s_nop 0
	global_load_lds_dwordx4 v174, s[10:11]
	ds_read_b128 v[194:197], v205
	ds_read_b128 v[212:215], v205 offset:1024
	ds_read_b128 v[216:219], v205 offset:2048
	ds_read_b128 v[220:223], v205 offset:3072
	s_waitcnt vmcnt(8)
	s_waitcnt lgkmcnt(4)
	s_setprio 1
	s_barrier
	v_mfma_f32_16x16x32_bf16 v[124:127], v[128:131], v[144:147], v[124:127]
	v_mfma_f32_16x16x32_bf16 v[120:123], v[136:139], v[144:147], v[120:123]
	v_mfma_f32_16x16x32_bf16 v[116:119], v[128:131], v[152:155], v[116:119]
	v_mfma_f32_16x16x32_bf16 v[104:107], v[136:139], v[152:155], v[104:107]
	v_mfma_f32_16x16x32_bf16 v[92:95], v[128:131], v[178:181], v[92:95]
	v_mfma_f32_16x16x32_bf16 v[88:91], v[136:139], v[178:181], v[88:91]
	v_mfma_f32_16x16x32_bf16 v[84:87], v[128:131], v[186:189], v[84:87]
	v_mfma_f32_16x16x32_bf16 v[72:75], v[136:139], v[186:189], v[72:75]
	v_mfma_f32_16x16x32_bf16 v[124:127], v[132:135], v[148:151], v[124:127]
	v_mfma_f32_16x16x32_bf16 v[120:123], v[140:143], v[148:151], v[120:123]
	v_mfma_f32_16x16x32_bf16 v[116:119], v[132:135], v[156:159], v[116:119]
	v_mfma_f32_16x16x32_bf16 v[104:107], v[140:143], v[156:159], v[104:107]
	v_mfma_f32_16x16x32_bf16 v[92:95], v[132:135], v[182:185], v[92:95]
	v_mfma_f32_16x16x32_bf16 v[88:91], v[140:143], v[182:185], v[88:91]
	v_mfma_f32_16x16x32_bf16 v[84:87], v[132:135], v[190:193], v[84:87]
	v_mfma_f32_16x16x32_bf16 v[72:75], v[140:143], v[190:193], v[72:75]
	s_waitcnt lgkmcnt(0)
	v_mfma_f32_16x16x32_bf16 v[112:115], v[194:197], v[144:147], v[112:115]
	v_mfma_f32_16x16x32_bf16 v[108:111], v[216:219], v[144:147], v[108:111]
	v_mfma_f32_16x16x32_bf16 v[100:103], v[194:197], v[152:155], v[100:103]
	v_mfma_f32_16x16x32_bf16 v[96:99], v[216:219], v[152:155], v[96:99]
	v_mfma_f32_16x16x32_bf16 v[80:83], v[194:197], v[178:181], v[80:83]
	v_mfma_f32_16x16x32_bf16 v[76:79], v[216:219], v[178:181], v[76:79]
	v_mfma_f32_16x16x32_bf16 v[68:71], v[194:197], v[186:189], v[68:71]
	v_mfma_f32_16x16x32_bf16 v[64:67], v[216:219], v[186:189], v[64:67]
	v_mfma_f32_16x16x32_bf16 v[112:115], v[212:215], v[148:151], v[112:115]
	v_mfma_f32_16x16x32_bf16 v[108:111], v[220:223], v[148:151], v[108:111]
	v_mfma_f32_16x16x32_bf16 v[100:103], v[212:215], v[156:159], v[100:103]
	v_mfma_f32_16x16x32_bf16 v[96:99], v[220:223], v[156:159], v[96:99]
	v_mfma_f32_16x16x32_bf16 v[80:83], v[212:215], v[182:185], v[80:83]
	v_mfma_f32_16x16x32_bf16 v[76:79], v[220:223], v[182:185], v[76:79]
	v_mfma_f32_16x16x32_bf16 v[68:71], v[212:215], v[190:193], v[68:71]
	v_mfma_f32_16x16x32_bf16 v[64:67], v[220:223], v[190:193], v[64:67]
	s_barrier
	s_setprio 0
	s_add_i32 s53, s80, s70
	s_add_u32 s98, s12, 0x80
	s_addc_u32 s99, s13, 0
	s_add_u32 s100, s64, 0x80
	s_addc_u32 s101, s65, 0
	s_mov_b32 m0, s53
	s_nop 0
	global_load_lds_dwordx4 v162, s[12:13]
	s_add_i32 m0, s53, 0x2000
	s_nop 0
	global_load_lds_dwordx4 v166, s[12:13]
	s_mov_b32 m0, s61
	ds_read_b128 v[144:147], v204 offset:16384
	ds_read_b128 v[148:151], v204 offset:17408
	ds_read_b128 v[152:155], v204 offset:18432
	ds_read_b128 v[156:159], v204 offset:19456
	ds_read_b128 v[178:181], v204 offset:20480
	ds_read_b128 v[182:185], v204 offset:21504
	ds_read_b128 v[186:189], v204 offset:22528
	ds_read_b128 v[190:193], v204 offset:23552
	global_load_lds_dwordx4 v160, s[64:65]
	s_mov_b32 m0, s63
	s_nop 0
	global_load_lds_dwordx4 v164, s[64:65]
	s_add_u32 s54, s12, 0x80000
	s_addc_u32 s55, s13, 0
	s_add_i32 s53, s81, s70
	s_mov_b32 m0, s53
	s_nop 0
	global_load_lds_dwordx4 v162, s[54:55]
	s_add_i32 m0, s53, 0x2000
	s_nop 0
	global_load_lds_dwordx4 v166, s[54:55]
	s_waitcnt vmcnt(8)
	s_waitcnt lgkmcnt(0)
	s_setprio 1
	s_barrier
	v_mfma_f32_16x16x32_bf16 v[60:63], v[128:131], v[144:147], v[60:63]
	v_mfma_f32_16x16x32_bf16 v[56:59], v[136:139], v[144:147], v[56:59]
	v_mfma_f32_16x16x32_bf16 v[48:51], v[128:131], v[152:155], v[48:51]
	v_mfma_f32_16x16x32_bf16 v[40:43], v[136:139], v[152:155], v[40:43]
	v_mfma_f32_16x16x32_bf16 v[28:31], v[128:131], v[178:181], v[28:31]
	v_mfma_f32_16x16x32_bf16 v[24:27], v[136:139], v[178:181], v[24:27]
	v_mfma_f32_16x16x32_bf16 v[12:15], v[128:131], v[186:189], v[12:15]
	v_mfma_f32_16x16x32_bf16 v[8:11], v[136:139], v[186:189], v[8:11]
	v_mfma_f32_16x16x32_bf16 v[60:63], v[132:135], v[148:151], v[60:63]
	v_mfma_f32_16x16x32_bf16 v[56:59], v[140:143], v[148:151], v[56:59]
	v_mfma_f32_16x16x32_bf16 v[48:51], v[132:135], v[156:159], v[48:51]
	v_mfma_f32_16x16x32_bf16 v[40:43], v[140:143], v[156:159], v[40:43]
	v_mfma_f32_16x16x32_bf16 v[28:31], v[132:135], v[182:185], v[28:31]
	v_mfma_f32_16x16x32_bf16 v[24:27], v[140:143], v[182:185], v[24:27]
	v_mfma_f32_16x16x32_bf16 v[12:15], v[132:135], v[190:193], v[12:15]
	v_mfma_f32_16x16x32_bf16 v[8:11], v[140:143], v[190:193], v[8:11]
	v_mfma_f32_16x16x32_bf16 v[52:55], v[194:197], v[144:147], v[52:55]
	v_mfma_f32_16x16x32_bf16 v[44:47], v[216:219], v[144:147], v[44:47]
	v_mfma_f32_16x16x32_bf16 v[36:39], v[194:197], v[152:155], v[36:39]
	v_mfma_f32_16x16x32_bf16 v[32:35], v[216:219], v[152:155], v[32:35]
	v_mfma_f32_16x16x32_bf16 v[20:23], v[194:197], v[178:181], v[20:23]
	v_mfma_f32_16x16x32_bf16 v[16:19], v[216:219], v[178:181], v[16:19]
	v_mfma_f32_16x16x32_bf16 v[4:7], v[194:197], v[186:189], v[4:7]
	v_mfma_f32_16x16x32_bf16 v[0:3], v[216:219], v[186:189], v[0:3]
	v_mfma_f32_16x16x32_bf16 v[52:55], v[212:215], v[148:151], v[52:55]
	v_mfma_f32_16x16x32_bf16 v[44:47], v[220:223], v[148:151], v[44:47]
	v_mfma_f32_16x16x32_bf16 v[36:39], v[212:215], v[156:159], v[36:39]
	v_mfma_f32_16x16x32_bf16 v[32:35], v[220:223], v[156:159], v[32:35]
	v_mfma_f32_16x16x32_bf16 v[20:23], v[212:215], v[182:185], v[20:23]
	v_mfma_f32_16x16x32_bf16 v[16:19], v[220:223], v[182:185], v[16:19]
	v_mfma_f32_16x16x32_bf16 v[4:7], v[212:215], v[190:193], v[4:7]
	v_mfma_f32_16x16x32_bf16 v[0:3], v[220:223], v[190:193], v[0:3]
	s_barrier
; #define PG8_STAGE(bufoff, gbase, voff) do { _Pragma("unroll") for (int _i = 0; _i < 2; ++_i) \
;     __builtin_amdgcn_global_load_lds((const unsigned*)((const char*)(gbase) + (voff)[_i]), (LAS unsigned*)(lds + (bufoff) + ldsw + _i * 8192), 16, 0, 0); } while (0)
; #define PG8_LDA(dst, b, h) do { _Pragma("unroll") for (int m = 0; m < 4; ++m) _Pragma("unroll") for (int k = 0; k < 2; ++k) dst[m][k] = *(const LAS bf16x8*)(lds + PG8_SA(b, h) + aoff + m * 2048 + k * 1024); } while (0)
; #define PG8_LDB(dst, b, h) do { _Pragma("unroll") for (int n = 0; n < 2; ++n) _Pragma("unroll") for (int k = 0; k < 2; ++k) dst[n][k] = *(const LAS bf16x8*)(lds + PG8_SB(b, h) + boff + n * 2048 + k * 1024); } while (0)
; #define PG8_MMA(ai, bj, At, Bt) do { __builtin_amdgcn_s_setprio(1); _Pragma("unroll") for (int m = 0; m < 4; ++m) _Pragma("unroll") for (int n = 0; n < 2; ++n) _Pragma("unroll") for (int k = 0; k < 2; ++k) \
;     acc[ai][bj][m][n] = __builtin_amdgcn_mfma_f32_16x16x32_bf16(Bt[n][k], At[m][k], acc[ai][bj][m][n], 0, 0, 0); __builtin_amdgcn_s_setprio(0); } while (0)
; #define PG8_WAIT_V(n) asm volatile("s_waitcnt vmcnt(" #n ")" ::: "memory")
; #define PG8_WAIT_L(n) asm volatile("s_waitcnt lgkmcnt(" #n ")" ::: "memory")
; #define PG8_BAR __builtin_amdgcn_s_barrier()
; #define PG8_SCHED __builtin_amdgcn_sched_barrier(0)
; template <class Epi, class Sched = StaticOrder>
; DI void gemm_phase(LAS unsigned char* lds, const Gemm g, const Sched& S, const Epi& E) {
;     ...
;       PG8_LDB(B0, 1, 0); PG8_SCHED; PG8_LDA(At, 1, 0); PG8_STAGE(PG8_SA(0, 1), a2 + hstep, voffA);
;       PG8_WAIT_L(8); PG8_BAR; PG8_WAIT_L(0); PG8_MMA(0, 0, At, B0); PG8_BAR; PG8_SCHED;
;       PG8_LDB(B1, 1, 1); PG8_STAGE(PG8_SB(1, 0), b3, voffB);
;       PG8_BAR; PG8_WAIT_L(0); PG8_MMA(0, 1, At, B1); PG8_BAR;
;       PG8_LDA(At, 1, 1); PG8_STAGE(PG8_SA(1, 0), a3, voffA);
;       PG8_BAR; PG8_WAIT_L(0); PG8_MMA(1, 0, At, B0); PG8_BAR; PG8_SCHED;
;       PG8_STAGE(PG8_SB(1, 1), b3 + hstep, voffB);
;       PG8_WAIT_V(6); PG8_BAR; PG8_MMA(1, 1, At, B1); PG8_BAR;
	s_setprio 0
	s_add_i32 s53, 0, 0x18000
	v_add_u32_e32 v140, s53, v199
	ds_read_b128 v[128:131], v140
	ds_read_b128 v[132:135], v140 offset:1024
	ds_read_b128 v[136:139], v140 offset:2048
	ds_read_b128 v[140:143], v140 offset:3072
	s_add_u32 s54, s64, 0x80000
	s_addc_u32 s55, s65, 0
	s_mov_b32 m0, s71
	ds_read_b128 v[144:147], v204 offset:32768
	ds_read_b128 v[148:151], v204 offset:33792
	ds_read_b128 v[152:155], v204 offset:34816
	ds_read_b128 v[156:159], v204 offset:35840
	ds_read_b128 v[178:181], v204 offset:36864
	ds_read_b128 v[182:185], v204 offset:37888
	ds_read_b128 v[186:189], v204 offset:38912
	ds_read_b128 v[190:193], v204 offset:39936
	global_load_lds_dwordx4 v160, s[54:55]
	s_mov_b32 m0, s72
	s_nop 0
	global_load_lds_dwordx4 v164, s[54:55]
	s_add_i32 s54, 0, 0x1c000
	v_add_u32_e32 v168, s54, v199
	ds_read_b128 v[194:197], v168
	ds_read_b128 v[212:215], v168 offset:1024
	ds_read_b128 v[216:219], v168 offset:2048
	ds_read_b128 v[220:223], v168 offset:3072
	s_waitcnt vmcnt(8)
	s_waitcnt lgkmcnt(4)
	s_setprio 1
	s_barrier
	v_mfma_f32_16x16x32_bf16 v[124:127], v[128:131], v[144:147], v[124:127]
	v_mfma_f32_16x16x32_bf16 v[120:123], v[136:139], v[144:147], v[120:123]
	v_mfma_f32_16x16x32_bf16 v[116:119], v[128:131], v[152:155], v[116:119]
	v_mfma_f32_16x16x32_bf16 v[104:107], v[136:139], v[152:155], v[104:107]
	v_mfma_f32_16x16x32_bf16 v[92:95], v[128:131], v[178:181], v[92:95]
	v_mfma_f32_16x16x32_bf16 v[88:91], v[136:139], v[178:181], v[88:91]
	v_mfma_f32_16x16x32_bf16 v[84:87], v[128:131], v[186:189], v[84:87]
	v_mfma_f32_16x16x32_bf16 v[72:75], v[136:139], v[186:189], v[72:75]
	v_mfma_f32_16x16x32_bf16 v[124:127], v[132:135], v[148:151], v[124:127]
	v_mfma_f32_16x16x32_bf16 v[120:123], v[140:143], v[148:151], v[120:123]
	v_mfma_f32_16x16x32_bf16 v[116:119], v[132:135], v[156:159], v[116:119]
	v_mfma_f32_16x16x32_bf16 v[104:107], v[140:143], v[156:159], v[104:107]
	v_mfma_f32_16x16x32_bf16 v[92:95], v[132:135], v[182:185], v[92:95]
	v_mfma_f32_16x16x32_bf16 v[88:91], v[140:143], v[182:185], v[88:91]
	v_mfma_f32_16x16x32_bf16 v[84:87], v[132:135], v[190:193], v[84:87]
	v_mfma_f32_16x16x32_bf16 v[72:75], v[140:143], v[190:193], v[72:75]
	s_waitcnt lgkmcnt(0)
	v_mfma_f32_16x16x32_bf16 v[112:115], v[194:197], v[144:147], v[112:115]
	v_mfma_f32_16x16x32_bf16 v[108:111], v[216:219], v[144:147], v[108:111]
	v_mfma_f32_16x16x32_bf16 v[100:103], v[194:197], v[152:155], v[100:103]
	v_mfma_f32_16x16x32_bf16 v[96:99], v[216:219], v[152:155], v[96:99]
	v_mfma_f32_16x16x32_bf16 v[80:83], v[194:197], v[178:181], v[80:83]
	v_mfma_f32_16x16x32_bf16 v[76:79], v[216:219], v[178:181], v[76:79]
	v_mfma_f32_16x16x32_bf16 v[68:71], v[194:197], v[186:189], v[68:71]
	v_mfma_f32_16x16x32_bf16 v[64:67], v[216:219], v[186:189], v[64:67]
	v_mfma_f32_16x16x32_bf16 v[112:115], v[212:215], v[148:151], v[112:115]
	v_mfma_f32_16x16x32_bf16 v[108:111], v[220:223], v[148:151], v[108:111]
	v_mfma_f32_16x16x32_bf16 v[100:103], v[212:215], v[156:159], v[100:103]
	v_mfma_f32_16x16x32_bf16 v[96:99], v[220:223], v[156:159], v[96:99]
	v_mfma_f32_16x16x32_bf16 v[80:83], v[212:215], v[182:185], v[80:83]
	v_mfma_f32_16x16x32_bf16 v[76:79], v[220:223], v[182:185], v[76:79]
	v_mfma_f32_16x16x32_bf16 v[68:71], v[212:215], v[190:193], v[68:71]
	v_mfma_f32_16x16x32_bf16 v[64:67], v[220:223], v[190:193], v[64:67]
	s_barrier
	s_setprio 0
	s_add_i32 s53, s53, s70
	s_mov_b32 m0, s53
	s_nop 0
	global_load_lds_dwordx4 v162, s[98:99]
	s_add_i32 m0, s53, 0x2000
	s_nop 0
	global_load_lds_dwordx4 v166, s[98:99]
	s_mov_b32 m0, s76
	ds_read_b128 v[144:147], v204 offset:49152
	ds_read_b128 v[148:151], v204 offset:50176
	ds_read_b128 v[152:155], v204 offset:51200
	ds_read_b128 v[156:159], v204 offset:52224
	ds_read_b128 v[178:181], v204 offset:53248
	ds_read_b128 v[182:185], v204 offset:54272
	ds_read_b128 v[186:189], v204 offset:55296
	ds_read_b128 v[190:193], v204 offset:56320
	global_load_lds_dwordx4 v160, s[100:101]
	s_mov_b32 m0, s77
	s_nop 0
	global_load_lds_dwordx4 v164, s[100:101]
	s_add_u32 s12, s12, 0x80080
	s_addc_u32 s13, s13, 0
	s_add_i32 s53, s54, s70
	s_mov_b32 m0, s53
	s_nop 0
	global_load_lds_dwordx4 v162, s[12:13]
	s_add_i32 m0, s53, 0x2000
	s_nop 0
	global_load_lds_dwordx4 v166, s[12:13]
	s_add_i32 s52, s52, 2
	s_add_u32 s10, s10, 0x100
	s_addc_u32 s11, s11, 0
	s_add_u32 s45, s45, 0x100
	s_addc_u32 s49, s49, 0
	s_cmp_gt_u32 s52, 29
	s_waitcnt vmcnt(8)
	s_waitcnt lgkmcnt(0)
	s_setprio 1
	s_barrier
	v_mfma_f32_16x16x32_bf16 v[60:63], v[128:131], v[144:147], v[60:63]
	v_mfma_f32_16x16x32_bf16 v[56:59], v[136:139], v[144:147], v[56:59]
	v_mfma_f32_16x16x32_bf16 v[48:51], v[128:131], v[152:155], v[48:51]
	v_mfma_f32_16x16x32_bf16 v[40:43], v[136:139], v[152:155], v[40:43]
	v_mfma_f32_16x16x32_bf16 v[28:31], v[128:131], v[178:181], v[28:31]
	v_mfma_f32_16x16x32_bf16 v[24:27], v[136:139], v[178:181], v[24:27]
	v_mfma_f32_16x16x32_bf16 v[12:15], v[128:131], v[186:189], v[12:15]
	v_mfma_f32_16x16x32_bf16 v[8:11], v[136:139], v[186:189], v[8:11]
	v_mfma_f32_16x16x32_bf16 v[60:63], v[132:135], v[148:151], v[60:63]
	v_mfma_f32_16x16x32_bf16 v[56:59], v[140:143], v[148:151], v[56:59]
	v_mfma_f32_16x16x32_bf16 v[48:51], v[132:135], v[156:159], v[48:51]
	v_mfma_f32_16x16x32_bf16 v[40:43], v[140:143], v[156:159], v[40:43]
	v_mfma_f32_16x16x32_bf16 v[28:31], v[132:135], v[182:185], v[28:31]
	v_mfma_f32_16x16x32_bf16 v[24:27], v[140:143], v[182:185], v[24:27]
	v_mfma_f32_16x16x32_bf16 v[12:15], v[132:135], v[190:193], v[12:15]
	v_mfma_f32_16x16x32_bf16 v[8:11], v[140:143], v[190:193], v[8:11]
	v_mfma_f32_16x16x32_bf16 v[52:55], v[194:197], v[144:147], v[52:55]
	v_mfma_f32_16x16x32_bf16 v[44:47], v[216:219], v[144:147], v[44:47]
	v_mfma_f32_16x16x32_bf16 v[36:39], v[194:197], v[152:155], v[36:39]
	v_mfma_f32_16x16x32_bf16 v[32:35], v[216:219], v[152:155], v[32:35]
	v_mfma_f32_16x16x32_bf16 v[20:23], v[194:197], v[178:181], v[20:23]
	v_mfma_f32_16x16x32_bf16 v[16:19], v[216:219], v[178:181], v[16:19]
	v_mfma_f32_16x16x32_bf16 v[4:7], v[194:197], v[186:189], v[4:7]
	v_mfma_f32_16x16x32_bf16 v[0:3], v[216:219], v[186:189], v[0:3]
	v_mfma_f32_16x16x32_bf16 v[52:55], v[212:215], v[148:151], v[52:55]
	v_mfma_f32_16x16x32_bf16 v[44:47], v[220:223], v[148:151], v[44:47]
	v_mfma_f32_16x16x32_bf16 v[36:39], v[212:215], v[156:159], v[36:39]
	v_mfma_f32_16x16x32_bf16 v[32:35], v[220:223], v[156:159], v[32:35]
	v_mfma_f32_16x16x32_bf16 v[20:23], v[212:215], v[182:185], v[20:23]
	v_mfma_f32_16x16x32_bf16 v[16:19], v[220:223], v[182:185], v[16:19]
	v_mfma_f32_16x16x32_bf16 v[4:7], v[212:215], v[190:193], v[4:7]
	v_mfma_f32_16x16x32_bf16 v[0:3], v[220:223], v[190:193], v[0:3]
	s_barrier
; DI float row_rstd(const float* ssq, int row, int fq) {
;   const f32x4 a = *(const f32x4*)(ssq + (size_t)row * 32 + fq * 8), b = *(const f32x4*)(ssq + (size_t)row * 32 + fq * 8 + 4);
;   float sm = ((a[0] + a[1]) + (a[2] + a[3])) + ((b[0] + b[1]) + (b[2] + b[3]));
;   sm += __shfl_xor(sm, 16); sm += __shfl_xor(sm, 32);
;   return rsqrtf(sm * (1.0f / 2048.f) + 1e-6f);
;   DI void operator()(const f32x4 (&acc)[2][2][4][2], const Unit& u, int wr, int wc, int fr, int fq) const {
;     ...
;     const int col = u.pn * 128 + wc * 32 + 8 * fq;
;     float w0[8], w1[8], w2[8];
; #pragma unroll
;     for (int e = 0; e < 8; ++e) { w0[e] = cw[col + e]; w1[e] = cw[2048 + col + e]; w2[e] = cw[4096 + col + e]; }
; #pragma unroll
;     for (int ai = 0; ai < 2; ++ai) {
;       const int row0 = u.pm * BM + ai * HALF + wr * 64, span = row0 >> 6;
;       float rsv[4];
; #pragma unroll
;       for (int m = 0; m < 4; ++m) rsv[m] = row_rstd(ssq, row0 + 16 * m + fr, fq);
	s_setprio 0
	s_cbranch_scc0 .LBB0_1052
	s_cmp_lt_i32 s62, 16
	s_mov_b64 s[10:11], -1
	s_cbranch_scc0 .LBB0_1067
	s_lshl_b32 s41, s60, 8
	s_add_i32 s41, s41, s75
	v_or_b32_e32 v186, s41, v177
	v_ashrrev_i32_e32 v187, 31, v186
	v_lshlrev_b64 v[128:129], 7, v[186:187]
	v_or_b32_e32 v180, 16, v186
	v_lshl_add_u64 v[128:129], v[170:171], 0, v[128:129]
	v_ashrrev_i32_e32 v181, 31, v180
	global_load_dwordx4 v[152:155], v[128:129], off
	global_load_dwordx4 v[156:159], v[128:129], off offset:16
	v_lshlrev_b64 v[128:129], 7, v[180:181]
	v_lshl_add_u64 v[128:129], v[170:171], 0, v[128:129]
	global_load_dwordx4 v[188:191], v[128:129], off
	global_load_dwordx4 v[192:195], v[128:129], off offset:16
	v_or_b32_e32 v184, 32, v186
	v_ashrrev_i32_e32 v185, 31, v184
	v_lshlrev_b64 v[128:129], 7, v[184:185]
	v_or_b32_e32 v182, 48, v186
	v_lshl_add_u64 v[128:129], v[170:171], 0, v[128:129]
	v_ashrrev_i32_e32 v183, 31, v182
	global_load_dwordx4 v[212:215], v[128:129], off
	global_load_dwordx4 v[216:219], v[128:129], off offset:16
	v_lshlrev_b64 v[128:129], 7, v[182:183]
	v_lshl_add_u64 v[128:129], v[170:171], 0, v[128:129]
	global_load_dwordx4 v[220:223], v[128:129], off
	global_load_dwordx4 v[224:227], v[128:129], off offset:16
	v_and_b32_e32 v129, 64, v206
	v_lshl_or_b32 v178, s62, 7, v200
	v_xor_b32_e32 v128, 16, v206
	v_add_u32_e32 v129, 64, v129
	v_readlane_b32 s44, v243, 3
	v_xor_b32_e32 v130, 32, v206
	v_ashrrev_i32_e32 v179, 31, v178
	v_readlane_b32 s45, v243, 4
	v_cmp_lt_i32_e32 vcc, v128, v129
	s_movk_i32 s10, 0x2000
	v_lshl_add_u64 v[144:145], v[178:179], 2, s[44:45]
	v_cndmask_b32_e32 v134, v206, v128, vcc
	v_cmp_lt_i32_e32 vcc, v130, v129
	v_lshl_add_u64 v[132:133], v[144:145], 0, s[26:27]
	v_lshl_add_u64 v[136:137], v[144:145], 0, s[28:29]
	v_cndmask_b32_e32 v135, v206, v130, vcc
	v_add_co_u32_e32 v146, vcc, s10, v144
	global_load_dwordx4 v[128:131], v[144:145], off offset:16
	global_load_dwordx4 v[140:143], v[144:145], off
	v_addc_co_u32_e32 v147, vcc, 0, v145, vcc
	v_add_co_u32_e32 v148, vcc, s74, v144
	v_lshlrev_b32_e32 v196, 2, v134
	s_nop 0
	v_addc_co_u32_e32 v149, vcc, 0, v145, vcc
	v_lshlrev_b32_e32 v207, 2, v135
	global_load_dwordx4 v[132:135], v[132:133], off offset:16
	s_nop 0
	global_load_dwordx4 v[136:139], v[136:137], off offset:16
	s_nop 0
	global_load_dwordx4 v[144:147], v[146:147], off
	s_nop 0
	global_load_dwordx4 v[148:151], v[148:149], off
	v_mov_b32_e32 v197, 0
	v_mov_b32_e32 v211, 0
	v_readlane_b32 s46, v243, 5
	v_readlane_b32 s47, v243, 6
	v_readlane_b32 s48, v243, 7
	v_readlane_b32 s49, v243, 8
	v_readlane_b32 s50, v243, 9
	v_readlane_b32 s51, v243, 10
	v_readlane_b32 s52, v243, 11
	v_readlane_b32 s53, v243, 12
	v_readlane_b32 s54, v243, 13
	v_readlane_b32 s55, v243, 14
	v_readlane_b32 s56, v243, 15
	v_readlane_b32 s57, v243, 16
	v_readlane_b32 s58, v243, 17
	v_readlane_b32 s59, v243, 18
	s_waitcnt vmcnt(0)
	v_mov_b32_e32 v208, v152
	v_mov_b32_e32 v209, v156
	v_mov_b32_e32 v156, v153
	v_mov_b32_e32 v152, v154
	v_mov_b32_e32 v153, v158
	v_mov_b32_e32 v158, v155
	v_pk_add_f32 v[154:155], v[208:209], v[156:157]
	v_pk_add_f32 v[152:153], v[152:153], v[158:159]
	v_mov_b32_e32 v156, v188
	v_mov_b32_e32 v157, v192
	v_mov_b32_e32 v192, v189
	v_mov_b32_e32 v158, v190
	v_mov_b32_e32 v159, v194
	v_mov_b32_e32 v194, v191
	v_pk_add_f32 v[152:153], v[154:155], v[152:153]
	v_pk_add_f32 v[154:155], v[156:157], v[192:193]
	v_pk_add_f32 v[156:157], v[158:159], v[194:195]
	v_mov_b32_e32 v188, v212
	v_pk_add_f32 v[154:155], v[154:155], v[156:157]
	v_mov_b32_e32 v157, v152
	v_mov_b32_e32 v156, v154
	v_mov_b32_e32 v152, v155
	v_pk_add_f32 v[152:153], v[156:157], v[152:153]
	ds_bpermute_b32 v155, v196, v153
	ds_bpermute_b32 v154, v196, v152
	v_mov_b32_e32 v189, v216
	v_mov_b32_e32 v216, v213
	v_mov_b32_e32 v190, v214
	v_mov_b32_e32 v191, v218
	s_waitcnt lgkmcnt(0)
	v_pk_add_f32 v[152:153], v[152:153], v[154:155]
	ds_bpermute_b32 v155, v207, v153
	ds_bpermute_b32 v154, v207, v152
	v_mov_b32_e32 v218, v215
	v_mov_b32_e32 v208, v220
	v_mov_b32_e32 v209, v224
	v_mov_b32_e32 v224, v221
	v_mov_b32_e32 v212, v222
	v_mov_b32_e32 v213, v226
	v_mov_b32_e32 v226, v223
	v_pk_add_f32 v[156:157], v[188:189], v[216:217]
	v_pk_add_f32 v[158:159], v[190:191], v[218:219]
	v_pk_add_f32 v[188:189], v[208:209], v[224:225]
	v_pk_add_f32 v[190:191], v[212:213], v[226:227]
	s_waitcnt lgkmcnt(0)
; DI unsigned pack2(float lo, float hi) { f32x2 v = {lo, hi}; bf16v2 r = __builtin_convertvector(v, bf16v2); return __builtin_bit_cast(unsigned, r); }
; DI float dpp_ror1(float v) { return __int_as_float(__builtin_amdgcn_update_dpp(0, __float_as_int(v), 0x121, 0xf, 0xf, false)); }
; DI float dpp_ror2(float v) { return __int_as_float(__builtin_amdgcn_update_dpp(0, __float_as_int(v), 0x122, 0xf, 0xf, false)); }
;   DI void operator()(const f32x4 (&acc)[2][2][4][2], const Unit& u, int wr, int wc, int fr, int fq) const {
;     ...
;       for (int m = 0; m < 4; ++m) {
;         float g[8], a[8];
;         const float rs1 = rsv[m], rs2 = rs1 * rs1;
; #pragma unroll
;         for (int e = 0; e < 4; ++e) { g[e] = acc[ai][0][m][0][e] * acc[ai][1][m][0][e] * rs2; g[4 + e] = acc[ai][0][m][1][e] * acc[ai][1][m][1][e] * rs2; }
; #pragma unroll
;         for (int e = 0; e < 8; ++e) {
;           const float x1 = dpp_ror1(g[e]), x2 = dpp_ror2(g[e]);
;           const float pr1 = (fr == 0) ? p1[e] : x1, pr2 = (fr < 2) ? p2[e] : x2;
;           a[e] = w2[e] * g[e] + w1[e] * pr1 + w0[e] * pr2;
;           p1[e] = x1; p2[e] = x2;
;         }
;         if (m == 0 && fr < 2) {
;           float* hc = headC + (size_t)(span * 2 + fr) * 2048 + col;
;           *(f32x4*)hc = (f32x4){a[0], a[1], a[2], a[3]}; *(f32x4*)(hc + 4) = (f32x4){a[4], a[5], a[6], a[7]};
;         } else {
;           u32x4 w; w.x = pack2(a[0] * rs1, a[1] * rs1); w.y = pack2(a[2] * rs1, a[3] * rs1); w.z = pack2(a[4] * rs1, a[5] * rs1); w.w = pack2(a[6] * rs1, a[7] * rs1);
;           *(u32x4*)(C + (size_t)(row0 + 16 * m + fr) * 2048 + col) = w;
;         }
	v_pk_add_f32 v[152:153], v[152:153], v[154:155]
	v_pk_add_f32 v[156:157], v[156:157], v[158:159]
	v_pk_add_f32 v[158:159], v[188:189], v[190:191]
	v_pk_fma_f32 v[188:189], v[152:153], s[30:31], v[176:177] op_sel_hi:[1,0,0]
	v_mov_b32_e32 v153, v156
	v_mul_f32_e32 v152, 0x4b800000, v189
	v_cmp_gt_f32_e64 s[10:11], s84, v189
	v_mov_b32_e32 v156, v159
	v_mov_b32_e32 v194, v123
	v_cndmask_b32_e64 v152, v189, v152, s[10:11]
	v_rsq_f32_e32 v168, v152
	v_mov_b32_e32 v152, v158
	v_pk_add_f32 v[152:153], v[152:153], v[156:157]
	ds_bpermute_b32 v155, v196, v153
	ds_bpermute_b32 v154, v196, v152
	v_mul_f32_e32 v156, 0x45800000, v168
	v_cndmask_b32_e64 v195, v168, v156, s[10:11]
	v_mov_b32_e32 v217, 0
	v_mul_f32_e32 v156, v125, v113
	s_waitcnt lgkmcnt(0)
	v_pk_add_f32 v[190:191], v[152:153], v[154:155]
	v_mov_b32_e32 v152, v111
	v_mov_b32_e32 v153, v195
	v_mul_f32_e32 v154, v124, v112
	v_pk_mul_f32 v[152:153], v[194:195], v[152:153]
	v_mul_f32_e32 v155, v120, v108
	v_mul_f32_e32 v154, v154, v153
	v_pk_mul_f32 v[222:223], v[152:153], v[152:153] op_sel:[0,1] op_sel_hi:[1,0]
	v_mov_b32_e32 v213, 0
	v_mov_b32_dpp v217, v154 row_ror:1 row_mask:0xf bank_mask:0xf
	v_cndmask_b32_e64 v152, v217, 0, s[0:1]
	v_mul_f32_e32 v157, v121, v109
	v_mul_f32_e32 v158, v126, v114
	v_mul_f32_e32 v159, v122, v110
	v_mul_f32_e32 v168, v127, v115
	v_mul_f32_e32 v194, v155, v153
	v_mul_f32_e32 v155, v156, v153
	v_mov_b32_dpp v213, v154 row_ror:2 row_mask:0xf bank_mask:0xf
	v_mov_b32_e32 v221, 0
	v_mul_f32_e32 v152, v144, v152
	v_mul_f32_e32 v208, v157, v153
	v_mul_f32_e32 v156, v158, v153
	v_mul_f32_e32 v159, v159, v153
	v_mul_f32_e32 v157, v168, v153
	v_mov_b32_dpp v221, v155 row_ror:1 row_mask:0xf bank_mask:0xf
	v_cndmask_b32_e64 v153, v213, 0, s[8:9]
	v_fmac_f32_e32 v152, v148, v154
	v_mov_b32_e32 v219, 0
	v_fmac_f32_e32 v152, v140, v153
	v_cndmask_b32_e64 v153, v221, 0, s[0:1]
	v_mov_b32_dpp v219, v155 row_ror:2 row_mask:0xf bank_mask:0xf
	v_mul_f32_e32 v153, v145, v153
	v_mov_b32_e32 v216, 0
	v_cndmask_b32_e64 v154, v219, 0, s[8:9]
	v_fmac_f32_e32 v153, v149, v155
	v_mov_b32_dpp v216, v156 row_ror:1 row_mask:0xf bank_mask:0xf
	v_fmac_f32_e32 v153, v141, v154
	v_mov_b32_e32 v212, 0
	v_cndmask_b32_e64 v154, v216, 0, s[0:1]
	v_mov_b32_e32 v220, 0
	v_mov_b32_dpp v212, v156 row_ror:2 row_mask:0xf bank_mask:0xf
	v_mul_f32_e32 v154, v146, v154
	v_mov_b32_dpp v220, v157 row_ror:1 row_mask:0xf bank_mask:0xf
	v_cndmask_b32_e64 v155, v212, 0, s[8:9]
	v_fmac_f32_e32 v154, v150, v156
	v_mov_b32_e32 v218, 0
	v_fmac_f32_e32 v154, v142, v155
	v_cndmask_b32_e64 v155, v220, 0, s[0:1]
	v_mov_b32_dpp v218, v157 row_ror:2 row_mask:0xf bank_mask:0xf
	v_mul_f32_e32 v155, v147, v155
	v_cndmask_b32_e64 v156, v218, 0, s[8:9]
	v_fmac_f32_e32 v155, v151, v157
	v_mov_b32_dpp v197, v194 row_ror:1 row_mask:0xf bank_mask:0xf
	v_fmac_f32_e32 v155, v143, v156
	v_mov_b32_e32 v189, 0
	v_cndmask_b32_e64 v156, v197, 0, s[0:1]
	v_mov_b32_e32 v214, 0
	v_mov_b32_dpp v189, v194 row_ror:2 row_mask:0xf bank_mask:0xf
	v_mul_f32_e32 v156, v132, v156
	v_mov_b32_dpp v214, v208 row_ror:1 row_mask:0xf bank_mask:0xf
	v_cndmask_b32_e64 v157, v189, 0, s[8:9]
	v_fmac_f32_e32 v156, v136, v194
	v_fmac_f32_e32 v156, v128, v157
	v_cndmask_b32_e64 v157, v214, 0, s[0:1]
	v_mov_b32_e32 v209, 0
	v_mul_f32_e32 v157, v133, v157
	v_fmac_f32_e32 v157, v137, v208
	v_mov_b32_dpp v209, v208 row_ror:2 row_mask:0xf bank_mask:0xf
	v_mov_b32_e32 v208, 0
	v_cndmask_b32_e64 v158, v209, 0, s[8:9]
	v_fmac_f32_e32 v157, v129, v158
	v_mov_b32_dpp v208, v159 row_ror:1 row_mask:0xf bank_mask:0xf
	v_mov_b32_e32 v194, 0
	v_cndmask_b32_e64 v158, v208, 0, s[0:1]
	ds_bpermute_b32 v193, v207, v191
	ds_bpermute_b32 v192, v207, v190
	v_mov_b32_dpp v194, v159 row_ror:2 row_mask:0xf bank_mask:0xf
	v_mov_b32_e32 v215, 0
	v_mul_f32_e32 v158, v134, v158
	v_cndmask_b32_e64 v168, v194, 0, s[8:9]
	v_mov_b32_dpp v215, v222 row_ror:1 row_mask:0xf bank_mask:0xf
	v_fmac_f32_e32 v158, v138, v159
	v_mov_b32_dpp v211, v222 row_ror:2 row_mask:0xf bank_mask:0xf
	v_fmac_f32_e32 v158, v130, v168
	v_cndmask_b32_e64 v168, v215, 0, s[0:1]
	v_mul_f32_e32 v159, v139, v222
	v_cndmask_b32_e64 v223, v211, 0, s[8:9]
	v_fmac_f32_e32 v159, v135, v168
	v_cmp_gt_f32_e32 vcc, s84, v188
	v_fmac_f32_e32 v159, v131, v223
	s_and_saveexec_b64 s[10:11], s[4:5]
	s_xor_b64 s[10:11], exec, s[10:11]
	s_cbranch_execz .LBB0_1056
	v_mul_f32_e32 v152, v195, v152
	v_mul_f32_e32 v153, v195, v153
	v_cvt_pk_bf16_f32 v152, v152, v153
	v_mul_f32_e32 v153, v195, v154
	v_mul_f32_e32 v154, v195, v155
	v_cvt_pk_bf16_f32 v153, v153, v154
	v_mul_f32_e32 v154, v195, v156
	v_mul_f32_e32 v155, v195, v157
	v_cvt_pk_bf16_f32 v154, v154, v155
	v_mul_f32_e32 v155, v195, v158
	v_mul_f32_e32 v156, v195, v159
	v_cvt_pk_bf16_f32 v155, v155, v156
	v_lshlrev_b64 v[156:157], 12, v[186:187]
	v_lshl_add_u64 v[156:157], s[18:19], 0, v[156:157]
	v_lshl_add_u64 v[156:157], v[178:179], 1, v[156:157]
	global_store_dwordx4 v[156:157], v[152:155], off

; #define PG8_STAGE(bufoff, gbase, voff) do { _Pragma("unroll") for (int _i = 0; _i < 2; ++_i) \
;     __builtin_amdgcn_global_load_lds((const unsigned*)((const char*)(gbase) + (voff)[_i]), (LAS unsigned*)(lds + (bufoff) + ldsw + _i * 8192), 16, 0, 0); } while (0)
; #define PG8_LDA(dst, b, h) do { _Pragma("unroll") for (int m = 0; m < 4; ++m) _Pragma("unroll") for (int k = 0; k < 2; ++k) dst[m][k] = *(const LAS bf16x8*)(lds + PG8_SA(b, h) + aoff + m * 2048 + k * 1024); } while (0)
; #define PG8_LDB(dst, b, h) do { _Pragma("unroll") for (int n = 0; n < 2; ++n) _Pragma("unroll") for (int k = 0; k < 2; ++k) dst[n][k] = *(const LAS bf16x8*)(lds + PG8_SB(b, h) + boff + n * 2048 + k * 1024); } while (0)
; #define PG8_MMA(ai, bj, At, Bt) do { __builtin_amdgcn_s_setprio(1); _Pragma("unroll") for (int m = 0; m < 4; ++m) _Pragma("unroll") for (int n = 0; n < 2; ++n) _Pragma("unroll") for (int k = 0; k < 2; ++k) \
;     acc[ai][bj][m][n] = __builtin_amdgcn_mfma_f32_16x16x32_bf16(Bt[n][k], At[m][k], acc[ai][bj][m][n], 0, 0, 0); __builtin_amdgcn_s_setprio(0); } while (0)
; #define PG8_WAIT_V(n) asm volatile("s_waitcnt vmcnt(" #n ")" ::: "memory")
; #define PG8_WAIT_L(n) asm volatile("s_waitcnt lgkmcnt(" #n ")" ::: "memory")
; #define PG8_BAR __builtin_amdgcn_s_barrier()
; #define PG8_SCHED __builtin_amdgcn_sched_barrier(0)
; template <class Epi, class Sched = StaticOrder>
; DI void gemm_phase(LAS unsigned char* lds, const Gemm g, const Sched& S, const Epi& E) {
;     ...
;     for (int t = 0; t < nt; t += 2) {
;       const bool last = (t == nt - 2);
;       const char* a1 = cA + (size_t)(t + 1) * kstep;
;       const char* a2 = last ? nA : cA + (size_t)(t + 2) * kstep; const char* b2 = last ? nB : cB + (size_t)(t + 2) * kstep;
;       const char* a3 = a2 + kstep; const char* b3 = b2 + kstep;
;       PG8_LDB(B0, 0, 0); PG8_SCHED; PG8_LDA(At, 0, 0); PG8_STAGE(PG8_SA(1, 1), a1 + hstep, voffA);
;       PG8_WAIT_L(8); PG8_BAR; PG8_WAIT_L(0); PG8_MMA(0, 0, At, B0); PG8_BAR; PG8_SCHED;
;       PG8_LDB(B1, 0, 1); PG8_STAGE(PG8_SB(0, 0), b2, voffB);
;       PG8_BAR; PG8_WAIT_L(0); PG8_MMA(0, 1, At, B1); PG8_BAR;
;       PG8_LDA(At, 0, 1); PG8_STAGE(PG8_SA(0, 0), a2, voffA);
;       PG8_BAR; PG8_WAIT_L(0); PG8_MMA(1, 0, At, B0); PG8_BAR; PG8_SCHED;
;       PG8_STAGE(PG8_SB(0, 1), b2 + hstep, voffB);
;       PG8_WAIT_V(6); PG8_BAR; PG8_MMA(1, 1, At, B1); PG8_BAR;
.LBB0_1194:
	ds_read_b128 v[128:131], v214
	ds_read_b128 v[132:135], v214 offset:1024
	ds_read_b128 v[136:139], v214 offset:2048
	ds_read_b128 v[140:143], v214 offset:3072
	s_add_u32 s24, s22, 0xfff80080
	s_addc_u32 s25, s23, -1
	s_cmp_eq_u32 s54, 28
	s_cselect_b32 s27, s17, s25
	s_cselect_b32 s26, s43, s24
	s_cselect_b32 s25, s15, s53
	s_cselect_b32 s24, s51, s52
	s_add_i32 m0, s37, 0xc000
	ds_read_b128 v[144:147], v215
	ds_read_b128 v[148:151], v215 offset:1024
	ds_read_b128 v[152:155], v215 offset:2048
	ds_read_b128 v[156:159], v215 offset:3072
	ds_read_b128 v[160:163], v215 offset:4096
	ds_read_b128 v[164:167], v215 offset:5120
	ds_read_b128 v[168:171], v215 offset:6144
	ds_read_b128 v[172:175], v215 offset:7168
	global_load_lds_dwordx4 v184, s[22:23]
	s_add_i32 m0, s37, 0xe000
	s_nop 0
	global_load_lds_dwordx4 v186, s[22:23]
	ds_read_b128 v[192:195], v216
	ds_read_b128 v[196:199], v216 offset:1024
	ds_read_b128 v[200:203], v216 offset:2048
	ds_read_b128 v[204:207], v216 offset:3072
	s_waitcnt vmcnt(8)
	s_waitcnt lgkmcnt(4)
	s_setprio 1
	s_barrier
	v_mfma_f32_16x16x32_bf16 v[124:127], v[128:131], v[144:147], v[124:127]
	v_mfma_f32_16x16x32_bf16 v[120:123], v[136:139], v[144:147], v[120:123]
	v_mfma_f32_16x16x32_bf16 v[108:111], v[128:131], v[152:155], v[108:111]
	v_mfma_f32_16x16x32_bf16 v[104:107], v[136:139], v[152:155], v[104:107]
	v_mfma_f32_16x16x32_bf16 v[92:95], v[128:131], v[160:163], v[92:95]
	v_mfma_f32_16x16x32_bf16 v[88:91], v[136:139], v[160:163], v[88:91]
	v_mfma_f32_16x16x32_bf16 v[76:79], v[128:131], v[168:171], v[76:79]
	v_mfma_f32_16x16x32_bf16 v[72:75], v[136:139], v[168:171], v[72:75]
	v_mfma_f32_16x16x32_bf16 v[124:127], v[132:135], v[148:151], v[124:127]
	v_mfma_f32_16x16x32_bf16 v[120:123], v[140:143], v[148:151], v[120:123]
	v_mfma_f32_16x16x32_bf16 v[108:111], v[132:135], v[156:159], v[108:111]
	v_mfma_f32_16x16x32_bf16 v[104:107], v[140:143], v[156:159], v[104:107]
	v_mfma_f32_16x16x32_bf16 v[92:95], v[132:135], v[164:167], v[92:95]
	v_mfma_f32_16x16x32_bf16 v[88:91], v[140:143], v[164:167], v[88:91]
	v_mfma_f32_16x16x32_bf16 v[76:79], v[132:135], v[172:175], v[76:79]
	v_mfma_f32_16x16x32_bf16 v[72:75], v[140:143], v[172:175], v[72:75]
	s_waitcnt lgkmcnt(0)
	v_mfma_f32_16x16x32_bf16 v[116:119], v[192:195], v[144:147], v[116:119]
	v_mfma_f32_16x16x32_bf16 v[112:115], v[200:203], v[144:147], v[112:115]
	v_mfma_f32_16x16x32_bf16 v[100:103], v[192:195], v[152:155], v[100:103]
	v_mfma_f32_16x16x32_bf16 v[96:99], v[200:203], v[152:155], v[96:99]
	v_mfma_f32_16x16x32_bf16 v[84:87], v[192:195], v[160:163], v[84:87]
	v_mfma_f32_16x16x32_bf16 v[80:83], v[200:203], v[160:163], v[80:83]
	v_mfma_f32_16x16x32_bf16 v[68:71], v[192:195], v[168:171], v[68:71]
	v_mfma_f32_16x16x32_bf16 v[64:67], v[200:203], v[168:171], v[64:67]
	v_mfma_f32_16x16x32_bf16 v[116:119], v[196:199], v[148:151], v[116:119]
	v_mfma_f32_16x16x32_bf16 v[112:115], v[204:207], v[148:151], v[112:115]
	v_mfma_f32_16x16x32_bf16 v[100:103], v[196:199], v[156:159], v[100:103]
	v_mfma_f32_16x16x32_bf16 v[96:99], v[204:207], v[156:159], v[96:99]
	v_mfma_f32_16x16x32_bf16 v[84:87], v[196:199], v[164:167], v[84:87]
	v_mfma_f32_16x16x32_bf16 v[80:83], v[204:207], v[164:167], v[80:83]
	v_mfma_f32_16x16x32_bf16 v[68:71], v[196:199], v[172:175], v[68:71]
	v_mfma_f32_16x16x32_bf16 v[64:67], v[204:207], v[172:175], v[64:67]
	s_barrier
	s_setprio 0
	s_add_i32 s55, s48, s35
	s_add_u32 s98, s24, 0x80
	s_addc_u32 s99, s25, 0
	s_add_u32 s100, s26, 0x80
	s_addc_u32 s101, s27, 0
	s_mov_b32 m0, s55
	s_nop 0
	global_load_lds_dwordx4 v180, s[24:25]
	s_add_i32 m0, s55, 0x2000
	s_nop 0
	global_load_lds_dwordx4 v176, s[24:25]
	s_mov_b32 m0, s37
	ds_read_b128 v[144:147], v215 offset:16384
	ds_read_b128 v[148:151], v215 offset:17408
	ds_read_b128 v[152:155], v215 offset:18432
	ds_read_b128 v[156:159], v215 offset:19456
	ds_read_b128 v[160:163], v215 offset:20480
	ds_read_b128 v[164:167], v215 offset:21504
	ds_read_b128 v[168:171], v215 offset:22528
	ds_read_b128 v[172:175], v215 offset:23552
	global_load_lds_dwordx4 v182, s[26:27]
	s_mov_b32 m0, s38
	s_nop 0
	global_load_lds_dwordx4 v178, s[26:27]
	s_add_u32 s56, s24, 0x80000
	s_addc_u32 s57, s25, 0
	s_add_i32 s55, s49, s35
	s_mov_b32 m0, s55
	s_nop 0
	global_load_lds_dwordx4 v180, s[56:57]
	s_add_i32 m0, s55, 0x2000
	s_nop 0
	global_load_lds_dwordx4 v176, s[56:57]
	s_waitcnt vmcnt(8)
	s_waitcnt lgkmcnt(0)
	s_setprio 1
	s_barrier
	v_mfma_f32_16x16x32_bf16 v[60:63], v[128:131], v[144:147], v[60:63]
	v_mfma_f32_16x16x32_bf16 v[56:59], v[136:139], v[144:147], v[56:59]
	v_mfma_f32_16x16x32_bf16 v[44:47], v[128:131], v[152:155], v[44:47]
	v_mfma_f32_16x16x32_bf16 v[40:43], v[136:139], v[152:155], v[40:43]
	v_mfma_f32_16x16x32_bf16 v[28:31], v[128:131], v[160:163], v[28:31]
	v_mfma_f32_16x16x32_bf16 v[24:27], v[136:139], v[160:163], v[24:27]
	v_mfma_f32_16x16x32_bf16 v[12:15], v[128:131], v[168:171], v[12:15]
	v_mfma_f32_16x16x32_bf16 v[8:11], v[136:139], v[168:171], v[8:11]
	v_mfma_f32_16x16x32_bf16 v[60:63], v[132:135], v[148:151], v[60:63]
	v_mfma_f32_16x16x32_bf16 v[56:59], v[140:143], v[148:151], v[56:59]
	v_mfma_f32_16x16x32_bf16 v[44:47], v[132:135], v[156:159], v[44:47]
	v_mfma_f32_16x16x32_bf16 v[40:43], v[140:143], v[156:159], v[40:43]
	v_mfma_f32_16x16x32_bf16 v[28:31], v[132:135], v[164:167], v[28:31]
	v_mfma_f32_16x16x32_bf16 v[24:27], v[140:143], v[164:167], v[24:27]
	v_mfma_f32_16x16x32_bf16 v[12:15], v[132:135], v[172:175], v[12:15]
	v_mfma_f32_16x16x32_bf16 v[8:11], v[140:143], v[172:175], v[8:11]
	v_mfma_f32_16x16x32_bf16 v[52:55], v[192:195], v[144:147], v[52:55]
	v_mfma_f32_16x16x32_bf16 v[48:51], v[200:203], v[144:147], v[48:51]
	v_mfma_f32_16x16x32_bf16 v[36:39], v[192:195], v[152:155], v[36:39]
	v_mfma_f32_16x16x32_bf16 v[32:35], v[200:203], v[152:155], v[32:35]
	v_mfma_f32_16x16x32_bf16 v[20:23], v[192:195], v[160:163], v[20:23]
	v_mfma_f32_16x16x32_bf16 v[16:19], v[200:203], v[160:163], v[16:19]
	v_mfma_f32_16x16x32_bf16 v[4:7], v[192:195], v[168:171], v[4:7]
	v_mfma_f32_16x16x32_bf16 v[0:3], v[200:203], v[168:171], v[0:3]
	v_mfma_f32_16x16x32_bf16 v[52:55], v[196:199], v[148:151], v[52:55]
	v_mfma_f32_16x16x32_bf16 v[48:51], v[204:207], v[148:151], v[48:51]
	v_mfma_f32_16x16x32_bf16 v[36:39], v[196:199], v[156:159], v[36:39]
	v_mfma_f32_16x16x32_bf16 v[32:35], v[204:207], v[156:159], v[32:35]
	v_mfma_f32_16x16x32_bf16 v[20:23], v[196:199], v[164:167], v[20:23]
	v_mfma_f32_16x16x32_bf16 v[16:19], v[204:207], v[164:167], v[16:19]
	v_mfma_f32_16x16x32_bf16 v[4:7], v[196:199], v[172:175], v[4:7]
	v_mfma_f32_16x16x32_bf16 v[0:3], v[204:207], v[172:175], v[0:3]
	s_barrier
; #define PG8_STAGE(bufoff, gbase, voff) do { _Pragma("unroll") for (int _i = 0; _i < 2; ++_i) \
;     __builtin_amdgcn_global_load_lds((const unsigned*)((const char*)(gbase) + (voff)[_i]), (LAS unsigned*)(lds + (bufoff) + ldsw + _i * 8192), 16, 0, 0); } while (0)
; #define PG8_LDA(dst, b, h) do { _Pragma("unroll") for (int m = 0; m < 4; ++m) _Pragma("unroll") for (int k = 0; k < 2; ++k) dst[m][k] = *(const LAS bf16x8*)(lds + PG8_SA(b, h) + aoff + m * 2048 + k * 1024); } while (0)
; #define PG8_LDB(dst, b, h) do { _Pragma("unroll") for (int n = 0; n < 2; ++n) _Pragma("unroll") for (int k = 0; k < 2; ++k) dst[n][k] = *(const LAS bf16x8*)(lds + PG8_SB(b, h) + boff + n * 2048 + k * 1024); } while (0)
; #define PG8_MMA(ai, bj, At, Bt) do { __builtin_amdgcn_s_setprio(1); _Pragma("unroll") for (int m = 0; m < 4; ++m) _Pragma("unroll") for (int n = 0; n < 2; ++n) _Pragma("unroll") for (int k = 0; k < 2; ++k) \
;     acc[ai][bj][m][n] = __builtin_amdgcn_mfma_f32_16x16x32_bf16(Bt[n][k], At[m][k], acc[ai][bj][m][n], 0, 0, 0); __builtin_amdgcn_s_setprio(0); } while (0)
; #define PG8_WAIT_V(n) asm volatile("s_waitcnt vmcnt(" #n ")" ::: "memory")
; #define PG8_WAIT_L(n) asm volatile("s_waitcnt lgkmcnt(" #n ")" ::: "memory")
; #define PG8_BAR __builtin_amdgcn_s_barrier()
; #define PG8_SCHED __builtin_amdgcn_sched_barrier(0)
; template <class Epi, class Sched = StaticOrder>
; DI void gemm_phase(LAS unsigned char* lds, const Gemm g, const Sched& S, const Epi& E) {
;     ...
;       PG8_LDB(B0, 1, 0); PG8_SCHED; PG8_LDA(At, 1, 0); PG8_STAGE(PG8_SA(0, 1), a2 + hstep, voffA);
;       PG8_WAIT_L(8); PG8_BAR; PG8_WAIT_L(0); PG8_MMA(0, 0, At, B0); PG8_BAR; PG8_SCHED;
;       PG8_LDB(B1, 1, 1); PG8_STAGE(PG8_SB(1, 0), b3, voffB);
;       PG8_BAR; PG8_WAIT_L(0); PG8_MMA(0, 1, At, B1); PG8_BAR;
;       PG8_LDA(At, 1, 1); PG8_STAGE(PG8_SA(1, 0), a3, voffA);
;       PG8_BAR; PG8_WAIT_L(0); PG8_MMA(1, 0, At, B0); PG8_BAR; PG8_SCHED;
;       PG8_STAGE(PG8_SB(1, 1), b3 + hstep, voffB);
;       PG8_WAIT_V(6); PG8_BAR; PG8_MMA(1, 1, At, B1); PG8_BAR;
	s_setprio 0
	s_add_i32 s55, 0, 0x18000
	v_add_u32_e32 v140, s55, v212
	ds_read_b128 v[128:131], v140
	ds_read_b128 v[132:135], v140 offset:1024
	ds_read_b128 v[136:139], v140 offset:2048
	ds_read_b128 v[140:143], v140 offset:3072
	s_add_u32 s26, s26, 0x80000
	s_addc_u32 s27, s27, 0
	s_mov_b32 m0, s39
	ds_read_b128 v[144:147], v215 offset:32768
	ds_read_b128 v[148:151], v215 offset:33792
	ds_read_b128 v[152:155], v215 offset:34816
	ds_read_b128 v[156:159], v215 offset:35840
	ds_read_b128 v[160:163], v215 offset:36864
	ds_read_b128 v[164:167], v215 offset:37888
	ds_read_b128 v[168:171], v215 offset:38912
	ds_read_b128 v[172:175], v215 offset:39936
	global_load_lds_dwordx4 v182, s[26:27]
	s_mov_b32 m0, s40
	s_nop 0
	global_load_lds_dwordx4 v178, s[26:27]
	s_add_i32 s26, 0, 0x1c000
	v_add_u32_e32 v204, s26, v212
	ds_read_b128 v[192:195], v204
	ds_read_b128 v[196:199], v204 offset:1024
	ds_read_b128 v[200:203], v204 offset:2048
	ds_read_b128 v[204:207], v204 offset:3072
	s_waitcnt vmcnt(8)
	s_waitcnt lgkmcnt(4)
	s_setprio 1
	s_barrier
	v_mfma_f32_16x16x32_bf16 v[124:127], v[128:131], v[144:147], v[124:127]
	v_mfma_f32_16x16x32_bf16 v[120:123], v[136:139], v[144:147], v[120:123]
	v_mfma_f32_16x16x32_bf16 v[108:111], v[128:131], v[152:155], v[108:111]
	v_mfma_f32_16x16x32_bf16 v[104:107], v[136:139], v[152:155], v[104:107]
	v_mfma_f32_16x16x32_bf16 v[92:95], v[128:131], v[160:163], v[92:95]
	v_mfma_f32_16x16x32_bf16 v[88:91], v[136:139], v[160:163], v[88:91]
	v_mfma_f32_16x16x32_bf16 v[76:79], v[128:131], v[168:171], v[76:79]
	v_mfma_f32_16x16x32_bf16 v[72:75], v[136:139], v[168:171], v[72:75]
	v_mfma_f32_16x16x32_bf16 v[124:127], v[132:135], v[148:151], v[124:127]
	v_mfma_f32_16x16x32_bf16 v[120:123], v[140:143], v[148:151], v[120:123]
	v_mfma_f32_16x16x32_bf16 v[108:111], v[132:135], v[156:159], v[108:111]
	v_mfma_f32_16x16x32_bf16 v[104:107], v[140:143], v[156:159], v[104:107]
	v_mfma_f32_16x16x32_bf16 v[92:95], v[132:135], v[164:167], v[92:95]
	v_mfma_f32_16x16x32_bf16 v[88:91], v[140:143], v[164:167], v[88:91]
	v_mfma_f32_16x16x32_bf16 v[76:79], v[132:135], v[172:175], v[76:79]
	v_mfma_f32_16x16x32_bf16 v[72:75], v[140:143], v[172:175], v[72:75]
	s_waitcnt lgkmcnt(0)
	v_mfma_f32_16x16x32_bf16 v[116:119], v[192:195], v[144:147], v[116:119]
	v_mfma_f32_16x16x32_bf16 v[112:115], v[200:203], v[144:147], v[112:115]
	v_mfma_f32_16x16x32_bf16 v[100:103], v[192:195], v[152:155], v[100:103]
	v_mfma_f32_16x16x32_bf16 v[96:99], v[200:203], v[152:155], v[96:99]
	v_mfma_f32_16x16x32_bf16 v[84:87], v[192:195], v[160:163], v[84:87]
	v_mfma_f32_16x16x32_bf16 v[80:83], v[200:203], v[160:163], v[80:83]
	v_mfma_f32_16x16x32_bf16 v[68:71], v[192:195], v[168:171], v[68:71]
	v_mfma_f32_16x16x32_bf16 v[64:67], v[200:203], v[168:171], v[64:67]
	v_mfma_f32_16x16x32_bf16 v[116:119], v[196:199], v[148:151], v[116:119]
	v_mfma_f32_16x16x32_bf16 v[112:115], v[204:207], v[148:151], v[112:115]
	v_mfma_f32_16x16x32_bf16 v[100:103], v[196:199], v[156:159], v[100:103]
	v_mfma_f32_16x16x32_bf16 v[96:99], v[204:207], v[156:159], v[96:99]
	v_mfma_f32_16x16x32_bf16 v[84:87], v[196:199], v[164:167], v[84:87]
	v_mfma_f32_16x16x32_bf16 v[80:83], v[204:207], v[164:167], v[80:83]
	v_mfma_f32_16x16x32_bf16 v[68:71], v[196:199], v[172:175], v[68:71]
	v_mfma_f32_16x16x32_bf16 v[64:67], v[204:207], v[172:175], v[64:67]
	s_barrier
	s_setprio 0
	s_add_i32 s27, s55, s35
	s_mov_b32 m0, s27
	s_nop 0
	global_load_lds_dwordx4 v180, s[98:99]
	s_add_i32 m0, s27, 0x2000
	s_nop 0
	global_load_lds_dwordx4 v176, s[98:99]
	s_mov_b32 m0, s44
	ds_read_b128 v[144:147], v215 offset:49152
	ds_read_b128 v[148:151], v215 offset:50176
	ds_read_b128 v[152:155], v215 offset:51200
	ds_read_b128 v[156:159], v215 offset:52224
	ds_read_b128 v[160:163], v215 offset:53248
	ds_read_b128 v[164:167], v215 offset:54272
	ds_read_b128 v[168:171], v215 offset:55296
	ds_read_b128 v[172:175], v215 offset:56320
	global_load_lds_dwordx4 v182, s[100:101]
	s_mov_b32 m0, s45
	s_nop 0
	global_load_lds_dwordx4 v178, s[100:101]
	s_add_u32 s24, s24, 0x80080
	s_addc_u32 s25, s25, 0
	s_add_i32 s26, s26, s35
	s_mov_b32 m0, s26
	s_nop 0
	global_load_lds_dwordx4 v180, s[24:25]
	s_add_i32 m0, s26, 0x2000
	s_nop 0
	global_load_lds_dwordx4 v176, s[24:25]
	s_add_i32 s54, s54, 2
	s_add_u32 s22, s22, 0x100
	s_addc_u32 s23, s23, 0
	s_add_u32 s52, s52, 0x100
	s_addc_u32 s53, s53, 0
	s_cmp_gt_u32 s54, 29
	s_waitcnt vmcnt(8)
	s_waitcnt lgkmcnt(0)
	s_setprio 1
	s_barrier
	v_mfma_f32_16x16x32_bf16 v[60:63], v[128:131], v[144:147], v[60:63]
	v_mfma_f32_16x16x32_bf16 v[56:59], v[136:139], v[144:147], v[56:59]
	v_mfma_f32_16x16x32_bf16 v[44:47], v[128:131], v[152:155], v[44:47]
	v_mfma_f32_16x16x32_bf16 v[40:43], v[136:139], v[152:155], v[40:43]
	v_mfma_f32_16x16x32_bf16 v[28:31], v[128:131], v[160:163], v[28:31]
	v_mfma_f32_16x16x32_bf16 v[24:27], v[136:139], v[160:163], v[24:27]
	v_mfma_f32_16x16x32_bf16 v[12:15], v[128:131], v[168:171], v[12:15]
	v_mfma_f32_16x16x32_bf16 v[8:11], v[136:139], v[168:171], v[8:11]
	v_mfma_f32_16x16x32_bf16 v[60:63], v[132:135], v[148:151], v[60:63]
	v_mfma_f32_16x16x32_bf16 v[56:59], v[140:143], v[148:151], v[56:59]
	v_mfma_f32_16x16x32_bf16 v[44:47], v[132:135], v[156:159], v[44:47]
	v_mfma_f32_16x16x32_bf16 v[40:43], v[140:143], v[156:159], v[40:43]
	v_mfma_f32_16x16x32_bf16 v[28:31], v[132:135], v[164:167], v[28:31]
	v_mfma_f32_16x16x32_bf16 v[24:27], v[140:143], v[164:167], v[24:27]
	v_mfma_f32_16x16x32_bf16 v[12:15], v[132:135], v[172:175], v[12:15]
	v_mfma_f32_16x16x32_bf16 v[8:11], v[140:143], v[172:175], v[8:11]
	v_mfma_f32_16x16x32_bf16 v[52:55], v[192:195], v[144:147], v[52:55]
	v_mfma_f32_16x16x32_bf16 v[48:51], v[200:203], v[144:147], v[48:51]
	v_mfma_f32_16x16x32_bf16 v[36:39], v[192:195], v[152:155], v[36:39]
	v_mfma_f32_16x16x32_bf16 v[32:35], v[200:203], v[152:155], v[32:35]
	v_mfma_f32_16x16x32_bf16 v[20:23], v[192:195], v[160:163], v[20:23]
	v_mfma_f32_16x16x32_bf16 v[16:19], v[200:203], v[160:163], v[16:19]
	v_mfma_f32_16x16x32_bf16 v[4:7], v[192:195], v[168:171], v[4:7]
	v_mfma_f32_16x16x32_bf16 v[0:3], v[200:203], v[168:171], v[0:3]
	v_mfma_f32_16x16x32_bf16 v[52:55], v[196:199], v[148:151], v[52:55]
	v_mfma_f32_16x16x32_bf16 v[48:51], v[204:207], v[148:151], v[48:51]
	v_mfma_f32_16x16x32_bf16 v[36:39], v[196:199], v[156:159], v[36:39]
	v_mfma_f32_16x16x32_bf16 v[32:35], v[204:207], v[156:159], v[32:35]
	v_mfma_f32_16x16x32_bf16 v[20:23], v[196:199], v[164:167], v[20:23]
	v_mfma_f32_16x16x32_bf16 v[16:19], v[204:207], v[164:167], v[16:19]
	v_mfma_f32_16x16x32_bf16 v[4:7], v[196:199], v[172:175], v[4:7]
	v_mfma_f32_16x16x32_bf16 v[0:3], v[204:207], v[172:175], v[0:3]
	s_barrier
; DI unsigned pack2(float lo, float hi) { f32x2 v = {lo, hi}; bf16v2 r = __builtin_convertvector(v, bf16v2); return __builtin_bit_cast(unsigned, r); }
;   DI void operator()(const f32x4 (&acc)[2][2][4][2], const Unit& u, int wr, int wc, int fr, int fq) const {
;     const int row0 = u.pm * BM + wr * 64 + fr, col0 = u.pn * BM + wc * 32 + 8 * fq;
; #pragma unroll
;     for (int ai = 0; ai < 2; ++ai) {
;       f32x4 bv[4][2][2];
; #pragma unroll
;       for (int m = 0; m < 4; ++m)
; #pragma unroll
;         for (int bj = 0; bj < 2; ++bj) {
;           const float* bp = base + (size_t)(row0 + ai * HALF + m * 16) * 2048 + col0 + bj * HALF;
;           bv[m][bj][0] = *(const f32x4*)bp; bv[m][bj][1] = *(const f32x4*)(bp + 4);
;         }
; #pragma unroll
;       for (int m = 0; m < 4; ++m) {
;         const int row = row0 + ai * HALF + m * 16;
;         const size_t off = (size_t)row * 2048 + col0;
;         float ss = 0.f;
; #pragma unroll
;         for (int bj = 0; bj < 2; ++bj) {
;           const f32x4 v0 = acc[ai][bj][m][0] + bv[m][bj][0], v1 = acc[ai][bj][m][1] + bv[m][bj][1];
;           *(f32x4*)(C + off + bj * HALF) = v0; *(f32x4*)(C + off + bj * HALF + 4) = v1;
;           if (xb) {
;             u32x4 w; w.x = pack2(v0[0], v0[1]); w.y = pack2(v0[2], v0[3]); w.z = pack2(v1[0], v1[1]); w.w = pack2(v1[2], v1[3]);
;             *(u32x4*)(xb + off + bj * HALF) = w;
;             ss += v0[0] * v0[0] + v0[1] * v0[1] + v0[2] * v0[2] + v0[3] * v0[3] + v1[0] * v1[0] + v1[1] * v1[1] + v1[2] * v1[2] + v1[3] * v1[3];
;           }
;         }
;         if (xb) {
;           ss += __shfl_xor(ss, 16); ss += __shfl_xor(ss, 32);
;           if (fq == 0) ssq[(size_t)row * 32 + u.pn * 4 + wc] = ss;
;         }
	s_setprio 0
	s_cbranch_scc0 .LBB0_1194
	v_lshl_add_u32 v194, s12, 8, v211
	v_lshl_or_b32 v192, s42, 8, v213
	v_readlane_b32 s52, v243, 3
	v_ashrrev_i32_e32 v193, 31, v192
	v_readlane_b32 s66, v243, 17
	v_readlane_b32 s67, v243, 18
	v_ashrrev_i32_e32 v195, 31, v194
	v_lshlrev_b64 v[128:129], 13, v[194:195]
	v_lshl_add_u64 v[196:197], v[192:193], 2, s[66:67]
	v_lshl_add_u64 v[236:237], v[196:197], 0, v[128:129]
	global_load_dwordx4 v[220:223], v[236:237], off
	global_load_dwordx4 v[224:227], v[236:237], off offset:16
	global_load_dwordx4 v[228:231], v[236:237], off offset:512
	global_load_dwordx4 v[232:235], v[236:237], off offset:528
	v_or_b32_e32 v206, 16, v194
	v_or_b32_e32 v202, 32, v194
	v_or_b32_e32 v198, 48, v194
	v_ashrrev_i32_e32 v207, 31, v206
	v_ashrrev_i32_e32 v203, 31, v202
	v_ashrrev_i32_e32 v199, 31, v198
	v_lshlrev_b64 v[128:129], 13, v[206:207]
	v_lshlrev_b64 v[130:131], 13, v[202:203]
	v_lshlrev_b64 v[132:133], 13, v[198:199]
	v_lshl_add_u64 v[208:209], v[196:197], 0, v[128:129]
	v_lshl_add_u64 v[204:205], v[196:197], 0, v[130:131]
	v_lshl_add_u64 v[200:201], v[196:197], 0, v[132:133]
	global_load_dwordx4 v[168:171], v[208:209], off offset:16
	global_load_dwordx4 v[172:175], v[208:209], off
	global_load_dwordx4 v[160:163], v[208:209], off offset:528
	global_load_dwordx4 v[164:167], v[208:209], off offset:512
	global_load_dwordx4 v[152:155], v[204:205], off offset:16
	global_load_dwordx4 v[156:159], v[204:205], off
	global_load_dwordx4 v[144:147], v[204:205], off offset:528
	global_load_dwordx4 v[148:151], v[204:205], off offset:512
	global_load_dwordx4 v[136:139], v[200:201], off offset:16
	global_load_dwordx4 v[140:143], v[200:201], off
	global_load_dwordx4 v[128:131], v[200:201], off offset:528
	global_load_dwordx4 v[132:135], v[200:201], off offset:512
	v_and_b32_e32 v218, 64, v217
	v_xor_b32_e32 v238, 16, v217
	v_add_u32_e32 v240, 64, v218
	v_xor_b32_e32 v239, 32, v217
	v_cmp_lt_i32_e32 vcc, v238, v240
	v_lshlrev_b64 v[218:219], 11, v[194:195]
	s_lshl_b32 s22, s42, 2
	v_cndmask_b32_e32 v241, v217, v238, vcc
	v_cmp_lt_i32_e32 vcc, v239, v240
	s_ashr_i32 s23, s22, 31
	v_readlane_b32 s53, v243, 4
	v_cndmask_b32_e32 v240, v217, v239, vcc
	v_lshl_add_u64 v[238:239], v[218:219], 0, v[192:193]
	v_lshlrev_b32_e32 v218, 2, v241
	v_lshl_add_u64 v[238:239], v[238:239], 1, s[2:3]
	v_readlane_b32 s54, v243, 5
	v_readlane_b32 s55, v243, 6
	v_readlane_b32 s56, v243, 7
	v_readlane_b32 s57, v243, 8
	v_readlane_b32 s58, v243, 9
	v_readlane_b32 s59, v243, 10
	v_readlane_b32 s60, v243, 11
	v_readlane_b32 s61, v243, 12
	v_readlane_b32 s62, v243, 13
	v_readlane_b32 s63, v243, 14
	v_readlane_b32 s64, v243, 15
	v_readlane_b32 s65, v243, 16
	s_waitcnt vmcnt(0)
	v_pk_add_f32 v[126:127], v[126:127], v[222:223]
	v_pk_add_f32 v[124:125], v[124:125], v[220:221]
	v_pk_add_f32 v[116:117], v[116:117], v[228:229]
	v_pk_add_f32 v[122:123], v[122:123], v[226:227]
	v_pk_add_f32 v[120:121], v[120:121], v[224:225]
	v_pk_add_f32 v[220:221], v[112:113], v[232:233]
	global_store_dwordx4 v[236:237], v[124:127], off
	global_store_dwordx4 v[236:237], v[120:123], off offset:16
	v_cvt_pk_bf16_f32 v112, v124, v125
	v_mul_f32_e32 v125, v125, v125
	v_mul_f32_e32 v219, v117, v117
	v_pk_add_f32 v[118:119], v[118:119], v[230:231]
	v_fmac_f32_e32 v125, v124, v124
	v_fmac_f32_e32 v219, v116, v116
	v_fmac_f32_e32 v125, v126, v126
	v_fmac_f32_e32 v219, v118, v118
	v_fmac_f32_e32 v125, v127, v127
	v_fmac_f32_e32 v219, v119, v119
	v_fmac_f32_e32 v125, v120, v120
	v_fmac_f32_e32 v219, v220, v220
	v_pk_add_f32 v[222:223], v[114:115], v[234:235]
	v_fmac_f32_e32 v125, v121, v121
	v_fmac_f32_e32 v219, v221, v221
	v_fmac_f32_e32 v125, v122, v122
	v_fmac_f32_e32 v219, v222, v222
	v_fmac_f32_e32 v125, v123, v123
	v_fmac_f32_e32 v219, v223, v223
	v_cvt_pk_bf16_f32 v114, v120, v121
	v_add_f32_e32 v121, v125, v219
	v_cvt_pk_bf16_f32 v115, v122, v123
	ds_bpermute_b32 v122, v218, v121
	v_cvt_pk_bf16_f32 v113, v126, v127
	global_store_dwordx4 v[238:239], v[112:115], off
	global_store_dwordx4 v[236:237], v[116:119], off offset:512
	global_store_dwordx4 v[236:237], v[220:223], off offset:528
	v_lshlrev_b32_e32 v126, 2, v240
	v_cvt_pk_bf16_f32 v120, v116, v117
	s_waitcnt lgkmcnt(0)
	v_add_f32_e32 v112, v121, v122
	ds_bpermute_b32 v113, v126, v112
	v_cvt_pk_bf16_f32 v121, v118, v119
	v_cvt_pk_bf16_f32 v122, v220, v221
	v_cvt_pk_bf16_f32 v123, v222, v223
	global_store_dwordx4 v[238:239], v[120:123], off offset:256
	s_and_saveexec_b64 s[24:25], s[0:1]
	s_cbranch_execz .LBB0_1197
	s_waitcnt lgkmcnt(0)
	v_add_f32_e32 v114, v112, v113
	v_lshlrev_b64 v[112:113], 7, v[194:195]
	v_lshl_add_u64 v[112:113], s[8:9], 0, v[112:113]
	v_lshl_add_u64 v[112:113], s[22:23], 2, v[112:113]
	s_lshl_b32 s12, s41, 2
	v_lshl_add_u64 v[112:113], v[112:113], 0, s[12:13]
	global_store_dword v[112:113], v114, off

; #define PG8_STAGE(bufoff, gbase, voff) do { _Pragma("unroll") for (int _i = 0; _i < 2; ++_i) \
;     __builtin_amdgcn_global_load_lds((const unsigned*)((const char*)(gbase) + (voff)[_i]), (LAS unsigned*)(lds + (bufoff) + ldsw + _i * 8192), 16, 0, 0); } while (0)
; #define PG8_LDA(dst, b, h) do { _Pragma("unroll") for (int m = 0; m < 4; ++m) _Pragma("unroll") for (int k = 0; k < 2; ++k) dst[m][k] = *(const LAS bf16x8*)(lds + PG8_SA(b, h) + aoff + m * 2048 + k * 1024); } while (0)
; #define PG8_LDB(dst, b, h) do { _Pragma("unroll") for (int n = 0; n < 2; ++n) _Pragma("unroll") for (int k = 0; k < 2; ++k) dst[n][k] = *(const LAS bf16x8*)(lds + PG8_SB(b, h) + boff + n * 2048 + k * 1024); } while (0)
; #define PG8_MMA(ai, bj, At, Bt) do { __builtin_amdgcn_s_setprio(1); _Pragma("unroll") for (int m = 0; m < 4; ++m) _Pragma("unroll") for (int n = 0; n < 2; ++n) _Pragma("unroll") for (int k = 0; k < 2; ++k) \
;     acc[ai][bj][m][n] = __builtin_amdgcn_mfma_f32_16x16x32_bf16(Bt[n][k], At[m][k], acc[ai][bj][m][n], 0, 0, 0); __builtin_amdgcn_s_setprio(0); } while (0)
; #define PG8_WAIT_V(n) asm volatile("s_waitcnt vmcnt(" #n ")" ::: "memory")
; #define PG8_WAIT_L(n) asm volatile("s_waitcnt lgkmcnt(" #n ")" ::: "memory")
; #define PG8_BAR __builtin_amdgcn_s_barrier()
; #define PG8_SCHED __builtin_amdgcn_sched_barrier(0)
; template <class Epi, class Sched = StaticOrder>
; DI void gemm_phase(LAS unsigned char* lds, const Gemm g, const Sched& S, const Epi& E) {
;     ...
;     for (int t = 0; t < nt; t += 2) {
;       const bool last = (t == nt - 2);
;       const char* a1 = cA + (size_t)(t + 1) * kstep;
;       const char* a2 = last ? nA : cA + (size_t)(t + 2) * kstep; const char* b2 = last ? nB : cB + (size_t)(t + 2) * kstep;
;       const char* a3 = a2 + kstep; const char* b3 = b2 + kstep;
;       PG8_LDB(B0, 0, 0); PG8_SCHED; PG8_LDA(At, 0, 0); PG8_STAGE(PG8_SA(1, 1), a1 + hstep, voffA);
;       PG8_WAIT_L(8); PG8_BAR; PG8_WAIT_L(0); PG8_MMA(0, 0, At, B0); PG8_BAR; PG8_SCHED;
;       PG8_LDB(B1, 0, 1); PG8_STAGE(PG8_SB(0, 0), b2, voffB);
;       PG8_BAR; PG8_WAIT_L(0); PG8_MMA(0, 1, At, B1); PG8_BAR;
;       PG8_LDA(At, 0, 1); PG8_STAGE(PG8_SA(0, 0), a2, voffA);
;       PG8_BAR; PG8_WAIT_L(0); PG8_MMA(1, 0, At, B0); PG8_BAR; PG8_SCHED;
;       PG8_STAGE(PG8_SB(0, 1), b2 + hstep, voffB);
;       PG8_WAIT_V(6); PG8_BAR; PG8_MMA(1, 1, At, B1); PG8_BAR;
.LBB0_1277:
	ds_read_b128 v[64:67], v201
	ds_read_b128 v[68:71], v201 offset:1024
	ds_read_b128 v[72:75], v201 offset:2048
	ds_read_b128 v[76:79], v201 offset:3072
	s_add_u32 s48, s14, 0xfff80080
	s_addc_u32 s49, s15, -1
	s_cmp_eq_u32 s58, 28
	s_cselect_b32 s51, s41, s49
	s_cselect_b32 s50, s42, s48
	s_cselect_b32 s49, s39, s53
	s_cselect_b32 s48, s43, s52
	s_add_i32 m0, s64, 0xc000
	ds_read_b128 v[80:83], v202
	ds_read_b128 v[84:87], v202 offset:1024
	ds_read_b128 v[88:91], v202 offset:2048
	ds_read_b128 v[92:95], v202 offset:3072
	ds_read_b128 v[180:183], v202 offset:4096
	ds_read_b128 v[184:187], v202 offset:5120
	ds_read_b128 v[188:191], v202 offset:6144
	ds_read_b128 v[192:195], v202 offset:7168
	global_load_lds_dwordx4 v170, s[14:15]
	s_add_i32 m0, s64, 0xe000
	s_nop 0
	global_load_lds_dwordx4 v172, s[14:15]
	ds_read_b128 v[206:209], v203
	ds_read_b128 v[212:215], v203 offset:1024
	ds_read_b128 v[216:219], v203 offset:2048
	ds_read_b128 v[220:223], v203 offset:3072
	s_waitcnt vmcnt(8)
	s_waitcnt lgkmcnt(4)
	s_setprio 1
	s_barrier
	v_mfma_f32_16x16x32_bf16 v[156:159], v[64:67], v[80:83], v[156:159]
	v_mfma_f32_16x16x32_bf16 v[144:147], v[72:75], v[80:83], v[144:147]
	v_mfma_f32_16x16x32_bf16 v[140:143], v[64:67], v[88:91], v[140:143]
	v_mfma_f32_16x16x32_bf16 v[132:135], v[72:75], v[88:91], v[132:135]
	v_mfma_f32_16x16x32_bf16 v[124:127], v[64:67], v[180:183], v[124:127]
	v_mfma_f32_16x16x32_bf16 v[116:119], v[72:75], v[180:183], v[116:119]
	v_mfma_f32_16x16x32_bf16 v[112:115], v[64:67], v[188:191], v[112:115]
	v_mfma_f32_16x16x32_bf16 v[108:111], v[72:75], v[188:191], v[108:111]
	v_mfma_f32_16x16x32_bf16 v[156:159], v[68:71], v[84:87], v[156:159]
	v_mfma_f32_16x16x32_bf16 v[144:147], v[76:79], v[84:87], v[144:147]
	v_mfma_f32_16x16x32_bf16 v[140:143], v[68:71], v[92:95], v[140:143]
	v_mfma_f32_16x16x32_bf16 v[132:135], v[76:79], v[92:95], v[132:135]
	v_mfma_f32_16x16x32_bf16 v[124:127], v[68:71], v[184:187], v[124:127]
	v_mfma_f32_16x16x32_bf16 v[116:119], v[76:79], v[184:187], v[116:119]
	v_mfma_f32_16x16x32_bf16 v[112:115], v[68:71], v[192:195], v[112:115]
	v_mfma_f32_16x16x32_bf16 v[108:111], v[76:79], v[192:195], v[108:111]
	s_waitcnt lgkmcnt(0)
	v_mfma_f32_16x16x32_bf16 v[152:155], v[206:209], v[80:83], v[152:155]
	v_mfma_f32_16x16x32_bf16 v[80:83], v[216:219], v[80:83], v[148:151]
	v_mfma_f32_16x16x32_bf16 v[152:155], v[212:215], v[84:87], v[152:155]
	v_mfma_f32_16x16x32_bf16 v[80:83], v[220:223], v[84:87], v[80:83]
	v_mfma_f32_16x16x32_bf16 v[84:87], v[206:209], v[88:91], v[136:139]
	v_mfma_f32_16x16x32_bf16 v[88:91], v[216:219], v[88:91], v[128:131]
	v_mfma_f32_16x16x32_bf16 v[104:107], v[216:219], v[180:183], v[104:107]
	v_mfma_f32_16x16x32_bf16 v[100:103], v[206:209], v[188:191], v[100:103]
	v_mfma_f32_16x16x32_bf16 v[96:99], v[216:219], v[188:191], v[96:99]
	v_mfma_f32_16x16x32_bf16 v[84:87], v[212:215], v[92:95], v[84:87]
	v_mfma_f32_16x16x32_bf16 v[88:91], v[220:223], v[92:95], v[88:91]
	v_mfma_f32_16x16x32_bf16 v[92:95], v[206:209], v[180:183], v[120:123]
	v_mfma_f32_16x16x32_bf16 v[104:107], v[220:223], v[184:187], v[104:107]
	v_mfma_f32_16x16x32_bf16 v[100:103], v[212:215], v[192:195], v[100:103]
	v_mfma_f32_16x16x32_bf16 v[96:99], v[220:223], v[192:195], v[96:99]
	v_mfma_f32_16x16x32_bf16 v[92:95], v[212:215], v[184:187], v[92:95]
	s_barrier
	s_setprio 0
	s_add_i32 s59, s72, s62
	s_add_u32 s98, s48, 0x80
	s_addc_u32 s99, s49, 0
	s_add_u32 s100, s50, 0x80
	s_addc_u32 s101, s51, 0
	s_mov_b32 m0, s59
	s_nop 0
	global_load_lds_dwordx4 v164, s[48:49]
	s_add_i32 m0, s59, 0x2000
	s_nop 0
	global_load_lds_dwordx4 v160, s[48:49]
	s_mov_b32 m0, s64
	ds_read_b128 v[120:123], v202 offset:16384
	ds_read_b128 v[128:131], v202 offset:17408
	ds_read_b128 v[136:139], v202 offset:18432
	ds_read_b128 v[148:151], v202 offset:19456
	ds_read_b128 v[180:183], v202 offset:20480
	ds_read_b128 v[184:187], v202 offset:21504
	ds_read_b128 v[188:191], v202 offset:22528
	ds_read_b128 v[192:195], v202 offset:23552
	global_load_lds_dwordx4 v166, s[50:51]
	s_mov_b32 m0, s65
	s_nop 0
	global_load_lds_dwordx4 v162, s[50:51]
	s_add_u32 s78, s48, 0x80000
	s_addc_u32 s79, s49, 0
	s_add_i32 s59, s73, s62
	s_mov_b32 m0, s59
	s_nop 0
	global_load_lds_dwordx4 v164, s[78:79]
	s_add_i32 m0, s59, 0x2000
	s_nop 0
	global_load_lds_dwordx4 v160, s[78:79]
	s_waitcnt vmcnt(8)
	s_waitcnt lgkmcnt(0)
	s_setprio 1
	s_barrier
	v_mfma_f32_16x16x32_bf16 v[60:63], v[64:67], v[120:123], v[60:63]
	v_mfma_f32_16x16x32_bf16 v[48:51], v[72:75], v[120:123], v[48:51]
	v_mfma_f32_16x16x32_bf16 v[44:47], v[64:67], v[136:139], v[44:47]
	v_mfma_f32_16x16x32_bf16 v[36:39], v[72:75], v[136:139], v[36:39]
	v_mfma_f32_16x16x32_bf16 v[28:31], v[64:67], v[180:183], v[28:31]
	v_mfma_f32_16x16x32_bf16 v[20:23], v[72:75], v[180:183], v[20:23]
	v_mfma_f32_16x16x32_bf16 v[16:19], v[64:67], v[188:191], v[16:19]
	v_mfma_f32_16x16x32_bf16 v[12:15], v[72:75], v[188:191], v[12:15]
	v_mfma_f32_16x16x32_bf16 v[60:63], v[68:71], v[128:131], v[60:63]
	v_mfma_f32_16x16x32_bf16 v[48:51], v[76:79], v[128:131], v[48:51]
	v_mfma_f32_16x16x32_bf16 v[44:47], v[68:71], v[148:151], v[44:47]
	v_mfma_f32_16x16x32_bf16 v[36:39], v[76:79], v[148:151], v[36:39]
	v_mfma_f32_16x16x32_bf16 v[28:31], v[68:71], v[184:187], v[28:31]
	v_mfma_f32_16x16x32_bf16 v[20:23], v[76:79], v[184:187], v[20:23]
	v_mfma_f32_16x16x32_bf16 v[16:19], v[68:71], v[192:195], v[16:19]
	v_mfma_f32_16x16x32_bf16 v[12:15], v[76:79], v[192:195], v[12:15]
	v_mfma_f32_16x16x32_bf16 v[56:59], v[206:209], v[120:123], v[56:59]
	v_mfma_f32_16x16x32_bf16 v[52:55], v[216:219], v[120:123], v[52:55]
	v_mfma_f32_16x16x32_bf16 v[40:43], v[206:209], v[136:139], v[40:43]
	v_mfma_f32_16x16x32_bf16 v[32:35], v[216:219], v[136:139], v[32:35]
	v_mfma_f32_16x16x32_bf16 v[24:27], v[206:209], v[180:183], v[24:27]
	v_mfma_f32_16x16x32_bf16 v[8:11], v[216:219], v[180:183], v[8:11]
	v_mfma_f32_16x16x32_bf16 v[4:7], v[206:209], v[188:191], v[4:7]
	v_mfma_f32_16x16x32_bf16 v[0:3], v[216:219], v[188:191], v[0:3]
	v_mfma_f32_16x16x32_bf16 v[56:59], v[212:215], v[128:131], v[56:59]
	v_mfma_f32_16x16x32_bf16 v[52:55], v[220:223], v[128:131], v[52:55]
	v_mfma_f32_16x16x32_bf16 v[40:43], v[212:215], v[148:151], v[40:43]
	v_mfma_f32_16x16x32_bf16 v[32:35], v[220:223], v[148:151], v[32:35]
	v_mfma_f32_16x16x32_bf16 v[24:27], v[212:215], v[184:187], v[24:27]
	v_mfma_f32_16x16x32_bf16 v[8:11], v[220:223], v[184:187], v[8:11]
	v_mfma_f32_16x16x32_bf16 v[4:7], v[212:215], v[192:195], v[4:7]
	v_mfma_f32_16x16x32_bf16 v[0:3], v[220:223], v[192:195], v[0:3]
	s_barrier
; #define PG8_STAGE(bufoff, gbase, voff) do { _Pragma("unroll") for (int _i = 0; _i < 2; ++_i) \
;     __builtin_amdgcn_global_load_lds((const unsigned*)((const char*)(gbase) + (voff)[_i]), (LAS unsigned*)(lds + (bufoff) + ldsw + _i * 8192), 16, 0, 0); } while (0)
; #define PG8_LDA(dst, b, h) do { _Pragma("unroll") for (int m = 0; m < 4; ++m) _Pragma("unroll") for (int k = 0; k < 2; ++k) dst[m][k] = *(const LAS bf16x8*)(lds + PG8_SA(b, h) + aoff + m * 2048 + k * 1024); } while (0)
; #define PG8_LDB(dst, b, h) do { _Pragma("unroll") for (int n = 0; n < 2; ++n) _Pragma("unroll") for (int k = 0; k < 2; ++k) dst[n][k] = *(const LAS bf16x8*)(lds + PG8_SB(b, h) + boff + n * 2048 + k * 1024); } while (0)
; #define PG8_MMA(ai, bj, At, Bt) do { __builtin_amdgcn_s_setprio(1); _Pragma("unroll") for (int m = 0; m < 4; ++m) _Pragma("unroll") for (int n = 0; n < 2; ++n) _Pragma("unroll") for (int k = 0; k < 2; ++k) \
;     acc[ai][bj][m][n] = __builtin_amdgcn_mfma_f32_16x16x32_bf16(Bt[n][k], At[m][k], acc[ai][bj][m][n], 0, 0, 0); __builtin_amdgcn_s_setprio(0); } while (0)
; #define PG8_WAIT_V(n) asm volatile("s_waitcnt vmcnt(" #n ")" ::: "memory")
; #define PG8_WAIT_L(n) asm volatile("s_waitcnt lgkmcnt(" #n ")" ::: "memory")
; #define PG8_BAR __builtin_amdgcn_s_barrier()
; #define PG8_SCHED __builtin_amdgcn_sched_barrier(0)
; template <class Epi, class Sched = StaticOrder>
; DI void gemm_phase(LAS unsigned char* lds, const Gemm g, const Sched& S, const Epi& E) {
;     ...
;       PG8_LDB(B0, 1, 0); PG8_SCHED; PG8_LDA(At, 1, 0); PG8_STAGE(PG8_SA(0, 1), a2 + hstep, voffA);
;       PG8_WAIT_L(8); PG8_BAR; PG8_WAIT_L(0); PG8_MMA(0, 0, At, B0); PG8_BAR; PG8_SCHED;
;       PG8_LDB(B1, 1, 1); PG8_STAGE(PG8_SB(1, 0), b3, voffB);
;       PG8_BAR; PG8_WAIT_L(0); PG8_MMA(0, 1, At, B1); PG8_BAR;
;       PG8_LDA(At, 1, 1); PG8_STAGE(PG8_SA(1, 0), a3, voffA);
;       PG8_BAR; PG8_WAIT_L(0); PG8_MMA(1, 0, At, B0); PG8_BAR; PG8_SCHED;
;       PG8_STAGE(PG8_SB(1, 1), b3 + hstep, voffB);
;       PG8_WAIT_V(6); PG8_BAR; PG8_MMA(1, 1, At, B1); PG8_BAR;
	s_setprio 0
	s_add_i32 s59, 0, 0x18000
	v_add_u32_e32 v76, s59, v198
	ds_read_b128 v[64:67], v76
	ds_read_b128 v[68:71], v76 offset:1024
	ds_read_b128 v[72:75], v76 offset:2048
	ds_read_b128 v[76:79], v76 offset:3072
	s_add_u32 s50, s50, 0x80000
	s_addc_u32 s51, s51, 0
	s_mov_b32 m0, s66
	ds_read_b128 v[120:123], v202 offset:32768
	ds_read_b128 v[128:131], v202 offset:33792
	ds_read_b128 v[180:183], v202 offset:34816
	ds_read_b128 v[184:187], v202 offset:35840
	ds_read_b128 v[188:191], v202 offset:36864
	ds_read_b128 v[192:195], v202 offset:37888
	ds_read_b128 v[206:209], v202 offset:38912
	ds_read_b128 v[212:215], v202 offset:39936
	global_load_lds_dwordx4 v166, s[50:51]
	s_mov_b32 m0, s67
	s_nop 0
	global_load_lds_dwordx4 v162, s[50:51]
	s_add_i32 s50, 0, 0x1c000
	v_add_u32_e32 v244, s50, v198
	ds_read_b128 v[216:219], v244
	ds_read_b128 v[220:223], v244 offset:1024
	ds_read_b128 v[224:227], v244 offset:2048
	ds_read_b128 v[228:231], v244 offset:3072
	s_waitcnt vmcnt(8)
	s_waitcnt lgkmcnt(4)
	s_setprio 1
	s_barrier
	v_mfma_f32_16x16x32_bf16 v[136:139], v[64:67], v[120:123], v[156:159]
	v_mfma_f32_16x16x32_bf16 v[156:159], v[68:71], v[128:131], v[136:139]
	v_mfma_f32_16x16x32_bf16 v[136:139], v[72:75], v[120:123], v[144:147]
	v_mfma_f32_16x16x32_bf16 v[144:147], v[76:79], v[128:131], v[136:139]
	v_mfma_f32_16x16x32_bf16 v[136:139], v[64:67], v[180:183], v[140:143]
	v_mfma_f32_16x16x32_bf16 v[132:135], v[72:75], v[180:183], v[132:135]
	v_mfma_f32_16x16x32_bf16 v[124:127], v[64:67], v[188:191], v[124:127]
	v_mfma_f32_16x16x32_bf16 v[116:119], v[72:75], v[188:191], v[116:119]
	v_mfma_f32_16x16x32_bf16 v[112:115], v[64:67], v[206:209], v[112:115]
	v_mfma_f32_16x16x32_bf16 v[108:111], v[72:75], v[206:209], v[108:111]
	v_mfma_f32_16x16x32_bf16 v[140:143], v[68:71], v[184:187], v[136:139]
	v_mfma_f32_16x16x32_bf16 v[132:135], v[76:79], v[184:187], v[132:135]
	v_mfma_f32_16x16x32_bf16 v[124:127], v[68:71], v[192:195], v[124:127]
	v_mfma_f32_16x16x32_bf16 v[116:119], v[76:79], v[192:195], v[116:119]
	v_mfma_f32_16x16x32_bf16 v[112:115], v[68:71], v[212:215], v[112:115]
	v_mfma_f32_16x16x32_bf16 v[108:111], v[76:79], v[212:215], v[108:111]
	s_waitcnt lgkmcnt(0)
	v_mfma_f32_16x16x32_bf16 v[80:83], v[224:227], v[120:123], v[80:83]
	v_mfma_f32_16x16x32_bf16 v[136:139], v[216:219], v[120:123], v[152:155]
	v_mfma_f32_16x16x32_bf16 v[148:151], v[228:231], v[128:131], v[80:83]
	v_mfma_f32_16x16x32_bf16 v[80:83], v[216:219], v[180:183], v[84:87]
	v_mfma_f32_16x16x32_bf16 v[152:155], v[220:223], v[128:131], v[136:139]
	v_mfma_f32_16x16x32_bf16 v[136:139], v[220:223], v[184:187], v[80:83]
	v_mfma_f32_16x16x32_bf16 v[80:83], v[224:227], v[180:183], v[88:91]
	v_mfma_f32_16x16x32_bf16 v[128:131], v[228:231], v[184:187], v[80:83]
	v_mfma_f32_16x16x32_bf16 v[80:83], v[216:219], v[188:191], v[92:95]
	v_mfma_f32_16x16x32_bf16 v[120:123], v[220:223], v[192:195], v[80:83]
	v_mfma_f32_16x16x32_bf16 v[80:83], v[224:227], v[188:191], v[104:107]
	v_mfma_f32_16x16x32_bf16 v[104:107], v[228:231], v[192:195], v[80:83]
	v_mfma_f32_16x16x32_bf16 v[80:83], v[216:219], v[206:209], v[100:103]
	v_mfma_f32_16x16x32_bf16 v[100:103], v[220:223], v[212:215], v[80:83]
	v_mfma_f32_16x16x32_bf16 v[80:83], v[224:227], v[206:209], v[96:99]
	v_mfma_f32_16x16x32_bf16 v[96:99], v[228:231], v[212:215], v[80:83]
	s_barrier
	s_setprio 0
	s_add_i32 s51, s59, s62
	s_mov_b32 m0, s51
	s_nop 0
	global_load_lds_dwordx4 v164, s[98:99]
	s_add_i32 m0, s51, 0x2000
	s_nop 0
	global_load_lds_dwordx4 v160, s[98:99]
	s_mov_b32 m0, s55
	s_nop 2
	ds_read_b128 v[80:83], v202 offset:49152
	ds_read_b128 v[84:87], v202 offset:50176
	ds_read_b128 v[88:91], v202 offset:51200
	ds_read_b128 v[92:95], v202 offset:52224
	ds_read_b128 v[180:183], v202 offset:53248
	ds_read_b128 v[184:187], v202 offset:54272
	ds_read_b128 v[188:191], v202 offset:55296
	ds_read_b128 v[192:195], v202 offset:56320
	global_load_lds_dwordx4 v166, s[100:101]
	s_mov_b32 m0, s68
	s_nop 0
	global_load_lds_dwordx4 v162, s[100:101]
	s_add_u32 s48, s48, 0x80080
	s_addc_u32 s49, s49, 0
	s_add_i32 s50, s50, s62
	s_mov_b32 m0, s50
	s_nop 0
	global_load_lds_dwordx4 v164, s[48:49]
	s_add_i32 m0, s50, 0x2000
	s_nop 0
	global_load_lds_dwordx4 v160, s[48:49]
	s_add_i32 s58, s58, 2
	s_add_u32 s14, s14, 0x100
	s_addc_u32 s15, s15, 0
	s_add_u32 s52, s52, 0x100
	s_addc_u32 s53, s53, 0
	s_cmp_gt_u32 s58, 29
	s_waitcnt vmcnt(8)
	s_waitcnt lgkmcnt(0)
	s_setprio 1
	s_barrier
	v_mfma_f32_16x16x32_bf16 v[60:63], v[64:67], v[80:83], v[60:63]
	v_mfma_f32_16x16x32_bf16 v[48:51], v[72:75], v[80:83], v[48:51]
	v_mfma_f32_16x16x32_bf16 v[44:47], v[64:67], v[88:91], v[44:47]
	v_mfma_f32_16x16x32_bf16 v[36:39], v[72:75], v[88:91], v[36:39]
	v_mfma_f32_16x16x32_bf16 v[28:31], v[64:67], v[180:183], v[28:31]
	v_mfma_f32_16x16x32_bf16 v[20:23], v[72:75], v[180:183], v[20:23]
	v_mfma_f32_16x16x32_bf16 v[16:19], v[64:67], v[188:191], v[16:19]
	v_mfma_f32_16x16x32_bf16 v[12:15], v[72:75], v[188:191], v[12:15]
	v_mfma_f32_16x16x32_bf16 v[60:63], v[68:71], v[84:87], v[60:63]
	v_mfma_f32_16x16x32_bf16 v[48:51], v[76:79], v[84:87], v[48:51]
	v_mfma_f32_16x16x32_bf16 v[44:47], v[68:71], v[92:95], v[44:47]
	v_mfma_f32_16x16x32_bf16 v[36:39], v[76:79], v[92:95], v[36:39]
	v_mfma_f32_16x16x32_bf16 v[28:31], v[68:71], v[184:187], v[28:31]
	v_mfma_f32_16x16x32_bf16 v[20:23], v[76:79], v[184:187], v[20:23]
	v_mfma_f32_16x16x32_bf16 v[16:19], v[68:71], v[192:195], v[16:19]
	v_mfma_f32_16x16x32_bf16 v[12:15], v[76:79], v[192:195], v[12:15]
	v_mfma_f32_16x16x32_bf16 v[56:59], v[216:219], v[80:83], v[56:59]
	v_mfma_f32_16x16x32_bf16 v[52:55], v[224:227], v[80:83], v[52:55]
	v_mfma_f32_16x16x32_bf16 v[40:43], v[216:219], v[88:91], v[40:43]
	v_mfma_f32_16x16x32_bf16 v[32:35], v[224:227], v[88:91], v[32:35]
	v_mfma_f32_16x16x32_bf16 v[24:27], v[216:219], v[180:183], v[24:27]
	v_mfma_f32_16x16x32_bf16 v[8:11], v[224:227], v[180:183], v[8:11]
	v_mfma_f32_16x16x32_bf16 v[4:7], v[216:219], v[188:191], v[4:7]
	v_mfma_f32_16x16x32_bf16 v[0:3], v[224:227], v[188:191], v[0:3]
	v_mfma_f32_16x16x32_bf16 v[56:59], v[220:223], v[84:87], v[56:59]
	v_mfma_f32_16x16x32_bf16 v[52:55], v[228:231], v[84:87], v[52:55]
	v_mfma_f32_16x16x32_bf16 v[40:43], v[220:223], v[92:95], v[40:43]
	v_mfma_f32_16x16x32_bf16 v[32:35], v[228:231], v[92:95], v[32:35]
	v_mfma_f32_16x16x32_bf16 v[24:27], v[220:223], v[184:187], v[24:27]
	v_mfma_f32_16x16x32_bf16 v[8:11], v[228:231], v[184:187], v[8:11]
	v_mfma_f32_16x16x32_bf16 v[4:7], v[220:223], v[192:195], v[4:7]
	v_mfma_f32_16x16x32_bf16 v[0:3], v[228:231], v[192:195], v[0:3]
	s_barrier
; DI float dpp_ror1(float v) { return __int_as_float(__builtin_amdgcn_update_dpp(0, __float_as_int(v), 0x121, 0xf, 0xf, false)); }
; DI float dpp_ror2(float v) { return __int_as_float(__builtin_amdgcn_update_dpp(0, __float_as_int(v), 0x122, 0xf, 0xf, false)); }
; DI float row_rstd(const float* ssq, int row, int fq) {
;   const f32x4 a = *(const f32x4*)(ssq + (size_t)row * 32 + fq * 8), b = *(const f32x4*)(ssq + (size_t)row * 32 + fq * 8 + 4);
;   float sm = ((a[0] + a[1]) + (a[2] + a[3])) + ((b[0] + b[1]) + (b[2] + b[3]));
;   sm += __shfl_xor(sm, 16); sm += __shfl_xor(sm, 32);
;   return rsqrtf(sm * (1.0f / 2048.f) + 1e-6f);
;   DI void operator()(const f32x4 (&acc)[2][2][4][2], const Unit& u, int wr, int wc, int fr, int fq) const {
;     const int col = u.pn * 128 + wc * 32 + 8 * fq;
;     float w0[8], w1[8], w2[8], bb[8];
; #pragma unroll
;     for (int e = 0; e < 8; ++e) { w0[e] = cw[col + e]; w1[e] = cw[5632 + col + e]; w2[e] = cw[2 * 5632 + col + e]; bb[e] = cb[col + e]; }
; #pragma unroll
;     for (int ai = 0; ai < 2; ++ai) {
;       const int row0 = u.pm * BM + ai * HALF + wr * 64, span = row0 >> 6;
;       float rsv[4];
; #pragma unroll
;       for (int m = 0; m < 4; ++m) rsv[m] = row_rstd(ssq, row0 + 16 * m + fr, fq);
;       float p1[8], p2[8];
; #pragma unroll
;       for (int e = 0; e < 8; ++e) { p1[e] = 0.f; p2[e] = 0.f; }
; #pragma unroll
;       for (int m = 0; m < 4; ++m) {
;         float g[8], uu[8], a[8];
;         const float rs = rsv[m];
; #pragma unroll
;         for (int e = 0; e < 4; ++e) { g[e] = acc[ai][0][m][0][e] * rs; g[4 + e] = acc[ai][0][m][1][e] * rs; uu[e] = acc[ai][1][m][0][e] * rs; uu[4 + e] = acc[ai][1][m][1][e] * rs; }
; #pragma unroll
;         for (int e = 0; e < 8; ++e) {
;           const float x1 = dpp_ror1(g[e]), x2 = dpp_ror2(g[e]);
;           const float pr1 = (fr == 0) ? p1[e] : x1, pr2 = (fr < 2) ? p2[e] : x2;
;           a[e] = w2[e] * g[e] + w1[e] * pr1 + w0[e] * pr2 + bb[e];
;           p1[e] = x1; p2[e] = x2;
;         }
	s_setprio 0
	s_cbranch_scc0 .LBB0_1277
	s_lshl_b32 s39, s12, 8
	s_add_i32 s39, s39, s54
	v_or_b32_e32 v190, s39, v179
	v_ashrrev_i32_e32 v191, 31, v190
	v_lshlrev_b64 v[64:65], 7, v[190:191]
	v_or_b32_e32 v188, 16, v190
	v_lshl_add_u64 v[64:65], v[168:169], 0, v[64:65]
	v_ashrrev_i32_e32 v189, 31, v188
	global_load_dwordx4 v[192:195], v[64:65], off
	global_load_dwordx4 v[206:209], v[64:65], off offset:16
	v_lshlrev_b64 v[64:65], 7, v[188:189]
	v_lshl_add_u64 v[64:65], v[168:169], 0, v[64:65]
	global_load_dwordx4 v[212:215], v[64:65], off
	global_load_dwordx4 v[216:219], v[64:65], off offset:16
	v_or_b32_e32 v186, 32, v190
	v_ashrrev_i32_e32 v187, 31, v186
	v_lshlrev_b64 v[64:65], 7, v[186:187]
	v_or_b32_e32 v184, 48, v190
	v_lshl_add_u64 v[64:65], v[168:169], 0, v[64:65]
	v_ashrrev_i32_e32 v185, 31, v184
	global_load_dwordx4 v[220:223], v[64:65], off
	global_load_dwordx4 v[224:227], v[64:65], off offset:16
	v_lshlrev_b64 v[64:65], 7, v[184:185]
	v_lshl_add_u64 v[64:65], v[168:169], 0, v[64:65]
	global_load_dwordx4 v[228:231], v[64:65], off
	global_load_dwordx4 v[232:235], v[64:65], off offset:16
	v_lshl_or_b32 v180, s13, 7, v200
	v_and_b32_e32 v65, 64, v204
	v_xor_b32_e32 v64, 16, v204
	v_ashrrev_i32_e32 v181, 31, v180
	v_add_u32_e32 v65, 64, v65
	v_xor_b32_e32 v66, 32, v204
	v_lshlrev_b64 v[182:183], 2, v[180:181]
	v_cmp_lt_i32_e32 vcc, v64, v65
	v_lshl_add_u64 v[88:89], s[16:17], 0, v[182:183]
	v_lshl_add_u64 v[72:73], s[18:19], 0, v[182:183]
	v_cndmask_b32_e32 v64, v204, v64, vcc
	v_cmp_lt_i32_e32 vcc, v66, v65
	v_lshl_add_u64 v[74:75], v[88:89], 0, s[30:31]
	v_lshl_add_u64 v[76:77], v[88:89], 0, s[34:35]
	v_cndmask_b32_e32 v65, v204, v66, vcc
	v_add_co_u32_e32 v90, vcc, 0x5000, v88
	v_lshlrev_b32_e32 v187, 2, v64
	s_nop 0
	v_addc_co_u32_e32 v91, vcc, 0, v89, vcc
	v_add_co_u32_e32 v92, vcc, 0xb000, v88
	v_lshlrev_b32_e32 v185, 2, v65
	s_nop 0
	v_addc_co_u32_e32 v93, vcc, 0, v89, vcc
	global_load_dwordx4 v[64:67], v[88:89], off offset:16
	global_load_dwordx4 v[80:83], v[88:89], off
	global_load_dwordx4 v[68:71], v[72:73], off offset:16
	global_load_dwordx4 v[84:87], v[72:73], off
	s_nop 0
	global_load_dwordx4 v[72:75], v[74:75], off offset:16
	s_nop 0
	global_load_dwordx4 v[76:79], v[76:77], off offset:16
	s_nop 0
	global_load_dwordx4 v[88:91], v[90:91], off offset:2048
	s_nop 0
	global_load_dwordx4 v[92:95], v[92:93], off
	v_mov_b32_e32 v211, 0
	v_mov_b32_e32 v205, 0
	s_waitcnt vmcnt(0)
	v_mov_b32_e32 v196, v192
	v_mov_b32_e32 v197, v206
	v_mov_b32_e32 v206, v193
	v_mov_b32_e32 v192, v194
	v_mov_b32_e32 v193, v208
	v_mov_b32_e32 v208, v195
	v_pk_add_f32 v[194:195], v[196:197], v[206:207]
	v_pk_add_f32 v[192:193], v[192:193], v[208:209]
	v_mov_b32_e32 v196, v212
	v_mov_b32_e32 v197, v216
	v_mov_b32_e32 v216, v213
	v_mov_b32_e32 v206, v214
	v_mov_b32_e32 v207, v218
	v_mov_b32_e32 v218, v215
	v_pk_add_f32 v[192:193], v[194:195], v[192:193]
	v_pk_add_f32 v[194:195], v[196:197], v[216:217]
	v_pk_add_f32 v[196:197], v[206:207], v[218:219]
	v_mov_b32_e32 v208, v220
	v_pk_add_f32 v[194:195], v[194:195], v[196:197]
	v_mov_b32_e32 v197, v192
	v_mov_b32_e32 v196, v194
	v_mov_b32_e32 v192, v195
	v_pk_add_f32 v[192:193], v[196:197], v[192:193]
	ds_bpermute_b32 v195, v187, v193
	ds_bpermute_b32 v194, v187, v192
	v_mov_b32_e32 v209, v224
	v_mov_b32_e32 v224, v221
	v_mov_b32_e32 v212, v222
	v_mov_b32_e32 v213, v226
	s_waitcnt lgkmcnt(0)
	v_pk_add_f32 v[192:193], v[192:193], v[194:195]
	ds_bpermute_b32 v195, v185, v193
	ds_bpermute_b32 v194, v185, v192
	v_mov_b32_e32 v226, v223
	v_mov_b32_e32 v196, v228
	v_mov_b32_e32 v197, v232
	v_mov_b32_e32 v232, v229
	s_waitcnt lgkmcnt(0)
	v_pk_add_f32 v[192:193], v[192:193], v[194:195]
	v_mov_b32_e32 v206, v230
	v_pk_fma_f32 v[192:193], v[192:193], s[36:37], v[178:179] op_sel_hi:[1,0,0]
	v_mov_b32_e32 v207, v234
	v_mul_f32_e32 v189, 0x4b800000, v193
	v_cmp_gt_f32_e64 s[12:13], s74, v193
	v_mov_b32_e32 v234, v231
	v_pk_add_f32 v[208:209], v[208:209], v[224:225]
	v_cndmask_b32_e64 v189, v193, v189, s[12:13]
	v_rsq_f32_e32 v189, v189
	v_pk_add_f32 v[212:213], v[212:213], v[226:227]
	v_pk_add_f32 v[196:197], v[196:197], v[232:233]
	v_pk_add_f32 v[194:195], v[206:207], v[234:235]
	v_mul_f32_e32 v191, 0x45800000, v189
	v_cndmask_b32_e64 v220, v189, v191, s[12:13]
	v_pk_add_f32 v[208:209], v[208:209], v[212:213]
	v_pk_add_f32 v[194:195], v[196:197], v[194:195]
	v_pk_mul_f32 v[156:157], v[156:157], v[220:221] op_sel_hi:[1,0]
	v_mov_b32_e32 v216, 0
	v_mov_b32_e32 v218, 0
	v_mov_b32_e32 v196, v194
	v_mov_b32_e32 v197, v208
	v_mov_b32_e32 v208, v195
	v_mov_b32_dpp v216, v156 row_ror:1 row_mask:0xf bank_mask:0xf
	v_mov_b32_dpp v218, v157 row_ror:1 row_mask:0xf bank_mask:0xf
	v_pk_add_f32 v[194:195], v[196:197], v[208:209]
	v_cndmask_b32_e64 v207, v218, 0, s[0:1]
	v_cndmask_b32_e64 v206, v216, 0, s[0:1]
	v_pk_mul_f32 v[158:159], v[158:159], v[220:221] op_sel_hi:[1,0]
	v_mov_b32_e32 v212, 0
	v_mov_b32_e32 v214, 0
	ds_bpermute_b32 v197, v187, v195
	ds_bpermute_b32 v196, v187, v194
	v_mov_b32_e32 v215, 0
	v_mov_b32_e32 v217, 0
	v_pk_mul_f32 v[206:207], v[88:89], v[206:207]
	v_mov_b32_dpp v212, v158 row_ror:1 row_mask:0xf bank_mask:0xf
	v_mov_b32_dpp v214, v159 row_ror:1 row_mask:0xf bank_mask:0xf
	v_mov_b32_dpp v215, v156 row_ror:2 row_mask:0xf bank_mask:0xf
	v_mov_b32_dpp v217, v157 row_ror:2 row_mask:0xf bank_mask:0xf
	v_pk_fma_f32 v[156:157], v[92:93], v[156:157], v[206:207]
	v_mov_b32_e32 v213, 0
	v_cndmask_b32_e64 v207, v214, 0, s[0:1]
	v_cndmask_b32_e64 v206, v212, 0, s[0:1]
	v_cndmask_b32_e64 v209, v217, 0, s[4:5]
	v_cndmask_b32_e64 v208, v215, 0, s[4:5]
	v_mov_b32_dpp v211, v158 row_ror:2 row_mask:0xf bank_mask:0xf
	v_mov_b32_dpp v213, v159 row_ror:2 row_mask:0xf bank_mask:0xf
	v_pk_mul_f32 v[206:207], v[90:91], v[206:207]
	v_pk_fma_f32 v[156:157], v[80:81], v[208:209], v[156:157]
	v_cndmask_b32_e64 v209, v213, 0, s[4:5]
	v_cndmask_b32_e64 v208, v211, 0, s[4:5]
	v_pk_fma_f32 v[158:159], v[94:95], v[158:159], v[206:207]
	v_pk_mul_f32 v[144:145], v[144:145], v[220:221] op_sel_hi:[1,0]
	v_pk_fma_f32 v[158:159], v[82:83], v[208:209], v[158:159]
	v_mov_b32_e32 v207, 0
	v_mov_b32_e32 v209, 0
	v_pk_mul_f32 v[146:147], v[146:147], v[220:221] op_sel_hi:[1,0]
	v_mov_b32_e32 v191, 0
	s_waitcnt lgkmcnt(0)
; DI unsigned pack2(float lo, float hi) { f32x2 v = {lo, hi}; bf16v2 r = __builtin_convertvector(v, bf16v2); return __builtin_bit_cast(unsigned, r); }
; DI float silu_f(float x) { return x * sigmoid_f(x); }
; DI float dpp_ror1(float v) { return __int_as_float(__builtin_amdgcn_update_dpp(0, __float_as_int(v), 0x121, 0xf, 0xf, false)); }
; DI float dpp_ror2(float v) { return __int_as_float(__builtin_amdgcn_update_dpp(0, __float_as_int(v), 0x122, 0xf, 0xf, false)); }
;   DI void operator()(const f32x4 (&acc)[2][2][4][2], const Unit& u, int wr, int wc, int fr, int fq) const {
;     ...
;       for (int m = 0; m < 4; ++m) {
;         float g[8], uu[8], a[8];
;         const float rs = rsv[m];
; #pragma unroll
;         for (int e = 0; e < 4; ++e) { g[e] = acc[ai][0][m][0][e] * rs; g[4 + e] = acc[ai][0][m][1][e] * rs; uu[e] = acc[ai][1][m][0][e] * rs; uu[4 + e] = acc[ai][1][m][1][e] * rs; }
; #pragma unroll
;         for (int e = 0; e < 8; ++e) {
;           const float x1 = dpp_ror1(g[e]), x2 = dpp_ror2(g[e]);
;           const float pr1 = (fr == 0) ? p1[e] : x1, pr2 = (fr < 2) ? p2[e] : x2;
;           a[e] = w2[e] * g[e] + w1[e] * pr1 + w0[e] * pr2 + bb[e];
;           p1[e] = x1; p2[e] = x2;
;         }
;         if (m == 0 && fr < 2) {
;           float* ha = headA + (size_t)(span * 2 + fr) * 5632 + col; float* hu = headU + (size_t)(span * 2 + fr) * 5632 + col;
;           *(f32x4*)ha = (f32x4){a[0], a[1], a[2], a[3]}; *(f32x4*)(ha + 4) = (f32x4){a[4], a[5], a[6], a[7]};
;           *(f32x4*)hu = (f32x4){uu[0], uu[1], uu[2], uu[3]}; *(f32x4*)(hu + 4) = (f32x4){uu[4], uu[5], uu[6], uu[7]};
;         } else {
;           u32x4 w;
;           w.x = pack2(silu_f(a[0]) * uu[0], silu_f(a[1]) * uu[1]);
;           w.y = pack2(silu_f(a[2]) * uu[2], silu_f(a[3]) * uu[3]);
;           w.z = pack2(silu_f(a[4]) * uu[4], silu_f(a[5]) * uu[5]);
;           w.w = pack2(silu_f(a[6]) * uu[6], silu_f(a[7]) * uu[7]);
;           *(u32x4*)(H + (size_t)(row0 + 16 * m + fr) * 5632 + col) = w;
	v_pk_add_f32 v[194:195], v[194:195], v[196:197]
	v_mov_b32_dpp v207, v144 row_ror:1 row_mask:0xf bank_mask:0xf
	v_mov_b32_dpp v209, v145 row_ror:1 row_mask:0xf bank_mask:0xf
	v_mov_b32_dpp v191, v146 row_ror:1 row_mask:0xf bank_mask:0xf
	v_mov_b32_dpp v205, v147 row_ror:1 row_mask:0xf bank_mask:0xf
	ds_bpermute_b32 v197, v185, v195
	ds_bpermute_b32 v196, v185, v194
	v_pk_mul_f32 v[152:153], v[152:153], v[220:221] op_sel_hi:[1,0]
	v_pk_mul_f32 v[148:149], v[148:149], v[220:221] op_sel_hi:[1,0]
	v_pk_mul_f32 v[154:155], v[154:155], v[220:221] op_sel_hi:[1,0]
	v_pk_mul_f32 v[150:151], v[150:151], v[220:221] op_sel_hi:[1,0]
	v_mov_b32_e32 v206, 0
	v_mov_b32_e32 v208, 0
	v_cndmask_b32_e64 v223, v209, 0, s[0:1]
	v_cndmask_b32_e64 v222, v207, 0, s[0:1]
	v_mov_b32_e32 v189, 0
	v_mov_b32_e32 v193, 0
	v_cndmask_b32_e64 v221, v205, 0, s[0:1]
	v_cndmask_b32_e64 v220, v191, 0, s[0:1]
	v_mov_b32_dpp v206, v144 row_ror:2 row_mask:0xf bank_mask:0xf
	v_mov_b32_dpp v208, v145 row_ror:2 row_mask:0xf bank_mask:0xf
	v_pk_mul_f32 v[222:223], v[72:73], v[222:223]
	v_mov_b32_dpp v189, v146 row_ror:2 row_mask:0xf bank_mask:0xf
	v_mov_b32_dpp v193, v147 row_ror:2 row_mask:0xf bank_mask:0xf
	v_pk_mul_f32 v[220:221], v[74:75], v[220:221]
	v_cndmask_b32_e64 v225, v208, 0, s[4:5]
	v_cndmask_b32_e64 v224, v206, 0, s[4:5]
	v_pk_fma_f32 v[144:145], v[76:77], v[144:145], v[222:223]
	v_cndmask_b32_e64 v223, v193, 0, s[4:5]
	v_cndmask_b32_e64 v222, v189, 0, s[4:5]
	v_pk_fma_f32 v[146:147], v[78:79], v[146:147], v[220:221]
	v_pk_fma_f32 v[144:145], v[64:65], v[224:225], v[144:145]
	v_pk_fma_f32 v[146:147], v[66:67], v[222:223], v[146:147]
	v_cmp_gt_f32_e32 vcc, s74, v192
	v_pk_add_f32 v[156:157], v[84:85], v[156:157]
	v_pk_add_f32 v[158:159], v[86:87], v[158:159]
	v_pk_add_f32 v[144:145], v[68:69], v[144:145]
	v_pk_add_f32 v[146:147], v[70:71], v[146:147]
	s_and_saveexec_b64 s[12:13], s[10:11]
	s_xor_b64 s[12:13], exec, s[12:13]
	s_cbranch_execz .LBB0_1280
	v_mul_f32_e32 v219, 0xbfb8aa3b, v156
	v_exp_f32_e32 v219, v219
	v_mul_f32_e32 v220, 0xbfb8aa3b, v157
	v_exp_f32_e32 v220, v220
	v_mul_f32_e32 v222, 0xbfb8aa3b, v159
	v_add_f32_e32 v219, 1.0, v219
	v_exp_f32_e32 v223, v222
	v_add_f32_e32 v221, 1.0, v220
	v_rcp_f32_e32 v220, v219
	v_mul_f32_e32 v219, 0xbfb8aa3b, v158
	v_exp_f32_e32 v219, v219
	v_rcp_f32_e32 v221, v221
	v_add_f32_e32 v219, 1.0, v219
	v_rcp_f32_e32 v222, v219
	v_add_f32_e32 v219, 1.0, v223
	v_rcp_f32_e32 v223, v219
	v_pk_mul_f32 v[156:157], v[156:157], v[220:221]
	s_nop 0
	v_pk_mul_f32 v[152:153], v[152:153], v[156:157]
	v_pk_mul_f32 v[156:157], v[158:159], v[222:223]
	v_cvt_pk_bf16_f32 v152, v152, v153
	v_mul_f32_e32 v153, 0xbfb8aa3b, v144
	v_pk_mul_f32 v[154:155], v[154:155], v[156:157]
	v_exp_f32_e32 v156, v153
	v_mul_f32_e32 v153, 0xbfb8aa3b, v145
	v_exp_f32_e32 v157, v153
	v_cvt_pk_bf16_f32 v153, v154, v155
	v_add_f32_e32 v154, 1.0, v156
	v_mul_f32_e32 v156, 0xbfb8aa3b, v146
	v_add_f32_e32 v155, 1.0, v157
	v_mul_f32_e32 v157, 0xbfb8aa3b, v147
	v_exp_f32_e32 v156, v156
	v_exp_f32_e32 v157, v157
	v_rcp_f32_e32 v154, v154
	v_rcp_f32_e32 v155, v155
	v_add_f32_e32 v156, 1.0, v156
	v_add_f32_e32 v157, 1.0, v157
	v_rcp_f32_e32 v156, v156
	v_rcp_f32_e32 v157, v157
	v_pk_mul_f32 v[144:145], v[144:145], v[154:155]
	s_nop 0
	v_pk_mul_f32 v[144:145], v[148:149], v[144:145]
	s_nop 0
	v_cvt_pk_bf16_f32 v154, v144, v145
	v_pk_mul_f32 v[144:145], v[146:147], v[156:157]
	s_nop 0
	v_pk_mul_f32 v[144:145], v[150:151], v[144:145]
	s_nop 0
	v_cvt_pk_bf16_f32 v155, v144, v145
	v_mov_b64_e32 v[144:145], s[20:21]
	v_mad_i64_i32 v[144:145], s[14:15], v190, s75, v[144:145]
	v_lshl_add_u64 v[144:145], v[180:181], 1, v[144:145]
	global_store_dwordx4 v[144:145], v[152:155], off

; #define PG8_STAGE(bufoff, gbase, voff) do { _Pragma("unroll") for (int _i = 0; _i < 2; ++_i) \
;     __builtin_amdgcn_global_load_lds((const unsigned*)((const char*)(gbase) + (voff)[_i]), (LAS unsigned*)(lds + (bufoff) + ldsw + _i * 8192), 16, 0, 0); } while (0)
; #define PG8_LDA(dst, b, h) do { _Pragma("unroll") for (int m = 0; m < 4; ++m) _Pragma("unroll") for (int k = 0; k < 2; ++k) dst[m][k] = *(const LAS bf16x8*)(lds + PG8_SA(b, h) + aoff + m * 2048 + k * 1024); } while (0)
; #define PG8_LDB(dst, b, h) do { _Pragma("unroll") for (int n = 0; n < 2; ++n) _Pragma("unroll") for (int k = 0; k < 2; ++k) dst[n][k] = *(const LAS bf16x8*)(lds + PG8_SB(b, h) + boff + n * 2048 + k * 1024); } while (0)
; #define PG8_MMA(ai, bj, At, Bt) do { __builtin_amdgcn_s_setprio(1); _Pragma("unroll") for (int m = 0; m < 4; ++m) _Pragma("unroll") for (int n = 0; n < 2; ++n) _Pragma("unroll") for (int k = 0; k < 2; ++k) \
;     acc[ai][bj][m][n] = __builtin_amdgcn_mfma_f32_16x16x32_bf16(Bt[n][k], At[m][k], acc[ai][bj][m][n], 0, 0, 0); __builtin_amdgcn_s_setprio(0); } while (0)
; #define PG8_WAIT_V(n) asm volatile("s_waitcnt vmcnt(" #n ")" ::: "memory")
; #define PG8_WAIT_L(n) asm volatile("s_waitcnt lgkmcnt(" #n ")" ::: "memory")
; #define PG8_BAR __builtin_amdgcn_s_barrier()
; #define PG8_SCHED __builtin_amdgcn_sched_barrier(0)
; template <class Epi, class Sched = StaticOrder>
; DI void gemm_phase(LAS unsigned char* lds, const Gemm g, const Sched& S, const Epi& E) {
;     ...
;     for (int t = 0; t < nt; t += 2) {
;       const bool last = (t == nt - 2);
;       const char* a1 = cA + (size_t)(t + 1) * kstep;
;       const char* a2 = last ? nA : cA + (size_t)(t + 2) * kstep; const char* b2 = last ? nB : cB + (size_t)(t + 2) * kstep;
;       const char* a3 = a2 + kstep; const char* b3 = b2 + kstep;
;       PG8_LDB(B0, 0, 0); PG8_SCHED; PG8_LDA(At, 0, 0); PG8_STAGE(PG8_SA(1, 1), a1 + hstep, voffA);
;       PG8_WAIT_L(8); PG8_BAR; PG8_WAIT_L(0); PG8_MMA(0, 0, At, B0); PG8_BAR; PG8_SCHED;
;       PG8_LDB(B1, 0, 1); PG8_STAGE(PG8_SB(0, 0), b2, voffB);
;       PG8_BAR; PG8_WAIT_L(0); PG8_MMA(0, 1, At, B1); PG8_BAR;
;       PG8_LDA(At, 0, 1); PG8_STAGE(PG8_SA(0, 0), a2, voffA);
;       PG8_BAR; PG8_WAIT_L(0); PG8_MMA(1, 0, At, B0); PG8_BAR; PG8_SCHED;
;       PG8_STAGE(PG8_SB(0, 1), b2 + hstep, voffB);
;       PG8_WAIT_V(6); PG8_BAR; PG8_MMA(1, 1, At, B1); PG8_BAR;
.LBB0_1424:
	ds_read_b128 v[144:147], v159
	ds_read_b128 v[148:151], v159 offset:1024
	ds_read_b128 v[152:155], v159 offset:2048
	ds_read_b128 v[162:165], v159 offset:3072
	s_add_u32 s18, s16, 0xffea0080
	s_addc_u32 s19, s17, -1
	s_cmpk_eq_i32 s47, 0x54
	s_cselect_b32 s21, s3, s19
	s_cselect_b32 s20, s2, s18
	s_cselect_b32 s19, s5, s46
	s_cselect_b32 s18, s4, s45
	s_add_i32 m0, s30, 0xc000
	ds_read_b128 v[166:169], v160
	ds_read_b128 v[170:173], v160 offset:1024
	ds_read_b128 v[174:177], v160 offset:2048
	ds_read_b128 v[178:181], v160 offset:3072
	ds_read_b128 v[182:185], v160 offset:4096
	ds_read_b128 v[186:189], v160 offset:5120
	ds_read_b128 v[190:193], v160 offset:6144
	ds_read_b128 v[194:197], v160 offset:7168
	global_load_lds_dwordx4 v136, s[16:17]
	s_add_i32 m0, s30, 0xe000
	s_nop 0
	global_load_lds_dwordx4 v138, s[16:17]
	ds_read_b128 v[198:201], v161
	ds_read_b128 v[202:205], v161 offset:1024
	ds_read_b128 v[206:209], v161 offset:2048
	ds_read_b128 v[210:213], v161 offset:3072
	s_waitcnt vmcnt(8)
	s_waitcnt lgkmcnt(4)
	s_setprio 1
	s_barrier
	v_mfma_f32_16x16x32_bf16 v[124:127], v[144:147], v[166:169], v[124:127]
	v_mfma_f32_16x16x32_bf16 v[120:123], v[152:155], v[166:169], v[120:123]
	v_mfma_f32_16x16x32_bf16 v[116:119], v[144:147], v[174:177], v[116:119]
	v_mfma_f32_16x16x32_bf16 v[112:115], v[152:155], v[174:177], v[112:115]
	v_mfma_f32_16x16x32_bf16 v[104:107], v[144:147], v[182:185], v[104:107]
	v_mfma_f32_16x16x32_bf16 v[96:99], v[152:155], v[182:185], v[96:99]
	v_mfma_f32_16x16x32_bf16 v[88:91], v[144:147], v[190:193], v[88:91]
	v_mfma_f32_16x16x32_bf16 v[80:83], v[152:155], v[190:193], v[80:83]
	v_mfma_f32_16x16x32_bf16 v[124:127], v[148:151], v[170:173], v[124:127]
	v_mfma_f32_16x16x32_bf16 v[120:123], v[162:165], v[170:173], v[120:123]
	v_mfma_f32_16x16x32_bf16 v[116:119], v[148:151], v[178:181], v[116:119]
	v_mfma_f32_16x16x32_bf16 v[112:115], v[162:165], v[178:181], v[112:115]
	v_mfma_f32_16x16x32_bf16 v[104:107], v[148:151], v[186:189], v[104:107]
	v_mfma_f32_16x16x32_bf16 v[96:99], v[162:165], v[186:189], v[96:99]
	v_mfma_f32_16x16x32_bf16 v[88:91], v[148:151], v[194:197], v[88:91]
	v_mfma_f32_16x16x32_bf16 v[80:83], v[162:165], v[194:197], v[80:83]
	s_waitcnt lgkmcnt(0)
	v_mfma_f32_16x16x32_bf16 v[108:111], v[198:201], v[166:169], v[108:111]
	v_mfma_f32_16x16x32_bf16 v[100:103], v[206:209], v[166:169], v[100:103]
	v_mfma_f32_16x16x32_bf16 v[92:95], v[198:201], v[174:177], v[92:95]
	v_mfma_f32_16x16x32_bf16 v[84:87], v[206:209], v[174:177], v[84:87]
	v_mfma_f32_16x16x32_bf16 v[76:79], v[198:201], v[182:185], v[76:79]
	v_mfma_f32_16x16x32_bf16 v[72:75], v[206:209], v[182:185], v[72:75]
	v_mfma_f32_16x16x32_bf16 v[68:71], v[198:201], v[190:193], v[68:71]
	v_mfma_f32_16x16x32_bf16 v[64:67], v[206:209], v[190:193], v[64:67]
	v_mfma_f32_16x16x32_bf16 v[108:111], v[202:205], v[170:173], v[108:111]
	v_mfma_f32_16x16x32_bf16 v[100:103], v[210:213], v[170:173], v[100:103]
	v_mfma_f32_16x16x32_bf16 v[92:95], v[202:205], v[178:181], v[92:95]
	v_mfma_f32_16x16x32_bf16 v[84:87], v[210:213], v[178:181], v[84:87]
	v_mfma_f32_16x16x32_bf16 v[76:79], v[202:205], v[186:189], v[76:79]
	v_mfma_f32_16x16x32_bf16 v[72:75], v[210:213], v[186:189], v[72:75]
	v_mfma_f32_16x16x32_bf16 v[68:71], v[202:205], v[194:197], v[68:71]
	v_mfma_f32_16x16x32_bf16 v[64:67], v[210:213], v[194:197], v[64:67]
	s_barrier
	s_setprio 0
	s_add_i32 s48, s39, s28
	s_add_u32 s98, s18, 0x80
	s_addc_u32 s99, s19, 0
	s_add_u32 s100, s20, 0x80
	s_addc_u32 s101, s21, 0
	s_mov_b32 m0, s48
	s_nop 0
	global_load_lds_dwordx4 v132, s[18:19]
	s_add_i32 m0, s48, 0x2000
	s_nop 0
	global_load_lds_dwordx4 v128, s[18:19]
	s_mov_b32 m0, s30
	ds_read_b128 v[166:169], v160 offset:16384
	ds_read_b128 v[170:173], v160 offset:17408
	ds_read_b128 v[174:177], v160 offset:18432
	ds_read_b128 v[178:181], v160 offset:19456
	ds_read_b128 v[182:185], v160 offset:20480
	ds_read_b128 v[186:189], v160 offset:21504
	ds_read_b128 v[190:193], v160 offset:22528
	ds_read_b128 v[194:197], v160 offset:23552
	global_load_lds_dwordx4 v134, s[20:21]
	s_mov_b32 m0, s31
	s_nop 0
	global_load_lds_dwordx4 v130, s[20:21]
	s_add_u32 s48, s18, 0x160000
	s_addc_u32 s49, s19, 0
	s_add_i32 s50, s40, s28
	s_mov_b32 m0, s50
	s_nop 0
	global_load_lds_dwordx4 v132, s[48:49]
	s_add_i32 m0, s50, 0x2000
	s_nop 0
	global_load_lds_dwordx4 v128, s[48:49]
	s_waitcnt vmcnt(8)
	s_waitcnt lgkmcnt(0)
	s_setprio 1
	s_barrier
	v_mfma_f32_16x16x32_bf16 v[60:63], v[144:147], v[166:169], v[60:63]
	v_mfma_f32_16x16x32_bf16 v[56:59], v[152:155], v[166:169], v[56:59]
	v_mfma_f32_16x16x32_bf16 v[52:55], v[144:147], v[174:177], v[52:55]
	v_mfma_f32_16x16x32_bf16 v[44:47], v[152:155], v[174:177], v[44:47]
	v_mfma_f32_16x16x32_bf16 v[36:39], v[144:147], v[182:185], v[36:39]
	v_mfma_f32_16x16x32_bf16 v[28:31], v[152:155], v[182:185], v[28:31]
	v_mfma_f32_16x16x32_bf16 v[20:23], v[144:147], v[190:193], v[20:23]
	v_mfma_f32_16x16x32_bf16 v[12:15], v[152:155], v[190:193], v[12:15]
	v_mfma_f32_16x16x32_bf16 v[60:63], v[148:151], v[170:173], v[60:63]
	v_mfma_f32_16x16x32_bf16 v[56:59], v[162:165], v[170:173], v[56:59]
	v_mfma_f32_16x16x32_bf16 v[52:55], v[148:151], v[178:181], v[52:55]
	v_mfma_f32_16x16x32_bf16 v[44:47], v[162:165], v[178:181], v[44:47]
	v_mfma_f32_16x16x32_bf16 v[36:39], v[148:151], v[186:189], v[36:39]
	v_mfma_f32_16x16x32_bf16 v[28:31], v[162:165], v[186:189], v[28:31]
	v_mfma_f32_16x16x32_bf16 v[20:23], v[148:151], v[194:197], v[20:23]
	v_mfma_f32_16x16x32_bf16 v[12:15], v[162:165], v[194:197], v[12:15]
	v_mfma_f32_16x16x32_bf16 v[48:51], v[198:201], v[166:169], v[48:51]
	v_mfma_f32_16x16x32_bf16 v[40:43], v[206:209], v[166:169], v[40:43]
	v_mfma_f32_16x16x32_bf16 v[32:35], v[198:201], v[174:177], v[32:35]
	v_mfma_f32_16x16x32_bf16 v[24:27], v[206:209], v[174:177], v[24:27]
	v_mfma_f32_16x16x32_bf16 v[16:19], v[198:201], v[182:185], v[16:19]
	v_mfma_f32_16x16x32_bf16 v[8:11], v[206:209], v[182:185], v[8:11]
	v_mfma_f32_16x16x32_bf16 v[4:7], v[198:201], v[190:193], v[4:7]
	v_mfma_f32_16x16x32_bf16 v[0:3], v[206:209], v[190:193], v[0:3]
	v_mfma_f32_16x16x32_bf16 v[48:51], v[202:205], v[170:173], v[48:51]
	v_mfma_f32_16x16x32_bf16 v[40:43], v[210:213], v[170:173], v[40:43]
	v_mfma_f32_16x16x32_bf16 v[32:35], v[202:205], v[178:181], v[32:35]
	v_mfma_f32_16x16x32_bf16 v[24:27], v[210:213], v[178:181], v[24:27]
	v_mfma_f32_16x16x32_bf16 v[16:19], v[202:205], v[186:189], v[16:19]
	v_mfma_f32_16x16x32_bf16 v[8:11], v[210:213], v[186:189], v[8:11]
	v_mfma_f32_16x16x32_bf16 v[4:7], v[202:205], v[194:197], v[4:7]
	v_mfma_f32_16x16x32_bf16 v[0:3], v[210:213], v[194:197], v[0:3]
	s_barrier
; #define PG8_STAGE(bufoff, gbase, voff) do { _Pragma("unroll") for (int _i = 0; _i < 2; ++_i) \
;     __builtin_amdgcn_global_load_lds((const unsigned*)((const char*)(gbase) + (voff)[_i]), (LAS unsigned*)(lds + (bufoff) + ldsw + _i * 8192), 16, 0, 0); } while (0)
; #define PG8_LDA(dst, b, h) do { _Pragma("unroll") for (int m = 0; m < 4; ++m) _Pragma("unroll") for (int k = 0; k < 2; ++k) dst[m][k] = *(const LAS bf16x8*)(lds + PG8_SA(b, h) + aoff + m * 2048 + k * 1024); } while (0)
; #define PG8_LDB(dst, b, h) do { _Pragma("unroll") for (int n = 0; n < 2; ++n) _Pragma("unroll") for (int k = 0; k < 2; ++k) dst[n][k] = *(const LAS bf16x8*)(lds + PG8_SB(b, h) + boff + n * 2048 + k * 1024); } while (0)
; #define PG8_MMA(ai, bj, At, Bt) do { __builtin_amdgcn_s_setprio(1); _Pragma("unroll") for (int m = 0; m < 4; ++m) _Pragma("unroll") for (int n = 0; n < 2; ++n) _Pragma("unroll") for (int k = 0; k < 2; ++k) \
;     acc[ai][bj][m][n] = __builtin_amdgcn_mfma_f32_16x16x32_bf16(Bt[n][k], At[m][k], acc[ai][bj][m][n], 0, 0, 0); __builtin_amdgcn_s_setprio(0); } while (0)
; #define PG8_WAIT_V(n) asm volatile("s_waitcnt vmcnt(" #n ")" ::: "memory")
; #define PG8_WAIT_L(n) asm volatile("s_waitcnt lgkmcnt(" #n ")" ::: "memory")
; #define PG8_BAR __builtin_amdgcn_s_barrier()
; #define PG8_SCHED __builtin_amdgcn_sched_barrier(0)
; template <class Epi, class Sched = StaticOrder>
; DI void gemm_phase(LAS unsigned char* lds, const Gemm g, const Sched& S, const Epi& E) {
;     ...
;       PG8_LDB(B0, 1, 0); PG8_SCHED; PG8_LDA(At, 1, 0); PG8_STAGE(PG8_SA(0, 1), a2 + hstep, voffA);
;       PG8_WAIT_L(8); PG8_BAR; PG8_WAIT_L(0); PG8_MMA(0, 0, At, B0); PG8_BAR; PG8_SCHED;
;       PG8_LDB(B1, 1, 1); PG8_STAGE(PG8_SB(1, 0), b3, voffB);
;       PG8_BAR; PG8_WAIT_L(0); PG8_MMA(0, 1, At, B1); PG8_BAR;
;       PG8_LDA(At, 1, 1); PG8_STAGE(PG8_SA(1, 0), a3, voffA);
;       PG8_BAR; PG8_WAIT_L(0); PG8_MMA(1, 0, At, B0); PG8_BAR; PG8_SCHED;
;       PG8_STAGE(PG8_SB(1, 1), b3 + hstep, voffB);
;       PG8_WAIT_V(6); PG8_BAR; PG8_MMA(1, 1, At, B1); PG8_BAR;
	s_setprio 0
	s_add_i32 s48, 0, 0x18000
	v_add_u32_e32 v162, s48, v157
	ds_read_b128 v[144:147], v162
	ds_read_b128 v[148:151], v162 offset:1024
	ds_read_b128 v[152:155], v162 offset:2048
	ds_read_b128 v[162:165], v162 offset:3072
	s_add_u32 s20, s20, 0x160000
	s_addc_u32 s21, s21, 0
	s_mov_b32 m0, s33
	ds_read_b128 v[166:169], v160 offset:32768
	ds_read_b128 v[170:173], v160 offset:33792
	ds_read_b128 v[174:177], v160 offset:34816
	ds_read_b128 v[178:181], v160 offset:35840
	ds_read_b128 v[182:185], v160 offset:36864
	ds_read_b128 v[186:189], v160 offset:37888
	ds_read_b128 v[190:193], v160 offset:38912
	ds_read_b128 v[194:197], v160 offset:39936
	global_load_lds_dwordx4 v134, s[20:21]
	s_mov_b32 m0, s34
	s_nop 0
	global_load_lds_dwordx4 v130, s[20:21]
	s_add_i32 s20, 0, 0x1c000
	v_add_u32_e32 v210, s20, v157
	ds_read_b128 v[198:201], v210
	ds_read_b128 v[202:205], v210 offset:1024
	ds_read_b128 v[206:209], v210 offset:2048
	ds_read_b128 v[210:213], v210 offset:3072
	s_waitcnt vmcnt(8)
	s_waitcnt lgkmcnt(4)
	s_setprio 1
	s_barrier
	v_mfma_f32_16x16x32_bf16 v[124:127], v[144:147], v[166:169], v[124:127]
	v_mfma_f32_16x16x32_bf16 v[120:123], v[152:155], v[166:169], v[120:123]
	v_mfma_f32_16x16x32_bf16 v[116:119], v[144:147], v[174:177], v[116:119]
	v_mfma_f32_16x16x32_bf16 v[112:115], v[152:155], v[174:177], v[112:115]
	v_mfma_f32_16x16x32_bf16 v[104:107], v[144:147], v[182:185], v[104:107]
	v_mfma_f32_16x16x32_bf16 v[96:99], v[152:155], v[182:185], v[96:99]
	v_mfma_f32_16x16x32_bf16 v[88:91], v[144:147], v[190:193], v[88:91]
	v_mfma_f32_16x16x32_bf16 v[80:83], v[152:155], v[190:193], v[80:83]
	v_mfma_f32_16x16x32_bf16 v[124:127], v[148:151], v[170:173], v[124:127]
	v_mfma_f32_16x16x32_bf16 v[120:123], v[162:165], v[170:173], v[120:123]
	v_mfma_f32_16x16x32_bf16 v[116:119], v[148:151], v[178:181], v[116:119]
	v_mfma_f32_16x16x32_bf16 v[112:115], v[162:165], v[178:181], v[112:115]
	v_mfma_f32_16x16x32_bf16 v[104:107], v[148:151], v[186:189], v[104:107]
	v_mfma_f32_16x16x32_bf16 v[96:99], v[162:165], v[186:189], v[96:99]
	v_mfma_f32_16x16x32_bf16 v[88:91], v[148:151], v[194:197], v[88:91]
	v_mfma_f32_16x16x32_bf16 v[80:83], v[162:165], v[194:197], v[80:83]
	s_waitcnt lgkmcnt(0)
	v_mfma_f32_16x16x32_bf16 v[108:111], v[198:201], v[166:169], v[108:111]
	v_mfma_f32_16x16x32_bf16 v[100:103], v[206:209], v[166:169], v[100:103]
	v_mfma_f32_16x16x32_bf16 v[92:95], v[198:201], v[174:177], v[92:95]
	v_mfma_f32_16x16x32_bf16 v[84:87], v[206:209], v[174:177], v[84:87]
	v_mfma_f32_16x16x32_bf16 v[76:79], v[198:201], v[182:185], v[76:79]
	v_mfma_f32_16x16x32_bf16 v[72:75], v[206:209], v[182:185], v[72:75]
	v_mfma_f32_16x16x32_bf16 v[68:71], v[198:201], v[190:193], v[68:71]
	v_mfma_f32_16x16x32_bf16 v[64:67], v[206:209], v[190:193], v[64:67]
	v_mfma_f32_16x16x32_bf16 v[108:111], v[202:205], v[170:173], v[108:111]
	v_mfma_f32_16x16x32_bf16 v[100:103], v[210:213], v[170:173], v[100:103]
	v_mfma_f32_16x16x32_bf16 v[92:95], v[202:205], v[178:181], v[92:95]
	v_mfma_f32_16x16x32_bf16 v[84:87], v[210:213], v[178:181], v[84:87]
	v_mfma_f32_16x16x32_bf16 v[76:79], v[202:205], v[186:189], v[76:79]
	v_mfma_f32_16x16x32_bf16 v[72:75], v[210:213], v[186:189], v[72:75]
	v_mfma_f32_16x16x32_bf16 v[68:71], v[202:205], v[194:197], v[68:71]
	v_mfma_f32_16x16x32_bf16 v[64:67], v[210:213], v[194:197], v[64:67]
	s_barrier
	s_setprio 0
	s_add_i32 s21, s48, s28
	s_mov_b32 m0, s21
	s_nop 0
	global_load_lds_dwordx4 v132, s[98:99]
	s_add_i32 m0, s21, 0x2000
	s_nop 0
	global_load_lds_dwordx4 v128, s[98:99]
	s_mov_b32 m0, s35
	ds_read_b128 v[166:169], v160 offset:49152
	ds_read_b128 v[170:173], v160 offset:50176
	ds_read_b128 v[174:177], v160 offset:51200
	ds_read_b128 v[178:181], v160 offset:52224
	ds_read_b128 v[182:185], v160 offset:53248
	ds_read_b128 v[186:189], v160 offset:54272
	ds_read_b128 v[190:193], v160 offset:55296
	ds_read_b128 v[194:197], v160 offset:56320
	global_load_lds_dwordx4 v134, s[100:101]
	s_mov_b32 m0, s36
	s_nop 0
	global_load_lds_dwordx4 v130, s[100:101]
	s_add_u32 s18, s18, 0x160080
	s_addc_u32 s19, s19, 0
	s_add_i32 s20, s20, s28
	s_mov_b32 m0, s20
	s_nop 0
	global_load_lds_dwordx4 v132, s[18:19]
	s_add_i32 m0, s20, 0x2000
	s_nop 0
	global_load_lds_dwordx4 v128, s[18:19]
	s_add_i32 s47, s47, 2
	s_add_u32 s16, s16, 0x100
	s_addc_u32 s17, s17, 0
	s_add_u32 s45, s45, 0x100
	s_addc_u32 s46, s46, 0
	s_cmpk_gt_u32 s47, 0x55
	s_waitcnt vmcnt(8)
	s_waitcnt lgkmcnt(0)
	s_setprio 1
	s_barrier
	v_mfma_f32_16x16x32_bf16 v[60:63], v[144:147], v[166:169], v[60:63]
	v_mfma_f32_16x16x32_bf16 v[56:59], v[152:155], v[166:169], v[56:59]
	v_mfma_f32_16x16x32_bf16 v[52:55], v[144:147], v[174:177], v[52:55]
	v_mfma_f32_16x16x32_bf16 v[44:47], v[152:155], v[174:177], v[44:47]
	v_mfma_f32_16x16x32_bf16 v[36:39], v[144:147], v[182:185], v[36:39]
	v_mfma_f32_16x16x32_bf16 v[28:31], v[152:155], v[182:185], v[28:31]
	v_mfma_f32_16x16x32_bf16 v[20:23], v[144:147], v[190:193], v[20:23]
	v_mfma_f32_16x16x32_bf16 v[12:15], v[152:155], v[190:193], v[12:15]
	v_mfma_f32_16x16x32_bf16 v[60:63], v[148:151], v[170:173], v[60:63]
	v_mfma_f32_16x16x32_bf16 v[56:59], v[162:165], v[170:173], v[56:59]
	v_mfma_f32_16x16x32_bf16 v[52:55], v[148:151], v[178:181], v[52:55]
	v_mfma_f32_16x16x32_bf16 v[44:47], v[162:165], v[178:181], v[44:47]
	v_mfma_f32_16x16x32_bf16 v[36:39], v[148:151], v[186:189], v[36:39]
	v_mfma_f32_16x16x32_bf16 v[28:31], v[162:165], v[186:189], v[28:31]
	v_mfma_f32_16x16x32_bf16 v[20:23], v[148:151], v[194:197], v[20:23]
	v_mfma_f32_16x16x32_bf16 v[12:15], v[162:165], v[194:197], v[12:15]
	v_mfma_f32_16x16x32_bf16 v[48:51], v[198:201], v[166:169], v[48:51]
	v_mfma_f32_16x16x32_bf16 v[40:43], v[206:209], v[166:169], v[40:43]
	v_mfma_f32_16x16x32_bf16 v[32:35], v[198:201], v[174:177], v[32:35]
	v_mfma_f32_16x16x32_bf16 v[24:27], v[206:209], v[174:177], v[24:27]
	v_mfma_f32_16x16x32_bf16 v[16:19], v[198:201], v[182:185], v[16:19]
	v_mfma_f32_16x16x32_bf16 v[8:11], v[206:209], v[182:185], v[8:11]
	v_mfma_f32_16x16x32_bf16 v[4:7], v[198:201], v[190:193], v[4:7]
	v_mfma_f32_16x16x32_bf16 v[0:3], v[206:209], v[190:193], v[0:3]
	v_mfma_f32_16x16x32_bf16 v[48:51], v[202:205], v[170:173], v[48:51]
	v_mfma_f32_16x16x32_bf16 v[40:43], v[210:213], v[170:173], v[40:43]
	v_mfma_f32_16x16x32_bf16 v[32:35], v[202:205], v[178:181], v[32:35]
	v_mfma_f32_16x16x32_bf16 v[24:27], v[210:213], v[178:181], v[24:27]
	v_mfma_f32_16x16x32_bf16 v[16:19], v[202:205], v[186:189], v[16:19]
	v_mfma_f32_16x16x32_bf16 v[8:11], v[210:213], v[186:189], v[8:11]
	v_mfma_f32_16x16x32_bf16 v[4:7], v[202:205], v[194:197], v[4:7]
	v_mfma_f32_16x16x32_bf16 v[0:3], v[210:213], v[194:197], v[0:3]
	s_barrier
;   DI void operator()(const f32x4 (&acc)[2][2][4][2], const Unit& u, int wr, int wc, int fr, int fq) const {
;     const int row0 = u.pm * BM + wr * 64 + fr, col0 = u.pn * BM + wc * 32 + 8 * fq;
; #pragma unroll
;     for (int ai = 0; ai < 2; ++ai) {
;       f32x4 bv[4][2][2];
; #pragma unroll
;       for (int m = 0; m < 4; ++m)
; #pragma unroll
;         for (int bj = 0; bj < 2; ++bj) {
;           const float* bp = base + (size_t)(row0 + ai * HALF + m * 16) * 2048 + col0 + bj * HALF;
;           bv[m][bj][0] = *(const f32x4*)bp; bv[m][bj][1] = *(const f32x4*)(bp + 4);
;         }
; #pragma unroll
;       for (int m = 0; m < 4; ++m) {
;         const int row = row0 + ai * HALF + m * 16;
;         const size_t off = (size_t)row * 2048 + col0;
;         float ss = 0.f;
; #pragma unroll
;         for (int bj = 0; bj < 2; ++bj) {
;           const f32x4 v0 = acc[ai][bj][m][0] + bv[m][bj][0], v1 = acc[ai][bj][m][1] + bv[m][bj][1];
;           *(f32x4*)(C + off + bj * HALF) = v0; *(f32x4*)(C + off + bj * HALF + 4) = v1;
	s_setprio 0
	s_cbranch_scc0 .LBB0_1424
	v_lshl_or_b32 v144, s44, 8, v158
	v_lshl_add_u32 v154, s43, 8, v156
	v_ashrrev_i32_e32 v145, 31, v144
	v_lshlrev_b64 v[144:145], 2, v[144:145]
	v_ashrrev_i32_e32 v155, 31, v154
	v_lshl_add_u64 v[146:147], s[54:55], 0, v[144:145]
	v_lshlrev_b64 v[148:149], 13, v[154:155]
	v_or_b32_e32 v174, 16, v154
	v_lshl_add_u64 v[170:171], v[146:147], 0, v[148:149]
	v_ashrrev_i32_e32 v175, 31, v174
	global_load_dwordx4 v[150:153], v[170:171], off offset:16
	global_load_dwordx4 v[162:165], v[170:171], off
	global_load_dwordx4 v[166:169], v[170:171], off offset:528
	s_nop 0
	global_load_dwordx4 v[170:173], v[170:171], off offset:512
	v_lshlrev_b64 v[222:223], 13, v[174:175]
	v_or_b32_e32 v190, 32, v154
	v_lshl_add_u64 v[186:187], v[146:147], 0, v[222:223]
	v_ashrrev_i32_e32 v191, 31, v190
	global_load_dwordx4 v[174:177], v[186:187], off offset:16
	global_load_dwordx4 v[178:181], v[186:187], off
	global_load_dwordx4 v[182:185], v[186:187], off offset:528
	s_nop 0
	global_load_dwordx4 v[186:189], v[186:187], off offset:512
	v_lshlrev_b64 v[224:225], 13, v[190:191]
	v_or_b32_e32 v154, 48, v154
	v_lshl_add_u64 v[202:203], v[146:147], 0, v[224:225]
	v_ashrrev_i32_e32 v155, 31, v154
	global_load_dwordx4 v[190:193], v[202:203], off offset:16
	global_load_dwordx4 v[194:197], v[202:203], off
	global_load_dwordx4 v[198:201], v[202:203], off offset:528
	s_nop 0
	global_load_dwordx4 v[202:205], v[202:203], off offset:512
	v_lshlrev_b64 v[154:155], 13, v[154:155]
	v_lshl_add_u64 v[218:219], v[146:147], 0, v[154:155]
	global_load_dwordx4 v[206:209], v[218:219], off offset:16
	global_load_dwordx4 v[210:213], v[218:219], off
	global_load_dwordx4 v[214:217], v[218:219], off offset:528
	s_nop 0
	global_load_dwordx4 v[218:221], v[218:219], off offset:512
	s_and_b64 vcc, exec, s[0:1]
	s_mov_b32 s44, s41
	s_mov_b32 s43, s42
	s_mov_b64 s[18:19], s[4:5]
	s_mov_b64 s[16:17], s[2:3]
	s_waitcnt vmcnt(0)
	v_pk_add_f32 v[120:121], v[120:121], v[150:151]
	v_lshl_add_u64 v[150:151], s[54:55], 0, v[148:149]
	v_pk_add_f32 v[126:127], v[126:127], v[164:165]
	v_pk_add_f32 v[124:125], v[124:125], v[162:163]
	v_lshl_add_u64 v[150:151], v[150:151], 0, v[144:145]
	v_pk_add_f32 v[110:111], v[110:111], v[172:173]
	v_pk_add_f32 v[108:109], v[108:109], v[170:171]
	v_pk_add_f32 v[122:123], v[122:123], v[152:153]
	global_store_dwordx4 v[150:151], v[124:127], off
	global_store_dwordx4 v[150:151], v[120:123], off offset:16
	v_pk_add_f32 v[102:103], v[102:103], v[168:169]
	v_pk_add_f32 v[100:101], v[100:101], v[166:167]
	global_store_dwordx4 v[150:151], v[108:111], off offset:512
	global_store_dwordx4 v[150:151], v[100:103], off offset:528
	v_pk_add_f32 v[94:95], v[94:95], v[188:189]
	v_pk_add_f32 v[108:109], v[112:113], v[174:175]
	v_lshl_add_u64 v[112:113], s[54:55], 0, v[222:223]
	v_pk_add_f32 v[102:103], v[118:119], v[180:181]
	v_pk_add_f32 v[100:101], v[116:117], v[178:179]
	v_lshl_add_u64 v[112:113], v[112:113], 0, v[144:145]
	v_pk_add_f32 v[92:93], v[92:93], v[186:187]
	v_pk_add_f32 v[110:111], v[114:115], v[176:177]
	global_store_dwordx4 v[112:113], v[100:103], off
	global_store_dwordx4 v[112:113], v[108:111], off offset:16
	v_pk_add_f32 v[86:87], v[86:87], v[184:185]
	v_pk_add_f32 v[84:85], v[84:85], v[182:183]
	global_store_dwordx4 v[112:113], v[92:95], off offset:512
	global_store_dwordx4 v[112:113], v[84:87], off offset:528
	v_pk_add_f32 v[78:79], v[78:79], v[204:205]
	v_pk_add_f32 v[92:93], v[96:97], v[190:191]
	v_lshl_add_u64 v[96:97], s[54:55], 0, v[224:225]
	v_pk_add_f32 v[86:87], v[106:107], v[196:197]
	v_pk_add_f32 v[84:85], v[104:105], v[194:195]
	v_lshl_add_u64 v[96:97], v[96:97], 0, v[144:145]
	v_pk_add_f32 v[76:77], v[76:77], v[202:203]
	v_pk_add_f32 v[94:95], v[98:99], v[192:193]
	global_store_dwordx4 v[96:97], v[84:87], off
	global_store_dwordx4 v[96:97], v[92:95], off offset:16
	v_pk_add_f32 v[74:75], v[74:75], v[200:201]
	v_pk_add_f32 v[72:73], v[72:73], v[198:199]
	global_store_dwordx4 v[96:97], v[76:79], off offset:512
	global_store_dwordx4 v[96:97], v[72:75], off offset:528
	v_pk_add_f32 v[70:71], v[70:71], v[220:221]
	v_pk_add_f32 v[76:77], v[80:81], v[206:207]
	v_lshl_add_u64 v[80:81], s[54:55], 0, v[154:155]
	v_pk_add_f32 v[74:75], v[90:91], v[212:213]
	v_pk_add_f32 v[72:73], v[88:89], v[210:211]
	v_lshl_add_u64 v[80:81], v[80:81], 0, v[144:145]
	v_pk_add_f32 v[68:69], v[68:69], v[218:219]
	v_pk_add_f32 v[64:65], v[64:65], v[214:215]
	v_lshl_add_u64 v[154:155], v[148:149], 0, s[10:11]
	v_pk_add_f32 v[78:79], v[82:83], v[208:209]
	global_store_dwordx4 v[80:81], v[72:75], off
	global_store_dwordx4 v[80:81], v[76:79], off offset:16
	v_pk_add_f32 v[66:67], v[66:67], v[216:217]
	global_store_dwordx4 v[80:81], v[68:71], off offset:512
	global_store_dwordx4 v[80:81], v[64:67], off offset:528
	v_lshl_add_u64 v[152:153], v[148:149], 0, s[12:13]
	v_lshl_add_u64 v[150:151], v[148:149], 0, s[14:15]
	v_lshl_add_u64 v[64:65], v[146:147], 0, v[154:155]
	global_load_dwordx4 v[108:111], v[64:65], off offset:16
	global_load_dwordx4 v[120:123], v[64:65], off
	global_load_dwordx4 v[92:95], v[64:65], off offset:528
	global_load_dwordx4 v[100:103], v[64:65], off offset:512
	v_lshl_add_u64 v[64:65], v[146:147], 0, v[152:153]
	global_load_dwordx4 v[88:91], v[64:65], off offset:16
	global_load_dwordx4 v[96:99], v[64:65], off
	global_load_dwordx4 v[76:79], v[64:65], off offset:528
	global_load_dwordx4 v[84:87], v[64:65], off offset:512
	v_lshl_add_u64 v[68:69], v[146:147], 0, v[150:151]
	global_load_dwordx4 v[72:75], v[68:69], off offset:16
	global_load_dwordx4 v[80:83], v[68:69], off
	global_load_dwordx4 v[64:67], v[68:69], off offset:528
	s_nop 0
	global_load_dwordx4 v[68:71], v[68:69], off offset:512
	v_lshl_add_u64 v[148:149], v[148:149], 0, s[6:7]
	v_lshl_add_u64 v[112:113], v[146:147], 0, v[148:149]
	global_load_dwordx4 v[116:119], v[112:113], off offset:16
	global_load_dwordx4 v[124:127], v[112:113], off
	global_load_dwordx4 v[104:107], v[112:113], off offset:528
	s_nop 0
	global_load_dwordx4 v[112:115], v[112:113], off offset:512
	s_waitcnt vmcnt(0)
; #define PG8_WAIT_V(n) asm volatile("s_waitcnt vmcnt(" #n ")" ::: "memory")
; #define PG8_BAR __builtin_amdgcn_s_barrier()
;   DI void operator()(const f32x4 (&acc)[2][2][4][2], const Unit& u, int wr, int wc, int fr, int fq) const {
;     const int row0 = u.pm * BM + wr * 64 + fr, col0 = u.pn * BM + wc * 32 + 8 * fq;
; #pragma unroll
;     for (int ai = 0; ai < 2; ++ai) {
;       f32x4 bv[4][2][2];
; #pragma unroll
;       for (int m = 0; m < 4; ++m)
; #pragma unroll
;         for (int bj = 0; bj < 2; ++bj) {
;           const float* bp = base + (size_t)(row0 + ai * HALF + m * 16) * 2048 + col0 + bj * HALF;
;           bv[m][bj][0] = *(const f32x4*)bp; bv[m][bj][1] = *(const f32x4*)(bp + 4);
;         }
; #pragma unroll
;       for (int m = 0; m < 4; ++m) {
;         const int row = row0 + ai * HALF + m * 16;
;         const size_t off = (size_t)row * 2048 + col0;
;         float ss = 0.f;
; #pragma unroll
;         for (int bj = 0; bj < 2; ++bj) {
;           const f32x4 v0 = acc[ai][bj][m][0] + bv[m][bj][0], v1 = acc[ai][bj][m][1] + bv[m][bj][1];
;           *(f32x4*)(C + off + bj * HALF) = v0; *(f32x4*)(C + off + bj * HALF + 4) = v1;
; template <class Epi, class Sched = StaticOrder>
; DI void gemm_phase(LAS unsigned char* lds, const Gemm g, const Sched& S, const Epi& E) {
;     ...
;     if (!has_next) break;
; #pragma unroll
;     for (int a = 0; a < 2; ++a)
; #pragma unroll
;       for (int b = 0; b < 2; ++b)
; #pragma unroll
;         for (int m = 0; m < 4; ++m)
; #pragma unroll
;           for (int n = 0; n < 2; ++n) acc[a][b][m][n] = (f32x4){0.f, 0.f, 0.f, 0.f};
;     cur = nxt; cA = nA; cB = nB; ++ui;
;   }
;   PG8_WAIT_V(0);
;   if (wr == 0) PG8_BAR;
;   PG8_BAR;
	v_pk_add_f32 v[56:57], v[56:57], v[108:109]
	v_lshl_add_u64 v[108:109], s[54:55], 0, v[154:155]
	v_pk_add_f32 v[62:63], v[62:63], v[122:123]
	v_pk_add_f32 v[60:61], v[60:61], v[120:121]
	v_lshl_add_u64 v[108:109], v[108:109], 0, v[144:145]
	v_pk_add_f32 v[50:51], v[50:51], v[102:103]
	v_pk_add_f32 v[48:49], v[48:49], v[100:101]
	v_pk_add_f32 v[58:59], v[58:59], v[110:111]
	global_store_dwordx4 v[108:109], v[60:63], off
	global_store_dwordx4 v[108:109], v[56:59], off offset:16
	v_pk_add_f32 v[42:43], v[42:43], v[94:95]
	v_pk_add_f32 v[40:41], v[40:41], v[92:93]
	global_store_dwordx4 v[108:109], v[48:51], off offset:512
	global_store_dwordx4 v[108:109], v[40:43], off offset:528
	v_pk_add_f32 v[34:35], v[34:35], v[86:87]
	v_lshl_add_u64 v[48:49], s[54:55], 0, v[152:153]
	v_pk_add_f32 v[42:43], v[54:55], v[98:99]
	v_pk_add_f32 v[40:41], v[52:53], v[96:97]
	v_lshl_add_u64 v[48:49], v[48:49], 0, v[144:145]
	v_pk_add_f32 v[32:33], v[32:33], v[84:85]
	v_pk_add_f32 v[46:47], v[46:47], v[90:91]
	v_pk_add_f32 v[44:45], v[44:45], v[88:89]
	global_store_dwordx4 v[48:49], v[40:43], off
	global_store_dwordx4 v[48:49], v[44:47], off offset:16
	v_pk_add_f32 v[26:27], v[26:27], v[78:79]
	v_pk_add_f32 v[24:25], v[24:25], v[76:77]
	global_store_dwordx4 v[48:49], v[32:35], off offset:512
	global_store_dwordx4 v[48:49], v[24:27], off offset:528
	v_pk_add_f32 v[18:19], v[18:19], v[70:71]
	v_lshl_add_u64 v[32:33], s[54:55], 0, v[150:151]
	v_pk_add_f32 v[26:27], v[38:39], v[82:83]
	v_pk_add_f32 v[24:25], v[36:37], v[80:81]
	v_lshl_add_u64 v[32:33], v[32:33], 0, v[144:145]
	v_pk_add_f32 v[16:17], v[16:17], v[68:69]
	v_pk_add_f32 v[30:31], v[30:31], v[74:75]
	v_pk_add_f32 v[28:29], v[28:29], v[72:73]
	global_store_dwordx4 v[32:33], v[24:27], off
	global_store_dwordx4 v[32:33], v[28:31], off offset:16
	v_pk_add_f32 v[10:11], v[10:11], v[66:67]
	v_pk_add_f32 v[8:9], v[8:9], v[64:65]
	global_store_dwordx4 v[32:33], v[16:19], off offset:512
	global_store_dwordx4 v[32:33], v[8:11], off offset:528
	v_pk_add_f32 v[6:7], v[6:7], v[114:115]
	v_lshl_add_u64 v[16:17], s[54:55], 0, v[148:149]
	v_pk_add_f32 v[10:11], v[22:23], v[126:127]
	v_pk_add_f32 v[8:9], v[20:21], v[124:125]
	v_lshl_add_u64 v[16:17], v[16:17], 0, v[144:145]
	v_pk_add_f32 v[4:5], v[4:5], v[112:113]
	v_pk_add_f32 v[14:15], v[14:15], v[118:119]
	v_pk_add_f32 v[12:13], v[12:13], v[116:117]
	global_store_dwordx4 v[16:17], v[8:11], off
	global_store_dwordx4 v[16:17], v[12:15], off offset:16
	v_pk_add_f32 v[2:3], v[2:3], v[106:107]
	v_pk_add_f32 v[0:1], v[0:1], v[104:105]
	global_store_dwordx4 v[16:17], v[4:7], off offset:512
	global_store_dwordx4 v[16:17], v[0:3], off offset:528
	s_cbranch_vccz .LBB0_1417
	s_waitcnt vmcnt(0)
	s_cmpk_gt_u32 s23, 0xff
	s_cbranch_scc1 .LBB0_1428
	s_barrier
